# scan waves: operand-load pipeline continuous across chunk barriers, y stored to global by scan waves (loader waves no longer read y back); loader path 2x unrolled without register copies
# speedup vs baseline: 1.0301x; 1.0093x over previous
; __device__ __forceinline__ void phase_scan(const Params& p, LAS unsigned char* lds) {
;     ...
;         const int pw_ = wave & 3, s_sub = lane >> 3, c8 = (lane & 7) * 8, s_l = 8 * pw_ + s_sub;
;         h16x8 mu_r8, mu_k8, mu_v8, mu_w8, mu_a8; f32x2 w0r[4], a0r[4], kkr[4], kar[4], omk[4], rkr[4];
; #pragma unroll
;         for (int e = 0; e < 8; ++e) { mu_r8[e] = (h16)mu[64 * h + c8 + e]; mu_k8[e] = (h16)mu[1024 + 64 * h + c8 + e]; mu_v8[e] = (h16)mu[2048 + 64 * h + c8 + e]; mu_w8[e] = (h16)mu[3072 + c8 + e]; mu_a8[e] = (h16)mu[3136 + c8 + e];
;             w0r[e >> 1][e & 1] = w0[c8 + e]; a0r[e >> 1][e & 1] = a0[c8 + e]; kkr[e >> 1][e & 1] = kkw[c8 + e]; kar[e >> 1][e & 1] = kaw[c8 + e]; omk[e >> 1][e & 1] = 1.f - kaw[c8 + e]; rkr[e >> 1][e & 1] = rkw[c8 + e]; }
;         f32x2 S01 = {0.f, 0.f}, S23 = {0.f, 0.f};
;         const int srow = 4 * (wave & 3) + (lane >> 4), j0 = 4 * (lane & 15);
;         const h16x8 z8 = {0, 0, 0, 0, 0, 0, 0, 0};
;         h16x8 pr, pk, pv, pw, pa, qr_, qk_, qv_, qw_, qa_;
;         const h16 *pcA, *pcB, *ppA, *ppB;
;         { const int t0_ = dir ? (SEQ - 1 - s_l) : s_l; pcA = PC + (size_t)(b * SEQ + t0_) * 3200 + c8 + 64 * h; pcB = pcA + 2048 - 64 * h;
;           const long po_ = (s_l > 0) ? (dir ? 3200 : -3200) : 0; ppA = pcA + po_; ppB = pcB + po_; }
;         const long cstride_ = dir ? -32 * 3200 : 32 * 3200;
;     ...
;         if (wave >= 4) { SCAN_LOAD_RAW(); if (s_l == 0) { qr_ = z8; qk_ = z8; qv_ = z8; qw_ = z8; qa_ = z8; } }
;         __syncthreads();
.LBB0_601:
	s_or_b64 exec, exec, s[10:11]
	s_waitcnt vmcnt(16)
	v_cvt_f16_f32_e32 v64, v64
	s_waitcnt vmcnt(13)
	v_cvt_f16_f32_e32 v68, v94
	v_cvt_f16_f32_e32 v0, v60
	s_waitcnt vmcnt(11)
	v_cvt_f16_f32_e32 v69, v98
	v_cvt_f16_f32_e32 v3, v90
	v_cvt_pk_f16_f32 v65, v65, v66
	v_cvt_pk_f16_f32 v90, v95, v96
	v_cvt_pk_f16_f32 v61, v61, v62
	v_pack_b32_f16 v62, v64, v65
	v_pack_b32_f16 v64, v68, v90
	v_cvt_pk_f16_f32 v68, v99, v100
	s_lshl_b64 s[48:49], s[12:13], 25
	s_lshl_b64 s[10:11], s[12:13], 20
	s_bfe_u32 s15, s78, 0x20003
	v_pack_b32_f16 v2, v0, v61
	v_cvt_pk_f16_f32 v0, v91, v92
	v_pack_b32_f16 v66, v69, v68
	v_cvt_pk_f16_f32 v69, v63, v74
	v_cvt_pk_f16_f32 v74, v93, v82
	s_waitcnt vmcnt(10)
	v_cvt_pk_f16_f32 v78, v101, v78
	v_cvt_pk_f16_f32 v75, v75, v76
	v_pack_b32_f16 v60, v3, v0
	v_alignbit_b32 v3, v69, v61, 16
	v_alignbit_b32 v61, v74, v0, 16
	v_cvt_pk_f16_f32 v0, v67, v70
	v_alignbit_b32 v67, v78, v68, 16
	v_alignbit_b32 v68, v75, v69, 16
	v_cvt_f16_f32_e32 v69, v77
	s_add_u32 s48, s68, s48
	s_addc_u32 s49, s69, s49
	s_add_u32 s34, s31, s10
	s_addc_u32 s35, s33, s11
	v_alignbit_b32 v69, v69, v75, 16
	v_cvt_f16_f32_e32 v75, v89
	s_add_u32 s54, s48, s20
	v_cvt_pk_f16_f32 v77, v79, v80
	s_addc_u32 s55, s49, 0
	s_lshl_b32 s14, s14, 2
	v_cvt_pk_f16_f32 v83, v83, v84
	v_cvt_pk_f16_f32 v84, v71, v72
	v_alignbit_b32 v76, v77, v78, 16
	v_cvt_f16_f32_e32 v71, v85
	v_cvt_f16_f32_e32 v73, v73
	v_cvt_f16_f32_e32 v78, v81
	s_add_u32 s52, s34, s14
	v_alignbit_b32 v63, v0, v65, 16
	v_cvt_pk_f16_f32 v82, v97, v86
	v_alignbit_b32 v72, v84, v0, 16
	v_cvt_pk_f16_f32 v0, v87, v88
	s_addc_u32 s53, s35, 0
	s_lshl_b32 s80, s15, 4
	s_lshl_b32 s14, s15, 5
	v_alignbit_b32 v70, v83, v74, 16
	v_alignbit_b32 v74, v0, v82, 16
	v_alignbit_b32 v75, v75, v0, 16
	v_or_b32_e32 v0, s15, v133
	s_add_u32 s14, s54, s14
	v_cmp_eq_u32_e64 s[10:11], s15, v176
	v_cmp_eq_u32_e64 s[12:13], 0, v0
	s_addc_u32 s15, s55, 0
	v_mov_b32_e32 v143, v1
	v_mov_b32_e32 v0, v1
	s_waitcnt vmcnt(2)
	v_pk_add_f32 v[154:155], v[48:49], 1.0 op_sel_hi:[1,0] neg_lo:[1,0] neg_hi:[1,0]
	v_pk_add_f32 v[156:157], v[50:51], 1.0 op_sel_hi:[1,0] neg_lo:[1,0] neg_hi:[1,0]
	v_alignbit_b32 v65, v82, v90, 16
	v_pk_add_f32 v[158:159], v[44:45], 1.0 op_sel_hi:[1,0] neg_lo:[1,0] neg_hi:[1,0]
	v_alignbit_b32 v71, v71, v83, 16
	v_alignbit_b32 v73, v73, v84, 16
	v_alignbit_b32 v77, v78, v77, 16
	v_pk_add_f32 v[160:161], v[46:47], 1.0 op_sel_hi:[1,0] neg_lo:[1,0] neg_hi:[1,0]
	s_waitcnt lgkmcnt(0)
	s_barrier
	v_lshl_add_u64 v[162:163], s[14:15], 0, v[142:143]
	s_mov_b32 s81, -1
	s_movk_i32 s82, 0xfc00
	v_mov_b32_e32 v143, v191
	v_mov_b32_e32 v145, v169
	v_mov_b64_e32 v[166:167], v[0:1]
	v_mov_b64_e32 v[164:165], v[0:1]
	s_cmp_eq_u64 s[0:1], 0
	s_cbranch_scc1 .Lscan_init
	ds_read_b128 v[132:135], v183 offset:64
	ds_read_b128 v[136:139], v183 offset:9280
	ds_read_b128 v[164:167], v183 offset:2368
	ds_read_b128 v[184:187], v183 offset:11584
	ds_read_b128 v[188:191], v183 offset:4672
	ds_read_b128 v[192:195], v183 offset:6976
	ds_read_b128 v[196:199], v183 offset:13888
	ds_read_b128 v[246:249], v183 offset:16192
	ds_read_b128 v[250:253], v183 offset:6912
	s_waitcnt lgkmcnt(0)
	s_branch .LBB0_604
.Lscan_init:
	v_mov_b64_e32 v[2:3], 0
	v_mov_b64_e32 v[4:5], 0
	v_mov_b64_e32 v[6:7], 0
	v_mov_b64_e32 v[8:9], 0
	v_mov_b64_e32 v[10:11], 0
	v_mov_b64_e32 v[12:13], 0
	v_mov_b64_e32 v[14:15], 0
	v_mov_b64_e32 v[16:17], 0
	v_mov_b64_e32 v[18:19], 0
	v_mov_b64_e32 v[20:21], 0
	v_mov_b64_e32 v[22:23], 0
	v_mov_b64_e32 v[24:25], 0
	v_mov_b64_e32 v[26:27], 0
	v_mov_b64_e32 v[28:29], 0
	v_mov_b64_e32 v[30:31], 0
	v_mov_b64_e32 v[32:33], 0
	v_mov_b64_e32 v[34:35], 0
	v_mov_b64_e32 v[36:37], 0
	v_mov_b64_e32 v[38:39], 0
	v_mov_b64_e32 v[40:41], 0
	v_mov_b64_e32 v[42:43], 0
	v_mov_b64_e32 v[44:45], 0
	v_mov_b64_e32 v[46:47], 0
	v_mov_b64_e32 v[48:49], 0
	v_mov_b64_e32 v[50:51], 0
	v_mov_b64_e32 v[52:53], 0
	v_mov_b64_e32 v[54:55], 0
	v_mov_b64_e32 v[56:57], 0
	v_mov_b64_e32 v[58:59], 0
	v_mov_b64_e32 v[60:61], 0
	v_mov_b64_e32 v[62:63], 0
	v_mov_b64_e32 v[64:65], 0
	v_mov_b64_e32 v[66:67], 0
	v_mov_b64_e32 v[68:69], 0
	v_mov_b64_e32 v[70:71], 0
	v_mov_b64_e32 v[72:73], 0
	v_mov_b64_e32 v[74:75], 0
	v_mov_b64_e32 v[76:77], 0
	v_mov_b64_e32 v[78:79], 0
	v_mov_b64_e32 v[80:81], 0
	v_mov_b64_e32 v[110:111], 0
	v_mov_b64_e32 v[112:113], 0
	v_mov_b64_e32 v[204:205], 0
	v_mov_b64_e32 v[206:207], 0
	v_mov_b64_e32 v[208:209], 0
	v_mov_b64_e32 v[210:211], 0
	s_mov_b32 s34, 0x22222222
	s_mov_b32 s35, 0x22222222
	s_mov_b32 s56, 0x44444444
	s_mov_b32 s57, 0x44444444
	s_mov_b32 s98, 0x88888888
	s_mov_b32 s99, 0x88888888
	s_cmp_lg_u64 s[8:9], 0
	s_mov_b32 s100, 0xffff0000
	s_cselect_b32 s100, 0x10000, s100
	s_cselect_b32 s101, 0, -1
	v_and_b32_e32 v202, 15, v130
	v_add_u32_e32 v202, 4, v202
	v_sub_u32_e32 v203, 0x1fff, v202
	v_cndmask_b32_e64 v202, v203, v202, s[8:9]
	v_add_u32_e32 v202, s79, v202
	v_mov_b32_e32 v203, 0
	v_lshlrev_b64 v[126:127], 11, v[202:203]
	v_lshl_add_u64 v[126:127], s[48:49], 0, v[126:127]
	s_lshl_b32 s14, s80, 1
	s_add_u32 s14, s14, s20
	s_mov_b32 s15, 0
	v_lshl_add_u64 v[126:127], v[126:127], 0, s[14:15]
	v_lshrrev_b32_e32 v202, 6, v179
	v_lshl_add_u64 v[126:127], v[126:127], 0, v[202:203]
	s_ashr_i64 s[14:15], s[100:101], 1
	s_sub_u32 s14, 0, s14
	s_subb_u32 s15, 0, s15
	v_lshl_add_u64 v[128:129], v[126:127], 0, s[14:15]
	s_branch .LBB0_604

; #define LAS __attribute__((address_space(3)))
; #define SCAN_LOAD(chn) SCAN_LOAD_RAW()
; __device__ __forceinline__ void phase_scan(const Params& p, LAS unsigned char* lds) {
;     ...
;                 if (n + 1 < SEQ / 32) {
;                     const int cn = n + 1;
;                     const int sg = cn * 32 + s_l; const int t = dir ? (SEQ - 1 - sg) : sg;
;                     f32x2 qr[4], qk[4]; float qv[8];
;                     LAS h16* TWp = (LAS h16*)priv; LAS h16* QAp = TWp + 8 * 72;
;                     { unsigned m1u_ = 0xBC00BC00u; asm volatile("" : "+s"(m1u_));
;                       typedef unsigned u32x4_ __attribute__((ext_vector_type(4))); const u32x4_ m1v_ = {m1u_, m1u_, m1u_, m1u_}; const h16x8 m1_ = __builtin_bit_cast(h16x8, m1v_);
;                       const h16x8 r8 = pr + mu_r8 * (pr * m1_ + qr_), k8 = pk + mu_k8 * (pk * m1_ + qk_), v8 = pv + mu_v8 * (pv * m1_ + qv_);
;                       const h16x8 w8 = pw + mu_w8 * (pw * m1_ + qw_), a8 = pa + mu_a8 * (pa * m1_ + qa_);
;                       h16x8 tw8;
; #pragma unroll
;                       for (int pi = 0; pi < 4; ++pi) { qr[pi] = (f32x2){(float)r8[2 * pi], (float)r8[2 * pi + 1]}; qk[pi] = (f32x2){(float)k8[2 * pi], (float)k8[2 * pi + 1]};
;                           qv[2 * pi] = (float)v8[2 * pi]; qv[2 * pi + 1] = (float)v8[2 * pi + 1];
;                           const f32x2 tx = (f32x2){(float)w8[2 * pi], (float)w8[2 * pi + 1]} * 2.8853900817779268f;
;                           const f32x2 dn = (f32x2){__builtin_amdgcn_exp2f(tx[0]), __builtin_amdgcn_exp2f(tx[1])} + 1.f;
;                           const f32x2 th = (f32x2){__builtin_amdgcn_rcpf(dn[0]), __builtin_amdgcn_rcpf(dn[1])} * -2.f + 1.f;
;                           tw8[2 * pi] = (h16)th[0]; tw8[2 * pi + 1] = (h16)th[1]; }
;                       *(LAS h16x8*)(TWp + s_sub * 72 + c8) = tw8; *(LAS h16x8*)(QAp + s_sub * 72 + c8) = a8; }
;                     if (cn + 1 < SEQ / 32) SCAN_LOAD(cn + 1);
.LBB0_604:
	s_cmp_eq_u64 s[0:1], 0
	s_cbranch_scc1 .Lscan_wave_top
	s_bitcmp1_b32 s81, 0
	s_cbranch_scc0 .Lpb_top
	s_cmp_eq_u32 s81, -1
	s_cbranch_scc0 .Lpa_body
	s_waitcnt vmcnt(9)
	v_mov_b64_e32 v[94:95], v[102:103]
	s_waitcnt vmcnt(8)
	v_mov_b64_e32 v[86:87], v[106:107]
	s_waitcnt vmcnt(7)
	v_mov_b64_e32 v[78:79], v[110:111]
	s_waitcnt vmcnt(4)
	v_mov_b64_e32 v[98:99], v[114:115]
	s_waitcnt vmcnt(3)
	v_mov_b64_e32 v[90:91], v[118:119]
	s_waitcnt vmcnt(2)
	v_mov_b64_e32 v[82:83], v[122:123]
	v_mov_b64_e32 v[96:97], v[104:105]
	v_mov_b64_e32 v[88:89], v[108:109]
	v_mov_b64_e32 v[80:81], v[112:113]
	v_mov_b64_e32 v[100:101], v[116:117]
	v_mov_b64_e32 v[92:93], v[120:121]
	v_mov_b64_e32 v[84:85], v[124:125]
.Lpa_body:
	s_waitcnt vmcnt(2)
	s_and_saveexec_b64 s[14:15], s[0:1]
	s_xor_b64 s[54:55], exec, s[14:15]
	s_cbranch_execz .LBB0_617
	s_cmpk_eq_i32 s81, 0xff
	s_cbranch_scc1 .LBB0_608
	s_mov_b32 s14, 0xbc00bc00
	s_cmpk_eq_i32 s81, 0xfe
	s_waitcnt vmcnt(1)
	v_pk_fma_f16 v0, v4, s14, v12
	v_pk_fma_f16 v102, v5, s14, v13
	v_pk_fma_f16 v103, v6, s14, v14
	v_pk_fma_f16 v104, v7, s14, v15
	v_pk_fma_f16 v107, v74, v103, v6
	v_pk_fma_f16 v109, v75, v104, v7
	v_pk_fma_f16 v105, v65, v102, v5
	v_pk_fma_f16 v0, v64, v0, v4
	v_cvt_f32_f16_e32 v104, v105
	v_cvt_f32_f16_e32 v102, v0
	v_cvt_f32_f16_sdwa v103, v0 dst_sel:DWORD dst_unused:UNUSED_PAD src0_sel:WORD_1
	v_cvt_f32_f16_sdwa v105, v105 dst_sel:DWORD dst_unused:UNUSED_PAD src0_sel:WORD_1
	v_cvt_f32_f16_e32 v106, v107
	v_cvt_f32_f16_sdwa v107, v107 dst_sel:DWORD dst_unused:UNUSED_PAD src0_sel:WORD_1
	v_cvt_f32_f16_e32 v108, v109
	v_cvt_f32_f16_sdwa v109, v109 dst_sel:DWORD dst_unused:UNUSED_PAD src0_sel:WORD_1
	v_pk_mul_f32 v[102:103], v[102:103], s[30:31] op_sel_hi:[1,0]
	v_pk_mul_f32 v[104:105], v[104:105], s[30:31] op_sel_hi:[1,0]
	v_pk_mul_f32 v[106:107], v[106:107], s[30:31] op_sel_hi:[1,0]
	v_pk_mul_f32 v[108:109], v[108:109], s[30:31] op_sel_hi:[1,0]
	v_exp_f32_e32 v102, v102
	v_exp_f32_e32 v103, v103
	v_exp_f32_e32 v104, v104
	v_exp_f32_e32 v105, v105
	v_exp_f32_e32 v106, v106
	v_exp_f32_e32 v107, v107
	v_exp_f32_e32 v108, v108
	v_exp_f32_e32 v109, v109
	v_pk_add_f32 v[102:103], v[102:103], 1.0 op_sel_hi:[1,0]
	v_pk_add_f32 v[104:105], v[104:105], 1.0 op_sel_hi:[1,0]
	v_pk_add_f32 v[106:107], v[106:107], 1.0 op_sel_hi:[1,0]
	v_pk_add_f32 v[108:109], v[108:109], 1.0 op_sel_hi:[1,0]
	v_rcp_f32_e32 v102, v102
	v_rcp_f32_e32 v103, v103
	v_rcp_f32_e32 v104, v104
	v_rcp_f32_e32 v105, v105
	v_rcp_f32_e32 v106, v106
	v_rcp_f32_e32 v107, v107
	v_rcp_f32_e32 v108, v108
	v_rcp_f32_e32 v109, v109
	s_waitcnt vmcnt(0)
	v_pk_fma_f16 v112, v8, s14, v16
	v_pk_fma_f16 v113, v9, s14, v17
	v_pk_fma_f16 v114, v10, s14, v18
	v_pk_fma_f16 v0, v11, s14, v19
	v_pk_fma_f32 v[110:111], v[102:103], 2.0, 1.0 op_sel_hi:[1,0,0] neg_lo:[1,0,0] neg_hi:[1,0,0]
	v_pk_fma_f32 v[102:103], v[104:105], 2.0, 1.0 op_sel_hi:[1,0,0] neg_lo:[1,0,0] neg_hi:[1,0,0]
	v_pk_fma_f32 v[106:107], v[106:107], 2.0, 1.0 op_sel_hi:[1,0,0] neg_lo:[1,0,0] neg_hi:[1,0,0]
	v_pk_fma_f32 v[104:105], v[108:109], 2.0, 1.0 op_sel_hi:[1,0,0] neg_lo:[1,0,0] neg_hi:[1,0,0]
	v_cvt_pk_f16_f32 v103, v102, v103
	v_cvt_pk_f16_f32 v105, v104, v105
	v_cvt_pk_f16_f32 v104, v106, v107
	v_cvt_pk_f16_f32 v102, v110, v111
	v_pk_fma_f16 v109, v77, v0, v11
	v_pk_fma_f16 v108, v76, v114, v10
	v_pk_fma_f16 v107, v67, v113, v9
	v_pk_fma_f16 v106, v66, v112, v8
	ds_write_b128 v171, v[102:105] offset:18432
	ds_write_b128 v172, v[106:109] offset:19584
	s_cbranch_scc1 .LBB0_609
	v_lshl_add_u64 v[4:5], v[148:149], 0, s[20:21]
	global_load_dwordx4 v[118:121], v[146:147], off
	global_load_dwordx4 v[110:113], v[146:147], off offset:2048
	global_load_dwordx4 v[102:105], v[4:5], off
	s_nop 0
	global_load_dwordx4 v[4:7], v[148:149], off offset:2048
	global_load_dwordx4 v[8:11], v[148:149], off offset:2176
	global_load_dwordx4 v[122:125], v[152:153], off
	global_load_dwordx4 v[114:117], v[152:153], off offset:2048
	v_lshl_add_u64 v[12:13], v[150:151], 0, s[20:21]
	global_load_dwordx4 v[106:109], v[12:13], off
	s_nop 0
	global_load_dwordx4 v[12:15], v[150:151], off offset:2048
	global_load_dwordx4 v[16:19], v[150:151], off offset:2176
	s_lshl_b64 s[34:35], s[46:47], 1
	v_lshl_add_u64 v[146:147], v[146:147], 0, s[34:35]
	v_lshl_add_u64 v[148:149], v[148:149], 0, s[34:35]
	s_lshl_b64 s[34:35], s[40:41], 1
	v_lshl_add_u64 v[152:153], v[146:147], 0, s[34:35]
	v_lshl_add_u64 v[150:151], v[148:149], 0, s[34:35]
	s_branch .LBB0_610
.LBB0_608:
	s_cmp_lt_i32 s81, 1
	s_branch .LBB0_616
; #define LAS __attribute__((address_space(3)))
; #define LDS_WAIT() asm volatile("s_waitcnt lgkmcnt(0)" ::: "memory")
; __device__ __forceinline__ void phase_scan(const Params& p, LAS unsigned char* lds) {
;     ...
;                     LDS_WAIT();
;                     f32x4 accw[4], acca[4];
; #pragma unroll
;                     for (int ct = 0; ct < 4; ++ct) { accw[ct] = (f32x4){0.f, 0.f, 0.f, 0.f}; acca[ct] = (f32x4){0.f, 0.f, 0.f, 0.f}; }
; #pragma unroll
;                     for (int ks = 0; ks < 2; ++ks) {
;                         const h16x8 atw = *(const LAS h16x8*)(TWp + (lane & 7) * 72 + 32 * ks + 8 * (lane >> 4));
;                         const h16x8 aqa = *(const LAS h16x8*)(QAp + (lane & 7) * 72 + 32 * ks + 8 * (lane >> 4));
; #pragma unroll
;                         for (int ct = 0; ct < 4; ++ct) {
;                             const h16x8 bw = *(const LAS h16x8*)(w2T + (16 * ct + (lane & 15)) * 72 + 32 * ks + 8 * (lane >> 4));
;                             const h16x8 ba = *(const LAS h16x8*)(a2T + (16 * ct + (lane & 15)) * 72 + 32 * ks + 8 * (lane >> 4));
;                             accw[ct] = __builtin_amdgcn_mfma_f32_16x16x32_f16(atw, bw, accw[ct], 0, 0, 0);
;                             acca[ct] = __builtin_amdgcn_mfma_f32_16x16x32_f16(aqa, ba, acca[ct], 0, 0, 0);
;                         }
;                     }
;                     LDS_WAIT();
;                     { LAS float* Zd = (LAS float*)priv + (lane >> 5) * 512 + (4 * ((lane >> 4) & 1)) * 64 + (lane & 15);
; #pragma unroll
;                       for (int ct = 0; ct < 4; ++ct)
; #pragma unroll
;                           for (int r = 0; r < 4; ++r) Zd[r * 64 + 16 * ct] = (lane < 32) ? accw[ct][r] : acca[ct][r]; }
;                     LDS_WAIT();
;                     const LAS float* Zw = (const LAS float*)priv + s_sub * 64 + c8; const LAS float* Za = Zw + 512;
;                     const f32x4 zw0 = *(const LAS f32x4*)Zw, zw1 = *(const LAS f32x4*)(Zw + 4), za0 = *(const LAS f32x4*)Za, za1 = *(const LAS f32x4*)(Za + 4);
;                     LDS_WAIT();
;                     f32x2 kk[4], av_[4], kp[4], dec[4], kn2 = {0.f, 0.f}, sb2 = {0.f, 0.f};
; #pragma unroll
;                     for (int pi = 0; pi < 4; ++pi) {
;                         const f32x2 zw = (pi < 2 ? (f32x2){zw0[2 * pi], zw0[2 * pi + 1]} : (f32x2){zw1[2 * pi - 4], zw1[2 * pi - 3]}) + w0r[pi];
.LBB0_609:
.LBB0_610:
	s_waitcnt lgkmcnt(0)
	v_pk_fma_f16 v222, v95, s14, v99
	v_pk_fma_f16 v218, v96, s14, v100
	v_pk_fma_f16 v219, v97, s14, v101
	ds_read_b128 v[126:129], v173 offset:18432
	ds_read_b128 v[202:205], v173 offset:19584
	ds_read_b128 v[206:209], v183
	ds_read_b128 v[210:213], v183 offset:9216
	v_pk_fma_f16 v0, v94, s14, v98
	ds_read_b128 v[214:217], v183 offset:2304
	ds_read_b128 v[98:101], v183 offset:11520
	v_pk_fma_f16 v242, v69, v219, v97
	v_pk_fma_f16 v238, v68, v218, v96
	ds_read_b128 v[218:221], v183 offset:4608
	v_pk_fma_f16 v239, v3, v222, v95
	ds_read_b128 v[222:225], v183 offset:13824
	ds_read_b128 v[230:233], v183 offset:16128
	ds_read_b128 v[234:237], v173 offset:18496
	ds_read_b128 v[226:229], v173 offset:19648
	s_waitcnt lgkmcnt(8)
	v_mfma_f32_16x16x32_f16 v[206:209], v[126:129], v[206:209], 0
	v_pk_fma_f16 v0, v2, v0, v94
	v_pk_fma_f16 v94, v86, s14, v90
	v_pk_fma_f16 v95, v87, s14, v91
	s_waitcnt lgkmcnt(7)
	v_mfma_f32_16x16x32_f16 v[210:213], v[202:205], v[210:213], 0
	v_pk_fma_f16 v240, v61, v95, v87
	v_cvt_f32_f16_sdwa v87, v0 dst_sel:DWORD dst_unused:UNUSED_PAD src0_sel:WORD_1
	s_bitcmp1_b32 s81, 0
	s_waitcnt lgkmcnt(6)
	v_mfma_f32_16x16x32_f16 v[214:217], v[126:129], v[214:217], 0
	s_cselect_b32 s15, 0, 0xa800
	s_add_i32 s15, s15, 0
	s_waitcnt lgkmcnt(5)
	v_mfma_f32_16x16x32_f16 v[96:99], v[202:205], v[98:101], 0
	v_pk_fma_f16 v100, v88, s14, v92
	v_pk_fma_f16 v101, v89, s14, v93
	v_pk_fma_f16 v244, v70, v100, v88
	s_waitcnt lgkmcnt(4)
	v_mfma_f32_16x16x32_f16 v[218:221], v[126:129], v[218:221], 0
	v_pk_fma_f16 v243, v71, v101, v89
	v_pk_fma_f16 v101, v60, v94, v86
	v_cvt_f32_f16_e32 v86, v0
	s_waitcnt lgkmcnt(3)
	v_mfma_f32_16x16x32_f16 v[222:225], v[202:205], v[222:225], 0
	v_cvt_f32_f16_e32 v100, v101
	v_cvt_f32_f16_sdwa v101, v101 dst_sel:DWORD dst_unused:UNUSED_PAD src0_sel:WORD_1
	v_mfma_f32_16x16x32_f16 v[126:129], v[126:129], v[250:253], 0
	s_waitcnt lgkmcnt(2)
	v_mfma_f32_16x16x32_f16 v[202:205], v[202:205], v[230:233], 0
	s_waitcnt lgkmcnt(1)
	v_mfma_f32_16x16x32_f16 v[206:209], v[234:237], v[132:135], v[206:209]
	s_waitcnt lgkmcnt(0)
	v_mfma_f32_16x16x32_f16 v[210:213], v[226:229], v[136:139], v[210:213]
	v_mfma_f32_16x16x32_f16 v[214:217], v[234:237], v[164:167], v[214:217]
	v_cvt_f32_f16_e32 v88, v239
	v_cvt_f32_f16_sdwa v89, v239 dst_sel:DWORD dst_unused:UNUSED_PAD src0_sel:WORD_1
	s_nop 2
	s_nop 1
	v_cndmask_b32_e64 v0, v210, v206, s[4:5]
	s_waitcnt lgkmcnt(0)
	v_mfma_f32_16x16x32_f16 v[218:221], v[234:237], v[188:191], v[218:221]
	v_cndmask_b32_e64 v206, v212, v208, s[4:5]
	v_add_u32_e32 v208, 0x4800, v174
	v_mfma_f32_16x16x32_f16 v[96:99], v[226:229], v[184:187], v[96:99]
	v_cvt_f32_f16_e32 v94, v240
	v_cvt_f32_f16_sdwa v95, v240 dst_sel:DWORD dst_unused:UNUSED_PAD src0_sel:WORD_1
	s_waitcnt lgkmcnt(0)
	v_mfma_f32_16x16x32_f16 v[222:225], v[226:229], v[196:199], v[222:225]
	v_cvt_f32_f16_e32 v90, v238
	v_cvt_f32_f16_sdwa v91, v238 dst_sel:DWORD dst_unused:UNUSED_PAD src0_sel:WORD_1
	v_mfma_f32_16x16x32_f16 v[126:129], v[234:237], v[192:195], v[126:129]
	s_nop 0
	v_cndmask_b32_e64 v96, v96, v214, s[4:5]
	s_waitcnt lgkmcnt(0)
	v_cndmask_b32_e64 v93, v211, v207, s[4:5]
	s_waitcnt lgkmcnt(0)
	v_mfma_f32_16x16x32_f16 v[202:205], v[226:229], v[246:249], v[202:205]
	ds_write2_b32 v208, v0, v96 offset1:16
	v_cndmask_b32_e64 v0, v97, v215, s[4:5]
	ds_write2_b32 v208, v93, v0 offset0:64 offset1:80
	v_cndmask_b32_e64 v0, v98, v216, s[4:5]
	v_cndmask_b32_e64 v207, v213, v209, s[4:5]
	ds_write2_b32 v208, v206, v0 offset0:128 offset1:144
	v_cndmask_b32_e64 v0, v99, v217, s[4:5]
	ds_write2_b32 v208, v207, v0 offset0:192 offset1:208
	v_cndmask_b32_e64 v0, v222, v218, s[4:5]
	v_cndmask_b32_e64 v98, v202, v126, s[4:5]
	v_cndmask_b32_e64 v93, v223, v219, s[4:5]
	ds_write2_b32 v208, v0, v98 offset0:32 offset1:48
	v_cndmask_b32_e64 v0, v203, v127, s[4:5]
	v_cndmask_b32_e64 v96, v224, v220, s[4:5]
	ds_write2_b32 v208, v93, v0 offset0:96 offset1:112
	v_cndmask_b32_e64 v0, v204, v128, s[4:5]
	v_cndmask_b32_e64 v97, v225, v221, s[4:5]
	ds_write2_b32 v208, v96, v0 offset0:160 offset1:176
	v_cndmask_b32_e64 v0, v205, v129, s[4:5]
	ds_write2_b32 v208, v97, v0 offset0:224 offset1:240
	s_waitcnt lgkmcnt(0)
	ds_read_b128 v[126:129], v200 offset:20480
	ds_read_b128 v[206:209], v200 offset:20496
	v_pk_mul_f32 v[212:213], v[40:41], v[100:101]
	v_pk_mul_f32 v[218:219], v[42:43], v[94:95]
	ds_read_b128 v[96:99], v200 offset:18432
	ds_read_b128 v[202:205], v200 offset:18448
	s_waitcnt lgkmcnt(3)
	v_pk_add_f32 v[126:127], v[32:33], v[126:127]
	s_waitcnt lgkmcnt(2)
	v_pk_add_f32 v[208:209], v[30:31], v[208:209]
	v_pk_mul_f32 v[126:127], v[126:127], s[36:37] op_sel_hi:[1,0]
	v_cvt_f32_f16_e32 v230, v244
	v_exp_f32_e32 v126, v126
	v_exp_f32_e32 v127, v127
	v_cvt_f32_f16_sdwa v231, v244 dst_sel:DWORD dst_unused:UNUSED_PAD src0_sel:WORD_1
	v_pk_mul_f32 v[208:209], v[208:209], s[36:37] op_sel_hi:[1,0]
	v_cvt_f32_f16_e32 v210, v243
	v_pk_add_f32 v[126:127], v[126:127], 1.0 op_sel_hi:[1,0]
	v_exp_f32_e32 v208, v208
	v_rcp_f32_e32 v214, v126
	v_rcp_f32_e32 v215, v127
	v_exp_f32_e32 v209, v209
	v_cvt_f32_f16_sdwa v211, v243 dst_sel:DWORD dst_unused:UNUSED_PAD src0_sel:WORD_1
	s_waitcnt lgkmcnt(1)
; #define LAS __attribute__((address_space(3)))
; __device__ __forceinline__ void phase_scan(const Params& p, LAS unsigned char* lds) {
;     ...
;                     f32x2 kk[4], av_[4], kp[4], dec[4], kn2 = {0.f, 0.f}, sb2 = {0.f, 0.f};
; #pragma unroll
;                     for (int pi = 0; pi < 4; ++pi) {
;                         const f32x2 zw = (pi < 2 ? (f32x2){zw0[2 * pi], zw0[2 * pi + 1]} : (f32x2){zw1[2 * pi - 4], zw1[2 * pi - 3]}) + w0r[pi];
;                         const f32x2 za = (pi < 2 ? (f32x2){za0[2 * pi], za0[2 * pi + 1]} : (f32x2){za1[2 * pi - 4], za1[2 * pi - 3]}) + a0r[pi];
;                         const f32x2 tw_ = zw * -1.4426950408889634f, ta_ = za * -1.4426950408889634f;
;                         const f32x2 dw = (f32x2){__builtin_amdgcn_exp2f(tw_[0]), __builtin_amdgcn_exp2f(tw_[1])} + 1.f, da = (f32x2){__builtin_amdgcn_exp2f(ta_[0]), __builtin_amdgcn_exp2f(ta_[1])} + 1.f;
;                         const f32x2 sw = (f32x2){__builtin_amdgcn_rcpf(dw[0]), __builtin_amdgcn_rcpf(dw[1])} * -0.8750387749225136f;
;                         dec[pi] = (f32x2){__builtin_amdgcn_exp2f(sw[0]), __builtin_amdgcn_exp2f(sw[1])};
;                         av_[pi] = (f32x2){__builtin_amdgcn_rcpf(da[0]), __builtin_amdgcn_rcpf(da[1])};
;                         kk[pi] = qk[pi] * kkr[pi]; kn2 = kk[pi] * kk[pi] + kn2;
;                         kp[pi] = qk[pi] * (av_[pi] * kar[pi] + omk[pi]);
;                         sb2 = (qr[pi] * kp[pi]) * rkr[pi] + sb2; }
;                     const float kn = red8(kn2[0] + kn2[1]), sbn = red8(sb2[0] + sb2[1]);
;                     const float ninv = -rsqrtf(fmaxf(kn, 1e-12f));
;                     LAS float* dR = OPS + (cn & 1) * SET_F + s_l * 64 + c8;
; #pragma unroll
;                     for (int hf = 0; hf < 2; ++hf) {
;                         const f32x2 na0 = kk[2 * hf] * ninv, na1 = kk[2 * hf + 1] * ninv;
;                         const f32x2 nb0 = na0 * av_[2 * hf], nb1 = na1 * av_[2 * hf + 1];
;                         *(LAS f32x4*)(dR + 4 * hf) = (f32x4){qr[2 * hf][0], qr[2 * hf][1], qr[2 * hf + 1][0], qr[2 * hf + 1][1]};
;                         *(LAS f32x4*)(dR + 2048 + 4 * hf) = (f32x4){dec[2 * hf][0], dec[2 * hf][1], dec[2 * hf + 1][0], dec[2 * hf + 1][1]};
;                         *(LAS f32x4*)(dR + 4096 + 4 * hf) = (f32x4){kp[2 * hf][0], kp[2 * hf][1], kp[2 * hf + 1][0], kp[2 * hf + 1][1]};
	v_pk_add_f32 v[96:97], v[24:25], v[96:97]
	v_pk_fma_f32 v[126:127], v[48:49], v[214:215], v[154:155]
	v_pk_add_f32 v[98:99], v[26:27], v[98:99]
	v_pk_mul_f32 v[126:127], v[126:127], v[100:101]
	v_pk_add_f32 v[100:101], v[34:35], v[128:129]
	v_pk_mul_f32 v[128:129], v[126:127], v[86:87]
	v_pk_mul_f32 v[100:101], v[100:101], s[36:37] op_sel_hi:[1,0]
	v_pk_fma_f32 v[216:217], v[56:57], v[128:129], 0 op_sel_hi:[1,1,0]
	v_exp_f32_e32 v100, v100
	v_exp_f32_e32 v101, v101
	v_pk_mul_f32 v[128:129], v[218:219], v[218:219]
	v_pk_mul_f32 v[224:225], v[36:37], v[230:231]
	v_pk_fma_f32 v[220:221], v[212:213], v[212:213], v[128:129]
	v_pk_add_f32 v[100:101], v[100:101], 1.0 op_sel_hi:[1,0]
	v_pk_mul_f32 v[96:97], v[96:97], s[36:37] op_sel_hi:[1,0]
	v_rcp_f32_e32 v100, v100
	v_rcp_f32_e32 v101, v101
	v_pk_mul_f32 v[98:99], v[98:99], s[36:37] op_sel_hi:[1,0]
	v_pk_add_f32 v[208:209], v[208:209], 1.0 op_sel_hi:[1,0]
	v_exp_f32_e32 v96, v96
	v_pk_fma_f32 v[128:129], v[50:51], v[100:101], v[156:157]
	v_exp_f32_e32 v97, v97
	v_pk_mul_f32 v[128:129], v[128:129], v[94:95]
	v_pk_add_f32 v[94:95], v[28:29], v[206:207]
	v_pk_mul_f32 v[206:207], v[128:129], v[88:89]
	v_pk_mul_f32 v[94:95], v[94:95], s[36:37] op_sel_hi:[1,0]
	v_pk_fma_f32 v[216:217], v[58:59], v[206:207], v[216:217]
	v_exp_f32_e32 v94, v94
	v_exp_f32_e32 v95, v95
	v_exp_f32_e32 v98, v98
	v_exp_f32_e32 v99, v99
	v_pk_mul_f32 v[226:227], v[38:39], v[210:211]
	v_pk_add_f32 v[94:95], v[94:95], 1.0 op_sel_hi:[1,0]
	s_waitcnt lgkmcnt(0)
	v_pk_add_f32 v[202:203], v[20:21], v[202:203]
	v_rcp_f32_e32 v222, v94
	v_rcp_f32_e32 v223, v95
	v_pk_fma_f32 v[94:95], v[224:225], v[224:225], v[220:221]
	v_pk_add_f32 v[204:205], v[22:23], v[204:205]
	v_pk_fma_f32 v[94:95], v[226:227], v[226:227], v[94:95]
	v_pk_fma_f32 v[206:207], v[44:45], v[222:223], v[158:159]
	v_cvt_f32_f16_e32 v92, v242
	v_pk_mul_f32 v[206:207], v[206:207], v[230:231]
	v_cvt_f32_f16_sdwa v93, v242 dst_sel:DWORD dst_unused:UNUSED_PAD src0_sel:WORD_1
	v_pk_mul_f32 v[220:221], v[206:207], v[90:91]
	v_pk_mul_f32 v[202:203], v[202:203], s[36:37] op_sel_hi:[1,0]
	v_pk_fma_f32 v[216:217], v[52:53], v[220:221], v[216:217]
	v_rcp_f32_e32 v220, v208
	v_rcp_f32_e32 v221, v209
	v_pk_mul_f32 v[204:205], v[204:205], s[36:37] op_sel_hi:[1,0]
	v_add_f32_e32 v0, v94, v95
	v_exp_f32_e32 v202, v202
	v_exp_f32_e32 v203, v203
	v_exp_f32_e32 v204, v204
	v_exp_f32_e32 v205, v205
	v_add_f32_dpp v0, v0, v0 quad_perm:[1,0,3,2] row_mask:0xf bank_mask:0xf bound_ctrl:1
	v_pk_add_f32 v[96:97], v[96:97], 1.0 op_sel_hi:[1,0]
	v_pk_add_f32 v[98:99], v[98:99], 1.0 op_sel_hi:[1,0]
	v_pk_fma_f32 v[208:209], v[46:47], v[220:221], v[160:161]
	v_add_f32_dpp v0, v0, v0 quad_perm:[2,3,0,1] row_mask:0xf bank_mask:0xf bound_ctrl:1
	v_rcp_f32_e32 v96, v96
	v_rcp_f32_e32 v97, v97
	v_rcp_f32_e32 v98, v98
	v_rcp_f32_e32 v99, v99
	v_pk_mul_f32 v[208:209], v[208:209], v[210:211]
	v_add_f32_dpp v95, v0, v0 row_half_mirror row_mask:0xf bank_mask:0xf bound_ctrl:1
	v_pk_mul_f32 v[210:211], v[208:209], v[92:93]
	v_max_f32_e32 v95, 0x2b8cbccc, v95
	v_pk_add_f32 v[202:203], v[202:203], 1.0 op_sel_hi:[1,0]
	v_pk_add_f32 v[204:205], v[204:205], 1.0 op_sel_hi:[1,0]
	v_pk_fma_f32 v[210:211], v[54:55], v[210:211], v[216:217]
	v_rsq_f32_e32 v216, v95
	v_rcp_f32_e32 v202, v202
	v_rcp_f32_e32 v203, v203
	v_rcp_f32_e32 v204, v204
	v_rcp_f32_e32 v205, v205
	v_pk_mul_f32 v[96:97], v[96:97], s[38:39] op_sel_hi:[1,0]
	v_pk_mul_f32 v[98:99], v[98:99], s[38:39] op_sel_hi:[1,0]
	v_add3_u32 v95, s15, v175, v144
	v_exp_f32_e32 v96, v96
	v_exp_f32_e32 v97, v97
	v_exp_f32_e32 v98, v98
	v_exp_f32_e32 v99, v99
	v_add_u32_e32 v217, 0x8800, v95
	v_add_f32_e32 v0, v210, v211
	v_pk_mul_f32 v[210:211], v[212:213], v[216:217] op_sel_hi:[1,0] neg_lo:[0,1] neg_hi:[0,1]
	v_pk_mul_f32 v[212:213], v[218:219], v[216:217] op_sel_hi:[1,0] neg_lo:[0,1] neg_hi:[0,1]
	v_pk_mul_f32 v[202:203], v[202:203], s[38:39] op_sel_hi:[1,0]
	v_pk_mul_f32 v[204:205], v[204:205], s[38:39] op_sel_hi:[1,0]
	v_pk_mul_f32 v[100:101], v[212:213], v[100:101]
	s_waitcnt lgkmcnt(0)
	v_exp_f32_e32 v202, v202
	v_exp_f32_e32 v203, v203
	v_exp_f32_e32 v204, v204
	v_exp_f32_e32 v205, v205
	ds_write_b128 v95, v[86:89] offset:34816
	ds_write_b128 v95, v[96:99] offset:43008
	ds_write_b128 v95, v[126:129] offset:51200
	ds_write_b128 v95, v[210:213] offset:59392
	v_pk_mul_f32 v[86:87], v[210:211], v[214:215] neg_lo:[0,1] neg_hi:[0,1]
	v_xor_b32_e32 v88, 0x80000000, v100
	v_xor_b32_e32 v89, 0x80000000, v101
	v_add_f32_dpp v0, v0, v0 quad_perm:[1,0,3,2] row_mask:0xf bank_mask:0xf bound_ctrl:1
	ds_write_b128 v217, v[86:89] offset:32768
	v_pk_mul_f32 v[88:89], v[226:227], v[216:217] op_sel_hi:[1,0] neg_lo:[0,1] neg_hi:[0,1]
	v_add_f32_dpp v0, v0, v0 quad_perm:[2,3,0,1] row_mask:0xf bank_mask:0xf bound_ctrl:1
	v_mov_b32_e32 v94, 0
	v_pk_mul_f32 v[86:87], v[224:225], v[216:217] op_sel_hi:[1,0] neg_lo:[0,1] neg_hi:[0,1]
	v_pk_mul_f32 v[96:97], v[88:89], v[220:221]
	v_mov_b32_dpp v94, v0 row_half_mirror row_mask:0xf bank_mask:0xf
	ds_write_b128 v95, v[90:93] offset:34832
	ds_write_b128 v95, v[202:205] offset:43024
	ds_write_b128 v95, v[206:209] offset:51216
	ds_write_b128 v95, v[86:89] offset:59408
	v_pk_mul_f32 v[86:87], v[86:87], v[222:223] neg_lo:[0,1] neg_hi:[0,1]
	v_xor_b32_e32 v88, 0x80000000, v96
	v_xor_b32_e32 v89, 0x80000000, v97
	ds_write_b128 v217, v[86:89] offset:32784
	s_and_saveexec_b64 s[56:57], s[10:11]
	s_cbranch_execz .LBB0_612
	v_pk_fma_f16 v82, v78, s14, v82
	v_pk_fma_f16 v83, v79, s14, v83
	v_pk_fma_f16 v78, v62, v82, v78
	v_pk_fma_f16 v84, v80, s14, v84
	v_pk_fma_f16 v79, v63, v83, v79
	v_cvt_f32_f16_e32 v82, v78
	v_cvt_f32_f16_sdwa v78, v78 dst_sel:DWORD dst_unused:UNUSED_PAD src0_sel:WORD_1
	s_add_i32 s15, s15, 0x8800
	v_pk_fma_f16 v85, v81, s14, v85
	v_pk_fma_f16 v80, v72, v84, v80
	v_cvt_f32_f16_e32 v83, v79
	v_cvt_f32_f16_sdwa v79, v79 dst_sel:DWORD dst_unused:UNUSED_PAD src0_sel:WORD_1
	v_lshlrev_b32_e32 v86, 2, v169
	v_pk_fma_f16 v81, v73, v85, v81
	v_cvt_f32_f16_e32 v84, v80
	v_cvt_f32_f16_sdwa v80, v80 dst_sel:DWORD dst_unused:UNUSED_PAD src0_sel:WORD_1
	v_add3_u32 v86, s15, v201, v86
	v_cvt_f32_f16_e32 v85, v81
	v_cvt_f32_f16_sdwa v81, v81 dst_sel:DWORD dst_unused:UNUSED_PAD src0_sel:WORD_1
	v_add_u32_e32 v86, 0xa000, v86
	ds_write2_b32 v86, v82, v78 offset1:32
	ds_write2_b32 v86, v83, v79 offset0:64 offset1:96
	ds_write2_b32 v86, v84, v80 offset0:128 offset1:160
	ds_write2_b32 v86, v85, v81 offset0:192 offset1:224

; #define LAS __attribute__((address_space(3)))
; #define SCAN_LOAD(chn) SCAN_LOAD_RAW()
; __device__ __forceinline__ void phase_scan(const Params& p, LAS unsigned char* lds) {
;     ...
;                     { unsigned m1u_ = 0xBC00BC00u; asm volatile("" : "+s"(m1u_));
;                       typedef unsigned u32x4_ __attribute__((ext_vector_type(4))); const u32x4_ m1v_ = {m1u_, m1u_, m1u_, m1u_}; const h16x8 m1_ = __builtin_bit_cast(h16x8, m1v_);
;                       const h16x8 r8 = pr + mu_r8 * (pr * m1_ + qr_), k8 = pk + mu_k8 * (pk * m1_ + qk_), v8 = pv + mu_v8 * (pv * m1_ + qv_);
;                       const h16x8 w8 = pw + mu_w8 * (pw * m1_ + qw_), a8 = pa + mu_a8 * (pa * m1_ + qa_);
;                       h16x8 tw8;
; #pragma unroll
;                       for (int pi = 0; pi < 4; ++pi) { qr[pi] = (f32x2){(float)r8[2 * pi], (float)r8[2 * pi + 1]}; qk[pi] = (f32x2){(float)k8[2 * pi], (float)k8[2 * pi + 1]};
;                           qv[2 * pi] = (float)v8[2 * pi]; qv[2 * pi + 1] = (float)v8[2 * pi + 1];
;                           const f32x2 tx = (f32x2){(float)w8[2 * pi], (float)w8[2 * pi + 1]} * 2.8853900817779268f;
;                           const f32x2 dn = (f32x2){__builtin_amdgcn_exp2f(tx[0]), __builtin_amdgcn_exp2f(tx[1])} + 1.f;
;                           const f32x2 th = (f32x2){__builtin_amdgcn_rcpf(dn[0]), __builtin_amdgcn_rcpf(dn[1])} * -2.f + 1.f;
;                           tw8[2 * pi] = (h16)th[0]; tw8[2 * pi + 1] = (h16)th[1]; }
;                       *(LAS h16x8*)(TWp + s_sub * 72 + c8) = tw8; *(LAS h16x8*)(QAp + s_sub * 72 + c8) = a8; }
;                     if (cn + 1 < SEQ / 32) SCAN_LOAD(cn + 1);
.LBB0_614:
	s_or_b64 exec, exec, s[56:57]
.LBB0_616:
.LBB0_617:
	s_andn2_saveexec_b64 s[54:55], s[54:55]
	s_cbranch_execz .LBB0_603
	s_branch .LBB0_603
.Lpb_top:
	s_waitcnt vmcnt(2)
	s_and_saveexec_b64 s[14:15], s[0:1]
	s_xor_b64 s[54:55], exec, s[14:15]
	s_cbranch_execz .Lpb_617
	s_cmpk_eq_i32 s81, 0xff
	s_cbranch_scc1 .Lpb_608
	s_mov_b32 s14, 0xbc00bc00
	s_cmpk_eq_i32 s81, 0xfe
	s_waitcnt vmcnt(1)
	v_pk_fma_f16 v0, v4, s14, v12
	v_pk_fma_f16 v78, v5, s14, v13
	v_pk_fma_f16 v79, v6, s14, v14
	v_pk_fma_f16 v80, v7, s14, v15
	v_pk_fma_f16 v83, v74, v79, v6
	v_pk_fma_f16 v85, v75, v80, v7
	v_pk_fma_f16 v81, v65, v78, v5
	v_pk_fma_f16 v0, v64, v0, v4
	v_cvt_f32_f16_e32 v80, v81
	v_cvt_f32_f16_e32 v78, v0
	v_cvt_f32_f16_sdwa v79, v0 dst_sel:DWORD dst_unused:UNUSED_PAD src0_sel:WORD_1
	v_cvt_f32_f16_sdwa v81, v81 dst_sel:DWORD dst_unused:UNUSED_PAD src0_sel:WORD_1
	v_cvt_f32_f16_e32 v82, v83
	v_cvt_f32_f16_sdwa v83, v83 dst_sel:DWORD dst_unused:UNUSED_PAD src0_sel:WORD_1
	v_cvt_f32_f16_e32 v84, v85
	v_cvt_f32_f16_sdwa v85, v85 dst_sel:DWORD dst_unused:UNUSED_PAD src0_sel:WORD_1
	v_pk_mul_f32 v[78:79], v[78:79], s[30:31] op_sel_hi:[1,0]
	v_pk_mul_f32 v[80:81], v[80:81], s[30:31] op_sel_hi:[1,0]
	v_pk_mul_f32 v[82:83], v[82:83], s[30:31] op_sel_hi:[1,0]
	v_pk_mul_f32 v[84:85], v[84:85], s[30:31] op_sel_hi:[1,0]
	v_exp_f32_e32 v78, v78
	v_exp_f32_e32 v79, v79
	v_exp_f32_e32 v80, v80
	v_exp_f32_e32 v81, v81
	v_exp_f32_e32 v82, v82
	v_exp_f32_e32 v83, v83
	v_exp_f32_e32 v84, v84
	v_exp_f32_e32 v85, v85
	v_pk_add_f32 v[78:79], v[78:79], 1.0 op_sel_hi:[1,0]
	v_pk_add_f32 v[80:81], v[80:81], 1.0 op_sel_hi:[1,0]
	v_pk_add_f32 v[82:83], v[82:83], 1.0 op_sel_hi:[1,0]
	v_pk_add_f32 v[84:85], v[84:85], 1.0 op_sel_hi:[1,0]
	v_rcp_f32_e32 v78, v78
	v_rcp_f32_e32 v79, v79
	v_rcp_f32_e32 v80, v80
	v_rcp_f32_e32 v81, v81
	v_rcp_f32_e32 v82, v82
	v_rcp_f32_e32 v83, v83
	v_rcp_f32_e32 v84, v84
	v_rcp_f32_e32 v85, v85
	s_waitcnt vmcnt(0)
	v_pk_fma_f16 v88, v8, s14, v16
	v_pk_fma_f16 v89, v9, s14, v17
	v_pk_fma_f16 v90, v10, s14, v18
	v_pk_fma_f16 v0, v11, s14, v19
	v_pk_fma_f32 v[86:87], v[78:79], 2.0, 1.0 op_sel_hi:[1,0,0] neg_lo:[1,0,0] neg_hi:[1,0,0]
	v_pk_fma_f32 v[78:79], v[80:81], 2.0, 1.0 op_sel_hi:[1,0,0] neg_lo:[1,0,0] neg_hi:[1,0,0]
	v_pk_fma_f32 v[82:83], v[82:83], 2.0, 1.0 op_sel_hi:[1,0,0] neg_lo:[1,0,0] neg_hi:[1,0,0]
	v_pk_fma_f32 v[80:81], v[84:85], 2.0, 1.0 op_sel_hi:[1,0,0] neg_lo:[1,0,0] neg_hi:[1,0,0]
	v_cvt_pk_f16_f32 v79, v78, v79
	v_cvt_pk_f16_f32 v81, v80, v81
	v_cvt_pk_f16_f32 v80, v82, v83
	v_cvt_pk_f16_f32 v78, v86, v87
	v_pk_fma_f16 v85, v77, v0, v11
	v_pk_fma_f16 v84, v76, v90, v10
	v_pk_fma_f16 v83, v67, v89, v9
	v_pk_fma_f16 v82, v66, v88, v8
	ds_write_b128 v171, v[78:81] offset:18432
	ds_write_b128 v172, v[82:85] offset:19584
	s_cbranch_scc1 .Lpb_609
	v_lshl_add_u64 v[4:5], v[148:149], 0, s[20:21]
	global_load_dwordx4 v[94:97], v[146:147], off
	global_load_dwordx4 v[86:89], v[146:147], off offset:2048
	global_load_dwordx4 v[78:81], v[4:5], off
	s_nop 0
	global_load_dwordx4 v[4:7], v[148:149], off offset:2048
	global_load_dwordx4 v[8:11], v[148:149], off offset:2176
	global_load_dwordx4 v[98:101], v[152:153], off
	global_load_dwordx4 v[90:93], v[152:153], off offset:2048
	v_lshl_add_u64 v[12:13], v[150:151], 0, s[20:21]
	global_load_dwordx4 v[82:85], v[12:13], off
	s_nop 0
	global_load_dwordx4 v[12:15], v[150:151], off offset:2048
	global_load_dwordx4 v[16:19], v[150:151], off offset:2176
	s_lshl_b64 s[34:35], s[46:47], 1
	v_lshl_add_u64 v[146:147], v[146:147], 0, s[34:35]
	v_lshl_add_u64 v[148:149], v[148:149], 0, s[34:35]
	s_lshl_b64 s[34:35], s[40:41], 1
	v_lshl_add_u64 v[152:153], v[146:147], 0, s[34:35]
	v_lshl_add_u64 v[150:151], v[148:149], 0, s[34:35]
	s_branch .Lpb_610

; #define LAS __attribute__((address_space(3)))
; #define LDS_WAIT() asm volatile("s_waitcnt lgkmcnt(0)" ::: "memory")
; __device__ __forceinline__ void phase_scan(const Params& p, LAS unsigned char* lds) {
;     ...
;                     LDS_WAIT();
;                     f32x4 accw[4], acca[4];
; #pragma unroll
;                     for (int ct = 0; ct < 4; ++ct) { accw[ct] = (f32x4){0.f, 0.f, 0.f, 0.f}; acca[ct] = (f32x4){0.f, 0.f, 0.f, 0.f}; }
; #pragma unroll
;                     for (int ks = 0; ks < 2; ++ks) {
;                         const h16x8 atw = *(const LAS h16x8*)(TWp + (lane & 7) * 72 + 32 * ks + 8 * (lane >> 4));
;                         const h16x8 aqa = *(const LAS h16x8*)(QAp + (lane & 7) * 72 + 32 * ks + 8 * (lane >> 4));
; #pragma unroll
;                         for (int ct = 0; ct < 4; ++ct) {
;                             const h16x8 bw = *(const LAS h16x8*)(w2T + (16 * ct + (lane & 15)) * 72 + 32 * ks + 8 * (lane >> 4));
;                             const h16x8 ba = *(const LAS h16x8*)(a2T + (16 * ct + (lane & 15)) * 72 + 32 * ks + 8 * (lane >> 4));
;                             accw[ct] = __builtin_amdgcn_mfma_f32_16x16x32_f16(atw, bw, accw[ct], 0, 0, 0);
;                             acca[ct] = __builtin_amdgcn_mfma_f32_16x16x32_f16(aqa, ba, acca[ct], 0, 0, 0);
;                         }
;                     }
;                     LDS_WAIT();
;                     { LAS float* Zd = (LAS float*)priv + (lane >> 5) * 512 + (4 * ((lane >> 4) & 1)) * 64 + (lane & 15);
; #pragma unroll
;                       for (int ct = 0; ct < 4; ++ct)
; #pragma unroll
;                           for (int r = 0; r < 4; ++r) Zd[r * 64 + 16 * ct] = (lane < 32) ? accw[ct][r] : acca[ct][r]; }
;                     LDS_WAIT();
;                     const LAS float* Zw = (const LAS float*)priv + s_sub * 64 + c8; const LAS float* Za = Zw + 512;
;                     const f32x4 zw0 = *(const LAS f32x4*)Zw, zw1 = *(const LAS f32x4*)(Zw + 4), za0 = *(const LAS f32x4*)Za, za1 = *(const LAS f32x4*)(Za + 4);
;                     LDS_WAIT();
;                     f32x2 kk[4], av_[4], kp[4], dec[4], kn2 = {0.f, 0.f}, sb2 = {0.f, 0.f};
; #pragma unroll
;                     for (int pi = 0; pi < 4; ++pi) {
;                         const f32x2 zw = (pi < 2 ? (f32x2){zw0[2 * pi], zw0[2 * pi + 1]} : (f32x2){zw1[2 * pi - 4], zw1[2 * pi - 3]}) + w0r[pi];
.Lpb_609:
.Lpb_610:
	s_waitcnt lgkmcnt(0)
	v_pk_fma_f16 v222, v119, s14, v123
	v_pk_fma_f16 v218, v120, s14, v124
	v_pk_fma_f16 v219, v121, s14, v125
	ds_read_b128 v[126:129], v173 offset:18432
	ds_read_b128 v[202:205], v173 offset:19584
	ds_read_b128 v[206:209], v183
	ds_read_b128 v[210:213], v183 offset:9216
	v_pk_fma_f16 v0, v118, s14, v122
	ds_read_b128 v[214:217], v183 offset:2304
	ds_read_b128 v[122:125], v183 offset:11520
	v_pk_fma_f16 v242, v69, v219, v121
	v_pk_fma_f16 v238, v68, v218, v120
	ds_read_b128 v[218:221], v183 offset:4608
	v_pk_fma_f16 v239, v3, v222, v119
	ds_read_b128 v[222:225], v183 offset:13824
	ds_read_b128 v[230:233], v183 offset:16128
	ds_read_b128 v[234:237], v173 offset:18496
	ds_read_b128 v[226:229], v173 offset:19648
	s_waitcnt lgkmcnt(8)
	v_mfma_f32_16x16x32_f16 v[206:209], v[126:129], v[206:209], 0
	v_pk_fma_f16 v0, v2, v0, v118
	v_pk_fma_f16 v118, v110, s14, v114
	v_pk_fma_f16 v119, v111, s14, v115
	s_waitcnt lgkmcnt(7)
	v_mfma_f32_16x16x32_f16 v[210:213], v[202:205], v[210:213], 0
	v_pk_fma_f16 v240, v61, v119, v111
	v_cvt_f32_f16_sdwa v111, v0 dst_sel:DWORD dst_unused:UNUSED_PAD src0_sel:WORD_1
	s_bitcmp1_b32 s81, 0
	s_waitcnt lgkmcnt(6)
	v_mfma_f32_16x16x32_f16 v[214:217], v[126:129], v[214:217], 0
	s_cselect_b32 s15, 0, 0xa800
	s_add_i32 s15, s15, 0
	s_waitcnt lgkmcnt(5)
	v_mfma_f32_16x16x32_f16 v[120:123], v[202:205], v[122:125], 0
	v_pk_fma_f16 v124, v112, s14, v116
	v_pk_fma_f16 v125, v113, s14, v117
	v_pk_fma_f16 v244, v70, v124, v112
	s_waitcnt lgkmcnt(4)
	v_mfma_f32_16x16x32_f16 v[218:221], v[126:129], v[218:221], 0
	v_pk_fma_f16 v243, v71, v125, v113
	v_pk_fma_f16 v125, v60, v118, v110
	v_cvt_f32_f16_e32 v110, v0
	s_waitcnt lgkmcnt(3)
	v_mfma_f32_16x16x32_f16 v[222:225], v[202:205], v[222:225], 0
	v_cvt_f32_f16_e32 v124, v125
	v_cvt_f32_f16_sdwa v125, v125 dst_sel:DWORD dst_unused:UNUSED_PAD src0_sel:WORD_1
	v_mfma_f32_16x16x32_f16 v[126:129], v[126:129], v[250:253], 0
	s_waitcnt lgkmcnt(2)
	v_mfma_f32_16x16x32_f16 v[202:205], v[202:205], v[230:233], 0
	s_waitcnt lgkmcnt(1)
	v_mfma_f32_16x16x32_f16 v[206:209], v[234:237], v[132:135], v[206:209]
	s_waitcnt lgkmcnt(0)
	v_mfma_f32_16x16x32_f16 v[210:213], v[226:229], v[136:139], v[210:213]
	v_mfma_f32_16x16x32_f16 v[214:217], v[234:237], v[164:167], v[214:217]
	v_cvt_f32_f16_e32 v112, v239
	v_cvt_f32_f16_sdwa v113, v239 dst_sel:DWORD dst_unused:UNUSED_PAD src0_sel:WORD_1
	s_nop 2
	s_nop 1
	v_cndmask_b32_e64 v0, v210, v206, s[4:5]
	s_waitcnt lgkmcnt(0)
	v_mfma_f32_16x16x32_f16 v[218:221], v[234:237], v[188:191], v[218:221]
	v_cndmask_b32_e64 v206, v212, v208, s[4:5]
	v_add_u32_e32 v208, 0x4800, v174
	v_mfma_f32_16x16x32_f16 v[120:123], v[226:229], v[184:187], v[120:123]
	v_cvt_f32_f16_e32 v118, v240
	v_cvt_f32_f16_sdwa v119, v240 dst_sel:DWORD dst_unused:UNUSED_PAD src0_sel:WORD_1
	s_waitcnt lgkmcnt(0)
	v_mfma_f32_16x16x32_f16 v[222:225], v[226:229], v[196:199], v[222:225]
	v_cvt_f32_f16_e32 v114, v238
	v_cvt_f32_f16_sdwa v115, v238 dst_sel:DWORD dst_unused:UNUSED_PAD src0_sel:WORD_1
	v_mfma_f32_16x16x32_f16 v[126:129], v[234:237], v[192:195], v[126:129]
	s_nop 0
	v_cndmask_b32_e64 v120, v120, v214, s[4:5]
	s_waitcnt lgkmcnt(0)
	v_cndmask_b32_e64 v117, v211, v207, s[4:5]
	s_waitcnt lgkmcnt(0)
	v_mfma_f32_16x16x32_f16 v[202:205], v[226:229], v[246:249], v[202:205]
	ds_write2_b32 v208, v0, v120 offset1:16
	v_cndmask_b32_e64 v0, v121, v215, s[4:5]
	ds_write2_b32 v208, v117, v0 offset0:64 offset1:80
	v_cndmask_b32_e64 v0, v122, v216, s[4:5]
	v_cndmask_b32_e64 v207, v213, v209, s[4:5]
	ds_write2_b32 v208, v206, v0 offset0:128 offset1:144
	v_cndmask_b32_e64 v0, v123, v217, s[4:5]
	ds_write2_b32 v208, v207, v0 offset0:192 offset1:208
	v_cndmask_b32_e64 v0, v222, v218, s[4:5]
	v_cndmask_b32_e64 v122, v202, v126, s[4:5]
	v_cndmask_b32_e64 v117, v223, v219, s[4:5]
	ds_write2_b32 v208, v0, v122 offset0:32 offset1:48
	v_cndmask_b32_e64 v0, v203, v127, s[4:5]
	v_cndmask_b32_e64 v120, v224, v220, s[4:5]
	ds_write2_b32 v208, v117, v0 offset0:96 offset1:112
	v_cndmask_b32_e64 v0, v204, v128, s[4:5]
	v_cndmask_b32_e64 v121, v225, v221, s[4:5]
	ds_write2_b32 v208, v120, v0 offset0:160 offset1:176
	v_cndmask_b32_e64 v0, v205, v129, s[4:5]
	ds_write2_b32 v208, v121, v0 offset0:224 offset1:240
	s_waitcnt lgkmcnt(0)
	ds_read_b128 v[126:129], v200 offset:20480
	ds_read_b128 v[206:209], v200 offset:20496
	v_pk_mul_f32 v[212:213], v[40:41], v[124:125]
	v_pk_mul_f32 v[218:219], v[42:43], v[118:119]
	ds_read_b128 v[120:123], v200 offset:18432
	ds_read_b128 v[202:205], v200 offset:18448
	s_waitcnt lgkmcnt(3)
	v_pk_add_f32 v[126:127], v[32:33], v[126:127]
	s_waitcnt lgkmcnt(2)
	v_pk_add_f32 v[208:209], v[30:31], v[208:209]
	v_pk_mul_f32 v[126:127], v[126:127], s[36:37] op_sel_hi:[1,0]
	v_cvt_f32_f16_e32 v230, v244
	v_exp_f32_e32 v126, v126
	v_exp_f32_e32 v127, v127
	v_cvt_f32_f16_sdwa v231, v244 dst_sel:DWORD dst_unused:UNUSED_PAD src0_sel:WORD_1
	v_pk_mul_f32 v[208:209], v[208:209], s[36:37] op_sel_hi:[1,0]
	v_cvt_f32_f16_e32 v210, v243
	v_pk_add_f32 v[126:127], v[126:127], 1.0 op_sel_hi:[1,0]
	v_exp_f32_e32 v208, v208
	v_rcp_f32_e32 v214, v126
	v_rcp_f32_e32 v215, v127
	v_exp_f32_e32 v209, v209
	v_cvt_f32_f16_sdwa v211, v243 dst_sel:DWORD dst_unused:UNUSED_PAD src0_sel:WORD_1
	s_waitcnt lgkmcnt(1)
; #define LAS __attribute__((address_space(3)))
; __device__ __forceinline__ void phase_scan(const Params& p, LAS unsigned char* lds) {
;     ...
;                     f32x2 kk[4], av_[4], kp[4], dec[4], kn2 = {0.f, 0.f}, sb2 = {0.f, 0.f};
; #pragma unroll
;                     for (int pi = 0; pi < 4; ++pi) {
;                         const f32x2 zw = (pi < 2 ? (f32x2){zw0[2 * pi], zw0[2 * pi + 1]} : (f32x2){zw1[2 * pi - 4], zw1[2 * pi - 3]}) + w0r[pi];
;                         const f32x2 za = (pi < 2 ? (f32x2){za0[2 * pi], za0[2 * pi + 1]} : (f32x2){za1[2 * pi - 4], za1[2 * pi - 3]}) + a0r[pi];
;                         const f32x2 tw_ = zw * -1.4426950408889634f, ta_ = za * -1.4426950408889634f;
;                         const f32x2 dw = (f32x2){__builtin_amdgcn_exp2f(tw_[0]), __builtin_amdgcn_exp2f(tw_[1])} + 1.f, da = (f32x2){__builtin_amdgcn_exp2f(ta_[0]), __builtin_amdgcn_exp2f(ta_[1])} + 1.f;
;                         const f32x2 sw = (f32x2){__builtin_amdgcn_rcpf(dw[0]), __builtin_amdgcn_rcpf(dw[1])} * -0.8750387749225136f;
;                         dec[pi] = (f32x2){__builtin_amdgcn_exp2f(sw[0]), __builtin_amdgcn_exp2f(sw[1])};
;                         av_[pi] = (f32x2){__builtin_amdgcn_rcpf(da[0]), __builtin_amdgcn_rcpf(da[1])};
;                         kk[pi] = qk[pi] * kkr[pi]; kn2 = kk[pi] * kk[pi] + kn2;
;                         kp[pi] = qk[pi] * (av_[pi] * kar[pi] + omk[pi]);
;                         sb2 = (qr[pi] * kp[pi]) * rkr[pi] + sb2; }
;                     const float kn = red8(kn2[0] + kn2[1]), sbn = red8(sb2[0] + sb2[1]);
;                     const float ninv = -rsqrtf(fmaxf(kn, 1e-12f));
;                     LAS float* dR = OPS + (cn & 1) * SET_F + s_l * 64 + c8;
; #pragma unroll
;                     for (int hf = 0; hf < 2; ++hf) {
;                         const f32x2 na0 = kk[2 * hf] * ninv, na1 = kk[2 * hf + 1] * ninv;
;                         const f32x2 nb0 = na0 * av_[2 * hf], nb1 = na1 * av_[2 * hf + 1];
;                         *(LAS f32x4*)(dR + 4 * hf) = (f32x4){qr[2 * hf][0], qr[2 * hf][1], qr[2 * hf + 1][0], qr[2 * hf + 1][1]};
;                         *(LAS f32x4*)(dR + 2048 + 4 * hf) = (f32x4){dec[2 * hf][0], dec[2 * hf][1], dec[2 * hf + 1][0], dec[2 * hf + 1][1]};
;                         *(LAS f32x4*)(dR + 4096 + 4 * hf) = (f32x4){kp[2 * hf][0], kp[2 * hf][1], kp[2 * hf + 1][0], kp[2 * hf + 1][1]};
	v_pk_add_f32 v[120:121], v[24:25], v[120:121]
	v_pk_fma_f32 v[126:127], v[48:49], v[214:215], v[154:155]
	v_pk_add_f32 v[122:123], v[26:27], v[122:123]
	v_pk_mul_f32 v[126:127], v[126:127], v[124:125]
	v_pk_add_f32 v[124:125], v[34:35], v[128:129]
	v_pk_mul_f32 v[128:129], v[126:127], v[110:111]
	v_pk_mul_f32 v[124:125], v[124:125], s[36:37] op_sel_hi:[1,0]
	v_pk_fma_f32 v[216:217], v[56:57], v[128:129], 0 op_sel_hi:[1,1,0]
	v_exp_f32_e32 v124, v124
	v_exp_f32_e32 v125, v125
	v_pk_mul_f32 v[128:129], v[218:219], v[218:219]
	v_pk_mul_f32 v[224:225], v[36:37], v[230:231]
	v_pk_fma_f32 v[220:221], v[212:213], v[212:213], v[128:129]
	v_pk_add_f32 v[124:125], v[124:125], 1.0 op_sel_hi:[1,0]
	v_pk_mul_f32 v[120:121], v[120:121], s[36:37] op_sel_hi:[1,0]
	v_rcp_f32_e32 v124, v124
	v_rcp_f32_e32 v125, v125
	v_pk_mul_f32 v[122:123], v[122:123], s[36:37] op_sel_hi:[1,0]
	v_pk_add_f32 v[208:209], v[208:209], 1.0 op_sel_hi:[1,0]
	v_exp_f32_e32 v120, v120
	v_pk_fma_f32 v[128:129], v[50:51], v[124:125], v[156:157]
	v_exp_f32_e32 v121, v121
	v_pk_mul_f32 v[128:129], v[128:129], v[118:119]
	v_pk_add_f32 v[118:119], v[28:29], v[206:207]
	v_pk_mul_f32 v[206:207], v[128:129], v[112:113]
	v_pk_mul_f32 v[118:119], v[118:119], s[36:37] op_sel_hi:[1,0]
	v_pk_fma_f32 v[216:217], v[58:59], v[206:207], v[216:217]
	v_exp_f32_e32 v118, v118
	v_exp_f32_e32 v119, v119
	v_exp_f32_e32 v122, v122
	v_exp_f32_e32 v123, v123
	v_pk_mul_f32 v[226:227], v[38:39], v[210:211]
	v_pk_add_f32 v[118:119], v[118:119], 1.0 op_sel_hi:[1,0]
	s_waitcnt lgkmcnt(0)
	v_pk_add_f32 v[202:203], v[20:21], v[202:203]
	v_rcp_f32_e32 v222, v118
	v_rcp_f32_e32 v223, v119
	v_pk_fma_f32 v[118:119], v[224:225], v[224:225], v[220:221]
	v_pk_add_f32 v[204:205], v[22:23], v[204:205]
	v_pk_fma_f32 v[118:119], v[226:227], v[226:227], v[118:119]
	v_pk_fma_f32 v[206:207], v[44:45], v[222:223], v[158:159]
	v_cvt_f32_f16_e32 v116, v242
	v_pk_mul_f32 v[206:207], v[206:207], v[230:231]
	v_cvt_f32_f16_sdwa v117, v242 dst_sel:DWORD dst_unused:UNUSED_PAD src0_sel:WORD_1
	v_pk_mul_f32 v[220:221], v[206:207], v[114:115]
	v_pk_mul_f32 v[202:203], v[202:203], s[36:37] op_sel_hi:[1,0]
	v_pk_fma_f32 v[216:217], v[52:53], v[220:221], v[216:217]
	v_rcp_f32_e32 v220, v208
	v_rcp_f32_e32 v221, v209
	v_pk_mul_f32 v[204:205], v[204:205], s[36:37] op_sel_hi:[1,0]
	v_add_f32_e32 v0, v118, v119
	v_exp_f32_e32 v202, v202
	v_exp_f32_e32 v203, v203
	v_exp_f32_e32 v204, v204
	v_exp_f32_e32 v205, v205
	v_add_f32_dpp v0, v0, v0 quad_perm:[1,0,3,2] row_mask:0xf bank_mask:0xf bound_ctrl:1
	v_pk_add_f32 v[120:121], v[120:121], 1.0 op_sel_hi:[1,0]
	v_pk_add_f32 v[122:123], v[122:123], 1.0 op_sel_hi:[1,0]
	v_pk_fma_f32 v[208:209], v[46:47], v[220:221], v[160:161]
	v_add_f32_dpp v0, v0, v0 quad_perm:[2,3,0,1] row_mask:0xf bank_mask:0xf bound_ctrl:1
	v_rcp_f32_e32 v120, v120
	v_rcp_f32_e32 v121, v121
	v_rcp_f32_e32 v122, v122
	v_rcp_f32_e32 v123, v123
	v_pk_mul_f32 v[208:209], v[208:209], v[210:211]
	v_add_f32_dpp v119, v0, v0 row_half_mirror row_mask:0xf bank_mask:0xf bound_ctrl:1
	v_pk_mul_f32 v[210:211], v[208:209], v[116:117]
	v_max_f32_e32 v119, 0x2b8cbccc, v119
	v_pk_add_f32 v[202:203], v[202:203], 1.0 op_sel_hi:[1,0]
	v_pk_add_f32 v[204:205], v[204:205], 1.0 op_sel_hi:[1,0]
	v_pk_fma_f32 v[210:211], v[54:55], v[210:211], v[216:217]
	v_rsq_f32_e32 v216, v119
	v_rcp_f32_e32 v202, v202
	v_rcp_f32_e32 v203, v203
	v_rcp_f32_e32 v204, v204
	v_rcp_f32_e32 v205, v205
	v_pk_mul_f32 v[120:121], v[120:121], s[38:39] op_sel_hi:[1,0]
	v_pk_mul_f32 v[122:123], v[122:123], s[38:39] op_sel_hi:[1,0]
	v_add3_u32 v119, s15, v175, v144
	v_exp_f32_e32 v120, v120
	v_exp_f32_e32 v121, v121
	v_exp_f32_e32 v122, v122
	v_exp_f32_e32 v123, v123
	v_add_u32_e32 v217, 0x8800, v119
	v_add_f32_e32 v0, v210, v211
	v_pk_mul_f32 v[210:211], v[212:213], v[216:217] op_sel_hi:[1,0] neg_lo:[0,1] neg_hi:[0,1]
	v_pk_mul_f32 v[212:213], v[218:219], v[216:217] op_sel_hi:[1,0] neg_lo:[0,1] neg_hi:[0,1]
	v_pk_mul_f32 v[202:203], v[202:203], s[38:39] op_sel_hi:[1,0]
	v_pk_mul_f32 v[204:205], v[204:205], s[38:39] op_sel_hi:[1,0]
	v_pk_mul_f32 v[124:125], v[212:213], v[124:125]
	s_waitcnt lgkmcnt(0)
	v_exp_f32_e32 v202, v202
	v_exp_f32_e32 v203, v203
	v_exp_f32_e32 v204, v204
	v_exp_f32_e32 v205, v205
	ds_write_b128 v119, v[110:113] offset:34816
	ds_write_b128 v119, v[120:123] offset:43008
	ds_write_b128 v119, v[126:129] offset:51200
	ds_write_b128 v119, v[210:213] offset:59392
	v_pk_mul_f32 v[110:111], v[210:211], v[214:215] neg_lo:[0,1] neg_hi:[0,1]
	v_xor_b32_e32 v112, 0x80000000, v124
	v_xor_b32_e32 v113, 0x80000000, v125
	v_add_f32_dpp v0, v0, v0 quad_perm:[1,0,3,2] row_mask:0xf bank_mask:0xf bound_ctrl:1
	ds_write_b128 v217, v[110:113] offset:32768
	v_pk_mul_f32 v[112:113], v[226:227], v[216:217] op_sel_hi:[1,0] neg_lo:[0,1] neg_hi:[0,1]
	v_add_f32_dpp v0, v0, v0 quad_perm:[2,3,0,1] row_mask:0xf bank_mask:0xf bound_ctrl:1
	v_mov_b32_e32 v118, 0
	v_pk_mul_f32 v[110:111], v[224:225], v[216:217] op_sel_hi:[1,0] neg_lo:[0,1] neg_hi:[0,1]
	v_pk_mul_f32 v[120:121], v[112:113], v[220:221]
	v_mov_b32_dpp v118, v0 row_half_mirror row_mask:0xf bank_mask:0xf
	ds_write_b128 v119, v[114:117] offset:34832
	ds_write_b128 v119, v[202:205] offset:43024
	ds_write_b128 v119, v[206:209] offset:51216
	ds_write_b128 v119, v[110:113] offset:59408
	v_pk_mul_f32 v[110:111], v[110:111], v[222:223] neg_lo:[0,1] neg_hi:[0,1]
	v_xor_b32_e32 v112, 0x80000000, v120
	v_xor_b32_e32 v113, 0x80000000, v121
	ds_write_b128 v217, v[110:113] offset:32784
	s_and_saveexec_b64 s[56:57], s[10:11]
	s_cbranch_execz .Lpb_612
	v_pk_fma_f16 v106, v102, s14, v106
	v_pk_fma_f16 v107, v103, s14, v107
	v_pk_fma_f16 v102, v62, v106, v102
	v_pk_fma_f16 v108, v104, s14, v108
	v_pk_fma_f16 v103, v63, v107, v103
	v_cvt_f32_f16_e32 v106, v102
	v_cvt_f32_f16_sdwa v102, v102 dst_sel:DWORD dst_unused:UNUSED_PAD src0_sel:WORD_1
	s_add_i32 s15, s15, 0x8800
	v_pk_fma_f16 v109, v105, s14, v109
	v_pk_fma_f16 v104, v72, v108, v104
	v_cvt_f32_f16_e32 v107, v103
	v_cvt_f32_f16_sdwa v103, v103 dst_sel:DWORD dst_unused:UNUSED_PAD src0_sel:WORD_1
	v_lshlrev_b32_e32 v110, 2, v169
	v_pk_fma_f16 v105, v73, v109, v105
	v_cvt_f32_f16_e32 v108, v104
	v_cvt_f32_f16_sdwa v104, v104 dst_sel:DWORD dst_unused:UNUSED_PAD src0_sel:WORD_1
	v_add3_u32 v110, s15, v201, v110
	v_cvt_f32_f16_e32 v109, v105
	v_cvt_f32_f16_sdwa v105, v105 dst_sel:DWORD dst_unused:UNUSED_PAD src0_sel:WORD_1
	v_add_u32_e32 v110, 0xa000, v110
	ds_write2_b32 v110, v106, v102 offset1:32
	ds_write2_b32 v110, v107, v103 offset0:64 offset1:96
	ds_write2_b32 v110, v108, v104 offset0:128 offset1:160
	ds_write2_b32 v110, v109, v105 offset0:192 offset1:224
; #define LAS __attribute__((address_space(3)))
; __device__ __forceinline__ void phase_scan(const Params& p, LAS unsigned char* lds) {
;     ...
;                     for (int hb = 0; hb < 2; ++hb) {
;                         f32x4 vn[4];
; #pragma unroll
;                         for (int u = 0; u < 4; ++u) vn[u] = *(const LAS f32x4*)(sV + srow * 32 + ((16 * (hb + 1)) & 31) + 4 * u);
; #pragma unroll
;                         for (int u16 = 0; u16 < 16; ++u16) {
;                             const int s = 16 * hb + u16;
;                             const int sn = (s + 1) & 31;
;                             const f32x4 a_n = *(const LAS f32x4*)(sA + sn * 64), w_n = *(const LAS f32x4*)(sW + sn * 64), b_n = *(const LAS f32x4*)(sB + sn * 64);
;                             const f32x4 k_n = *(const LAS f32x4*)(sK + sn * 64), r_n = *(const LAS f32x4*)(sR + sn * 64);
;                             const float v = vq[u16 >> 2][u16 & 3];
;                             const f32x2 vv = {v, v};
;                             f32x2 pp = S01 * (f32x2){a_[0], a_[1]}; pp = S23 * (f32x2){a_[2], a_[3]} + pp;
;                             f32x2 yy = S01 * (f32x2){rp[0], rp[1]}; yy = S23 * (f32x2){rp[2], rp[3]} + yy;
;                             float sa = pp[0] + pp[1], y = yy[0] + yy[1];
;                             sa += dpp_f<0xB1>(sa); y += dpp_f<0xB1>(y);
;                             sa += dpp_f<0x4E>(sa); y += dpp_f<0x4E>(y);
;                             sa += dpp_f<0x141>(sa); y += dpp_f<0x141>(y);
;                             sa += dpp_f<0x140>(sa); y += dpp_f<0x140>(y);
;                             sY[((s - 1) & 31) * 16 + srow] = y;
;                             const f32x2 sv = {sa, sa};
;                             S01 = S01 * (f32x2){w_[0], w_[1]} + vv * (f32x2){k_[0], k_[1]};
;                             S23 = S23 * (f32x2){w_[2], w_[3]} + vv * (f32x2){k_[2], k_[3]};
;                             S01 = sv * (f32x2){b_[0], b_[1]} + S01;
;                             S23 = sv * (f32x2){b_[2], b_[3]} + S23;
;                             rp = r_;
;                             a_ = a_n; w_ = w_n; b_ = b_n; k_ = k_n; r_ = r_n;
;                         }
;     ...
;                     if (q == 0 && (lane & 7) == 0) SB[(size_t)(b * SEQ + t) * 16 + h] = sbn;
.Lpb_612:
	s_or_b64 exec, exec, s[56:57]
	s_and_saveexec_b64 s[56:57], s[12:13]
	s_cbranch_execz .Lpb_614
	v_subrev_u32_e32 v102, 64, v143
	v_cndmask_b32_e64 v102, v102, v145, s[8:9]
	v_add_u32_e32 v102, s79, v102
	v_ashrrev_i32_e32 v103, 31, v102
	v_lshlrev_b64 v[102:103], 6, v[102:103]
	v_add_f32_e32 v0, v0, v118
	v_lshl_add_u64 v[102:103], s[52:53], 0, v[102:103]
	global_store_dword v[102:103], v0, off
.Lpb_614:
	s_or_b64 exec, exec, s[56:57]
.Lpb_616:
.Lpb_617:
	s_andn2_saveexec_b64 s[54:55], s[54:55]
	s_cbranch_execz .LBB0_603
	s_branch .LBB0_603
.Lscan_wave_top:
	s_mov_b64 s[54:55], 0
	s_cmp_lt_i32 s81, 0
	s_cbranch_scc1 .LBB0_603
	s_setprio 3
	s_and_b32 s14, s81, 1
	s_mul_i32 s15, s14, 0xa800
	s_add_i32 s15, s15, 0x8800
	v_add_u32_e32 v124, s15, v178
	v_add_u32_e32 v125, s15, v179
	s_cmp_eq_u32 s81, 0
	s_cselect_b32 s14, 0xf000f000, -1
	s_mov_b32 s15, s14
	v_pk_mul_f32 v[114:115], v[166:167], v[22:23]
	v_pk_mul_f32 v[116:117], v[166:167], v[18:19]
	v_pk_fma_f32 v[114:115], v[164:165], v[24:25], v[114:115]
	v_pk_fma_f32 v[116:117], v[164:165], v[20:21], v[116:117]
	v_add_f32_e32 v122, v114, v115
	v_pk_mul_f32 v[118:119], v[110:111], v[34:35] op_sel:[1,0]
	v_add_f32_e32 v212, v116, v117
	v_add_f32_dpp v122, v122, v122 quad_perm:[1,0,3,2] row_mask:0xf bank_mask:0xf bound_ctrl:1
	v_pk_mul_f32 v[120:121], v[110:111], v[36:37] op_sel:[1,0]
	ds_read_b128 v[14:17], v124 offset:16384
	v_add_f32_dpp v122, v122, v122 quad_perm:[2,3,0,1] row_mask:0xf bank_mask:0xf bound_ctrl:1
	v_pk_fma_f32 v[166:167], v[166:167], v[26:27], v[118:119]
	ds_read_b128 v[6:9], v124 offset:8192
	v_add_f32_dpp v122, v122, v122 row_half_mirror row_mask:0xf bank_mask:0xf bound_ctrl:1
	v_pk_fma_f32 v[164:165], v[164:165], v[28:29], v[120:121]
	ds_read_b128 v[10:13], v124 offset:32768
	v_add_f32_dpp v122, v122, v122 row_mirror row_mask:0xf bank_mask:0xf bound_ctrl:1
	v_add_f32_dpp v204, v204, v204 row_mirror row_mask:0xf bank_mask:0xf bound_ctrl:1
	v_add_f32_dpp v204, v212, v212 row_mirror row_mask:0xf bank_mask:0xc bound_ctrl:1
	v_pk_fma_f32 v[166:167], v[30:31], v[122:123], v[166:167] op_sel_hi:[1,0,1]
	v_pk_fma_f32 v[164:165], v[32:33], v[122:123], v[164:165] op_sel_hi:[1,0,1]
	ds_read_b128 v[18:21], v124 offset:0
	ds_read_b128 v[2:5], v124 offset:24576
	ds_read_b128 v[82:85], v125 offset:40960
	v_pk_mul_f32 v[114:115], v[166:167], v[42:43]
	v_pk_mul_f32 v[116:117], v[166:167], v[38:39]
	v_pk_fma_f32 v[114:115], v[164:165], v[44:45], v[114:115]
	v_pk_fma_f32 v[116:117], v[164:165], v[40:41], v[116:117]
	v_add_f32_e32 v122, v114, v115
	v_pk_mul_f32 v[118:119], v[112:113], v[54:55] op_sel_hi:[0,1]
	v_add_f32_e32 v213, v116, v117
	v_add_f32_dpp v122, v122, v122 quad_perm:[1,0,3,2] row_mask:0xf bank_mask:0xf bound_ctrl:1
	v_pk_mul_f32 v[120:121], v[112:113], v[56:57] op_sel_hi:[0,1]
	ds_read_b128 v[34:37], v124 offset:16640
	v_add_f32_dpp v122, v122, v122 quad_perm:[2,3,0,1] row_mask:0xf bank_mask:0xf bound_ctrl:1
	v_pk_fma_f32 v[166:167], v[166:167], v[46:47], v[118:119]
	ds_read_b128 v[26:29], v124 offset:8448
	v_add_f32_dpp v122, v122, v122 row_half_mirror row_mask:0xf bank_mask:0xf bound_ctrl:1
	v_pk_fma_f32 v[164:165], v[164:165], v[48:49], v[120:121]
	ds_read_b128 v[30:33], v124 offset:33024
	v_add_f32_dpp v122, v122, v122 row_mirror row_mask:0xf bank_mask:0xf bound_ctrl:1
	v_add_f32_dpp v205, v205, v205 row_mirror row_mask:0xf bank_mask:0xf bound_ctrl:1
	v_add_f32_dpp v205, v213, v213 row_mirror row_mask:0xf bank_mask:0xc bound_ctrl:1
	v_pk_fma_f32 v[166:167], v[50:51], v[122:123], v[166:167] op_sel_hi:[1,0,1]
	v_pk_fma_f32 v[164:165], v[52:53], v[122:123], v[164:165] op_sel_hi:[1,0,1]
	ds_read_b128 v[38:41], v124 offset:256
	ds_read_b128 v[22:25], v124 offset:24832
	v_pk_mul_f32 v[114:115], v[166:167], v[62:63]
	v_pk_mul_f32 v[116:117], v[166:167], v[58:59]
	v_pk_fma_f32 v[114:115], v[164:165], v[64:65], v[114:115]
	v_pk_fma_f32 v[116:117], v[164:165], v[60:61], v[116:117]
	v_add_f32_e32 v122, v114, v115
	v_pk_mul_f32 v[118:119], v[112:113], v[74:75] op_sel:[1,0]
	v_add_f32_e32 v214, v116, v117
	v_add_f32_dpp v122, v122, v122 quad_perm:[1,0,3,2] row_mask:0xf bank_mask:0xf bound_ctrl:1
	v_pk_mul_f32 v[120:121], v[112:113], v[76:77] op_sel:[1,0]
	ds_read_b128 v[54:57], v124 offset:16896
	v_add_f32_dpp v122, v122, v122 quad_perm:[2,3,0,1] row_mask:0xf bank_mask:0xf bound_ctrl:1
	v_pk_fma_f32 v[166:167], v[166:167], v[66:67], v[118:119]
	ds_read_b128 v[46:49], v124 offset:8704
	v_add_f32_dpp v122, v122, v122 row_half_mirror row_mask:0xf bank_mask:0xf bound_ctrl:1
	v_pk_fma_f32 v[164:165], v[164:165], v[68:69], v[120:121]
	ds_read_b128 v[50:53], v124 offset:33280
	v_add_f32_dpp v122, v122, v122 row_mirror row_mask:0xf bank_mask:0xf bound_ctrl:1
	v_add_f32_dpp v206, v206, v206 row_mirror row_mask:0xf bank_mask:0xf bound_ctrl:1
	v_add_f32_dpp v206, v214, v214 row_mirror row_mask:0xf bank_mask:0xc bound_ctrl:1
	v_pk_fma_f32 v[166:167], v[70:71], v[122:123], v[166:167] op_sel_hi:[1,0,1]
	v_pk_fma_f32 v[164:165], v[72:73], v[122:123], v[164:165] op_sel_hi:[1,0,1]
	ds_read_b128 v[58:61], v124 offset:512
	ds_read_b128 v[42:45], v124 offset:25088
	s_waitcnt lgkmcnt(11)
	v_pk_mul_f32 v[114:115], v[166:167], v[2:3]
	v_pk_mul_f32 v[116:117], v[166:167], v[78:79]
	v_pk_fma_f32 v[114:115], v[164:165], v[4:5], v[114:115]
	v_pk_fma_f32 v[116:117], v[164:165], v[80:81], v[116:117]
	v_add_f32_e32 v122, v114, v115
	s_waitcnt lgkmcnt(10)
; #define LAS __attribute__((address_space(3)))
; template <int CTRL> __device__ __forceinline__ float dpp_f(float x) { return __int_as_float(__builtin_amdgcn_update_dpp(0, __float_as_int(x), CTRL, 0xf, 0xf, false)); }
; __device__ __forceinline__ void phase_scan(const Params& p, LAS unsigned char* lds) {
;     ...
;                     for (int hb = 0; hb < 2; ++hb) {
;                         f32x4 vn[4];
; #pragma unroll
;                         for (int u = 0; u < 4; ++u) vn[u] = *(const LAS f32x4*)(sV + srow * 32 + ((16 * (hb + 1)) & 31) + 4 * u);
; #pragma unroll
;                         for (int u16 = 0; u16 < 16; ++u16) {
;                             const int s = 16 * hb + u16;
;                             const int sn = (s + 1) & 31;
;                             const f32x4 a_n = *(const LAS f32x4*)(sA + sn * 64), w_n = *(const LAS f32x4*)(sW + sn * 64), b_n = *(const LAS f32x4*)(sB + sn * 64);
;                             const f32x4 k_n = *(const LAS f32x4*)(sK + sn * 64), r_n = *(const LAS f32x4*)(sR + sn * 64);
;                             const float v = vq[u16 >> 2][u16 & 3];
;                             const f32x2 vv = {v, v};
;                             f32x2 pp = S01 * (f32x2){a_[0], a_[1]}; pp = S23 * (f32x2){a_[2], a_[3]} + pp;
;                             f32x2 yy = S01 * (f32x2){rp[0], rp[1]}; yy = S23 * (f32x2){rp[2], rp[3]} + yy;
;                             float sa = pp[0] + pp[1], y = yy[0] + yy[1];
;                             sa += dpp_f<0xB1>(sa); y += dpp_f<0xB1>(y);
;                             sa += dpp_f<0x4E>(sa); y += dpp_f<0x4E>(y);
;                             sa += dpp_f<0x141>(sa); y += dpp_f<0x141>(y);
;                             sa += dpp_f<0x140>(sa); y += dpp_f<0x140>(y);
;                             sY[((s - 1) & 31) * 16 + srow] = y;
;                             const f32x2 sv = {sa, sa};
;                             S01 = S01 * (f32x2){w_[0], w_[1]} + vv * (f32x2){k_[0], k_[1]};
;                             S23 = S23 * (f32x2){w_[2], w_[3]} + vv * (f32x2){k_[2], k_[3]};
;                             S01 = sv * (f32x2){b_[0], b_[1]} + S01;
;                             S23 = sv * (f32x2){b_[2], b_[3]} + S23;
;                             rp = r_;
;                             a_ = a_n; w_ = w_n; b_ = b_n; k_ = k_n; r_ = r_n;
;                         }
	v_pk_mul_f32 v[118:119], v[82:83], v[14:15] op_sel_hi:[0,1]
	v_add_f32_e32 v215, v116, v117
	v_add_f32_dpp v122, v122, v122 quad_perm:[1,0,3,2] row_mask:0xf bank_mask:0xf bound_ctrl:1
	v_pk_mul_f32 v[120:121], v[82:83], v[16:17] op_sel_hi:[0,1]
	ds_read_b128 v[74:77], v124 offset:17152
	v_add_f32_dpp v122, v122, v122 quad_perm:[2,3,0,1] row_mask:0xf bank_mask:0xf bound_ctrl:1
	v_pk_fma_f32 v[166:167], v[166:167], v[6:7], v[118:119]
	ds_read_b128 v[66:69], v124 offset:8960
	v_add_f32_dpp v122, v122, v122 row_half_mirror row_mask:0xf bank_mask:0xf bound_ctrl:1
	v_pk_fma_f32 v[164:165], v[164:165], v[8:9], v[120:121]
	ds_read_b128 v[70:73], v124 offset:33536
	v_add_f32_dpp v122, v122, v122 row_mirror row_mask:0xf bank_mask:0xf bound_ctrl:1
	v_add_f32_dpp v207, v207, v207 row_mirror row_mask:0xf bank_mask:0xf bound_ctrl:1
	v_add_f32_dpp v207, v215, v215 row_mirror row_mask:0xf bank_mask:0xc bound_ctrl:1
	v_pk_fma_f32 v[166:167], v[10:11], v[122:123], v[166:167] op_sel_hi:[1,0,1]
	v_pk_fma_f32 v[164:165], v[12:13], v[122:123], v[164:165] op_sel_hi:[1,0,1]
	ds_read_b128 v[78:81], v124 offset:768
	ds_read_b128 v[62:65], v124 offset:25344
	s_waitcnt lgkmcnt(10)
	v_pk_mul_f32 v[114:115], v[166:167], v[22:23]
	v_pk_mul_f32 v[116:117], v[166:167], v[18:19]
	v_pk_fma_f32 v[114:115], v[164:165], v[24:25], v[114:115]
	v_pk_fma_f32 v[116:117], v[164:165], v[20:21], v[116:117]
	v_add_f32_e32 v122, v114, v115
	v_pk_mul_f32 v[118:119], v[82:83], v[34:35] op_sel:[1,0]
	v_add_f32_e32 v216, v116, v117
	v_add_f32_dpp v122, v122, v122 quad_perm:[1,0,3,2] row_mask:0xf bank_mask:0xf bound_ctrl:1
	v_pk_mul_f32 v[120:121], v[82:83], v[36:37] op_sel:[1,0]
	ds_read_b128 v[14:17], v124 offset:17408
	v_add_f32_dpp v122, v122, v122 quad_perm:[2,3,0,1] row_mask:0xf bank_mask:0xf bound_ctrl:1
	v_pk_fma_f32 v[166:167], v[166:167], v[26:27], v[118:119]
	ds_read_b128 v[6:9], v124 offset:9216
	v_add_f32_dpp v122, v122, v122 row_half_mirror row_mask:0xf bank_mask:0xf bound_ctrl:1
	v_pk_fma_f32 v[164:165], v[164:165], v[28:29], v[120:121]
	ds_read_b128 v[10:13], v124 offset:33792
	v_add_f32_dpp v122, v122, v122 row_mirror row_mask:0xf bank_mask:0xf bound_ctrl:1
	v_add_f32_dpp v208, v208, v208 row_mirror row_mask:0xf bank_mask:0xf bound_ctrl:1
	v_add_f32_dpp v208, v216, v216 row_mirror row_mask:0xf bank_mask:0xc bound_ctrl:1
	v_pk_fma_f32 v[166:167], v[30:31], v[122:123], v[166:167] op_sel_hi:[1,0,1]
	v_pk_fma_f32 v[164:165], v[32:33], v[122:123], v[164:165] op_sel_hi:[1,0,1]
	ds_read_b128 v[18:21], v124 offset:1024
	ds_read_b128 v[2:5], v124 offset:25600
	ds_read_b128 v[86:89], v125 offset:40976
	s_waitcnt lgkmcnt(11)
	v_pk_mul_f32 v[114:115], v[166:167], v[42:43]
	v_pk_mul_f32 v[116:117], v[166:167], v[38:39]
	v_pk_fma_f32 v[114:115], v[164:165], v[44:45], v[114:115]
	v_pk_fma_f32 v[116:117], v[164:165], v[40:41], v[116:117]
	v_add_f32_e32 v122, v114, v115
	v_pk_mul_f32 v[118:119], v[84:85], v[54:55] op_sel_hi:[0,1]
	v_add_f32_e32 v217, v116, v117
	v_add_f32_dpp v122, v122, v122 quad_perm:[1,0,3,2] row_mask:0xf bank_mask:0xf bound_ctrl:1
	v_pk_mul_f32 v[120:121], v[84:85], v[56:57] op_sel_hi:[0,1]
	ds_read_b128 v[34:37], v124 offset:17664
	v_add_f32_dpp v122, v122, v122 quad_perm:[2,3,0,1] row_mask:0xf bank_mask:0xf bound_ctrl:1
	v_pk_fma_f32 v[166:167], v[166:167], v[46:47], v[118:119]
	ds_read_b128 v[26:29], v124 offset:9472
	v_add_f32_dpp v122, v122, v122 row_half_mirror row_mask:0xf bank_mask:0xf bound_ctrl:1
	v_pk_fma_f32 v[164:165], v[164:165], v[48:49], v[120:121]
	ds_read_b128 v[30:33], v124 offset:34048
	v_add_f32_dpp v122, v122, v122 row_mirror row_mask:0xf bank_mask:0xf bound_ctrl:1
	v_add_f32_dpp v209, v209, v209 row_mirror row_mask:0xf bank_mask:0xf bound_ctrl:1
	v_add_f32_dpp v209, v217, v217 row_mirror row_mask:0xf bank_mask:0xc bound_ctrl:1
	v_pk_fma_f32 v[166:167], v[50:51], v[122:123], v[166:167] op_sel_hi:[1,0,1]
	v_pk_fma_f32 v[164:165], v[52:53], v[122:123], v[164:165] op_sel_hi:[1,0,1]
	ds_read_b128 v[38:41], v124 offset:1280
	ds_read_b128 v[22:25], v124 offset:25856
	s_waitcnt lgkmcnt(11)
	v_pk_mul_f32 v[114:115], v[166:167], v[62:63]
	v_pk_mul_f32 v[116:117], v[166:167], v[58:59]
	v_pk_fma_f32 v[114:115], v[164:165], v[64:65], v[114:115]
	v_pk_fma_f32 v[116:117], v[164:165], v[60:61], v[116:117]
	v_add_f32_e32 v122, v114, v115
	v_pk_mul_f32 v[118:119], v[84:85], v[74:75] op_sel:[1,0]
	v_add_f32_e32 v218, v116, v117
	v_add_f32_dpp v122, v122, v122 quad_perm:[1,0,3,2] row_mask:0xf bank_mask:0xf bound_ctrl:1
	v_pk_mul_f32 v[120:121], v[84:85], v[76:77] op_sel:[1,0]
	ds_read_b128 v[54:57], v124 offset:17920
	v_add_f32_dpp v122, v122, v122 quad_perm:[2,3,0,1] row_mask:0xf bank_mask:0xf bound_ctrl:1
	v_pk_fma_f32 v[166:167], v[166:167], v[66:67], v[118:119]
	ds_read_b128 v[46:49], v124 offset:9728
	v_add_f32_dpp v122, v122, v122 row_half_mirror row_mask:0xf bank_mask:0xf bound_ctrl:1
	v_pk_fma_f32 v[164:165], v[164:165], v[68:69], v[120:121]
	ds_read_b128 v[50:53], v124 offset:34304
	v_add_f32_dpp v122, v122, v122 row_mirror row_mask:0xf bank_mask:0xf bound_ctrl:1
	v_add_f32_dpp v210, v210, v210 row_mirror row_mask:0xf bank_mask:0xf bound_ctrl:1
	v_add_f32_dpp v210, v218, v218 row_mirror row_mask:0xf bank_mask:0xc bound_ctrl:1
	v_pk_fma_f32 v[166:167], v[70:71], v[122:123], v[166:167] op_sel_hi:[1,0,1]
	v_pk_fma_f32 v[164:165], v[72:73], v[122:123], v[164:165] op_sel_hi:[1,0,1]
	ds_read_b128 v[58:61], v124 offset:1536
	ds_read_b128 v[42:45], v124 offset:26112
	s_waitcnt lgkmcnt(11)
	v_pk_mul_f32 v[114:115], v[166:167], v[2:3]
	v_pk_mul_f32 v[116:117], v[166:167], v[78:79]
	v_pk_fma_f32 v[114:115], v[164:165], v[4:5], v[114:115]
	v_pk_fma_f32 v[116:117], v[164:165], v[80:81], v[116:117]
	v_add_f32_e32 v122, v114, v115
	s_waitcnt lgkmcnt(10)
; #define LAS __attribute__((address_space(3)))
; template <int CTRL> __device__ __forceinline__ float dpp_f(float x) { return __int_as_float(__builtin_amdgcn_update_dpp(0, __float_as_int(x), CTRL, 0xf, 0xf, false)); }
; __device__ __forceinline__ void phase_scan(const Params& p, LAS unsigned char* lds) {
;     ...
;                     for (int hb = 0; hb < 2; ++hb) {
;                         f32x4 vn[4];
; #pragma unroll
;                         for (int u = 0; u < 4; ++u) vn[u] = *(const LAS f32x4*)(sV + srow * 32 + ((16 * (hb + 1)) & 31) + 4 * u);
; #pragma unroll
;                         for (int u16 = 0; u16 < 16; ++u16) {
;                             const int s = 16 * hb + u16;
;                             const int sn = (s + 1) & 31;
;                             const f32x4 a_n = *(const LAS f32x4*)(sA + sn * 64), w_n = *(const LAS f32x4*)(sW + sn * 64), b_n = *(const LAS f32x4*)(sB + sn * 64);
;                             const f32x4 k_n = *(const LAS f32x4*)(sK + sn * 64), r_n = *(const LAS f32x4*)(sR + sn * 64);
;                             const float v = vq[u16 >> 2][u16 & 3];
;                             const f32x2 vv = {v, v};
;                             f32x2 pp = S01 * (f32x2){a_[0], a_[1]}; pp = S23 * (f32x2){a_[2], a_[3]} + pp;
;                             f32x2 yy = S01 * (f32x2){rp[0], rp[1]}; yy = S23 * (f32x2){rp[2], rp[3]} + yy;
;                             float sa = pp[0] + pp[1], y = yy[0] + yy[1];
;                             sa += dpp_f<0xB1>(sa); y += dpp_f<0xB1>(y);
;                             sa += dpp_f<0x4E>(sa); y += dpp_f<0x4E>(y);
;                             sa += dpp_f<0x141>(sa); y += dpp_f<0x141>(y);
;                             sa += dpp_f<0x140>(sa); y += dpp_f<0x140>(y);
;                             sY[((s - 1) & 31) * 16 + srow] = y;
;                             const f32x2 sv = {sa, sa};
;                             S01 = S01 * (f32x2){w_[0], w_[1]} + vv * (f32x2){k_[0], k_[1]};
;                             S23 = S23 * (f32x2){w_[2], w_[3]} + vv * (f32x2){k_[2], k_[3]};
;                             S01 = sv * (f32x2){b_[0], b_[1]} + S01;
;                             S23 = sv * (f32x2){b_[2], b_[3]} + S23;
;                             rp = r_;
;                             a_ = a_n; w_ = w_n; b_ = b_n; k_ = k_n; r_ = r_n;
;                         }
	v_pk_mul_f32 v[118:119], v[86:87], v[14:15] op_sel_hi:[0,1]
	v_add_f32_e32 v219, v116, v117
	v_add_f32_dpp v122, v122, v122 quad_perm:[1,0,3,2] row_mask:0xf bank_mask:0xf bound_ctrl:1
	v_pk_mul_f32 v[120:121], v[86:87], v[16:17] op_sel_hi:[0,1]
	ds_read_b128 v[74:77], v124 offset:18176
	v_add_f32_dpp v122, v122, v122 quad_perm:[2,3,0,1] row_mask:0xf bank_mask:0xf bound_ctrl:1
	v_pk_fma_f32 v[166:167], v[166:167], v[6:7], v[118:119]
	ds_read_b128 v[66:69], v124 offset:9984
	v_add_f32_dpp v122, v122, v122 row_half_mirror row_mask:0xf bank_mask:0xf bound_ctrl:1
	v_pk_fma_f32 v[164:165], v[164:165], v[8:9], v[120:121]
	ds_read_b128 v[70:73], v124 offset:34560
	v_add_f32_dpp v122, v122, v122 row_mirror row_mask:0xf bank_mask:0xf bound_ctrl:1
	v_add_f32_dpp v211, v211, v211 row_mirror row_mask:0xf bank_mask:0xf bound_ctrl:1
	v_add_f32_dpp v211, v219, v219 row_mirror row_mask:0xf bank_mask:0xc bound_ctrl:1
	v_pk_fma_f32 v[166:167], v[10:11], v[122:123], v[166:167] op_sel_hi:[1,0,1]
	v_pk_fma_f32 v[164:165], v[12:13], v[122:123], v[164:165] op_sel_hi:[1,0,1]
	ds_read_b128 v[78:81], v124 offset:1792
	ds_read_b128 v[62:65], v124 offset:26368
	s_waitcnt lgkmcnt(10)
	v_pk_mul_f32 v[114:115], v[166:167], v[22:23]
	v_pk_mul_f32 v[116:117], v[166:167], v[18:19]
	v_pk_fma_f32 v[114:115], v[164:165], v[24:25], v[114:115]
	v_pk_fma_f32 v[116:117], v[164:165], v[20:21], v[116:117]
	v_add_f32_e32 v122, v114, v115
	v_pk_mul_f32 v[118:119], v[86:87], v[34:35] op_sel:[1,0]
	v_add_f32_e32 v220, v116, v117
	v_add_f32_dpp v122, v122, v122 quad_perm:[1,0,3,2] row_mask:0xf bank_mask:0xf bound_ctrl:1
	v_pk_mul_f32 v[120:121], v[86:87], v[36:37] op_sel:[1,0]
	ds_read_b128 v[14:17], v124 offset:18432
	v_add_f32_dpp v122, v122, v122 quad_perm:[2,3,0,1] row_mask:0xf bank_mask:0xf bound_ctrl:1
	v_pk_fma_f32 v[166:167], v[166:167], v[26:27], v[118:119]
	ds_read_b128 v[6:9], v124 offset:10240
	v_add_f32_dpp v122, v122, v122 row_half_mirror row_mask:0xf bank_mask:0xf bound_ctrl:1
	v_pk_fma_f32 v[164:165], v[164:165], v[28:29], v[120:121]
	ds_read_b128 v[10:13], v124 offset:34816
	v_add_f32_dpp v122, v122, v122 row_mirror row_mask:0xf bank_mask:0xf bound_ctrl:1
	v_add_f32_dpp v204, v204, v204 row_half_mirror row_mask:0xf bank_mask:0xf bound_ctrl:1
	v_add_f32_dpp v205, v205, v205 row_half_mirror row_mask:0xf bank_mask:0xf bound_ctrl:1
	v_pk_fma_f32 v[166:167], v[30:31], v[122:123], v[166:167] op_sel_hi:[1,0,1]
	v_pk_fma_f32 v[164:165], v[32:33], v[122:123], v[164:165] op_sel_hi:[1,0,1]
	ds_read_b128 v[18:21], v124 offset:2048
	ds_read_b128 v[2:5], v124 offset:26624
	ds_read_b128 v[90:93], v125 offset:40992
	s_waitcnt lgkmcnt(11)
	v_pk_mul_f32 v[114:115], v[166:167], v[42:43]
	v_pk_mul_f32 v[116:117], v[166:167], v[38:39]
	v_pk_fma_f32 v[114:115], v[164:165], v[44:45], v[114:115]
	v_pk_fma_f32 v[116:117], v[164:165], v[40:41], v[116:117]
	v_add_f32_e32 v122, v114, v115
	v_pk_mul_f32 v[118:119], v[88:89], v[54:55] op_sel_hi:[0,1]
	v_add_f32_e32 v221, v116, v117
	v_add_f32_dpp v122, v122, v122 quad_perm:[1,0,3,2] row_mask:0xf bank_mask:0xf bound_ctrl:1
	v_pk_mul_f32 v[120:121], v[88:89], v[56:57] op_sel_hi:[0,1]
	ds_read_b128 v[34:37], v124 offset:18688
	v_add_f32_dpp v122, v122, v122 quad_perm:[2,3,0,1] row_mask:0xf bank_mask:0xf bound_ctrl:1
	v_pk_fma_f32 v[166:167], v[166:167], v[46:47], v[118:119]
	ds_read_b128 v[26:29], v124 offset:10496
	v_add_f32_dpp v122, v122, v122 row_half_mirror row_mask:0xf bank_mask:0xf bound_ctrl:1
	v_pk_fma_f32 v[164:165], v[164:165], v[48:49], v[120:121]
	ds_read_b128 v[30:33], v124 offset:35072
	v_add_f32_dpp v122, v122, v122 row_mirror row_mask:0xf bank_mask:0xf bound_ctrl:1
	v_add_f32_dpp v206, v206, v206 row_half_mirror row_mask:0xf bank_mask:0xf bound_ctrl:1
	v_add_f32_dpp v207, v207, v207 row_half_mirror row_mask:0xf bank_mask:0xf bound_ctrl:1
	v_pk_fma_f32 v[166:167], v[50:51], v[122:123], v[166:167] op_sel_hi:[1,0,1]
	v_pk_fma_f32 v[164:165], v[52:53], v[122:123], v[164:165] op_sel_hi:[1,0,1]
	ds_read_b128 v[38:41], v124 offset:2304
	ds_read_b128 v[22:25], v124 offset:26880
	s_waitcnt lgkmcnt(11)
	v_pk_mul_f32 v[114:115], v[166:167], v[62:63]
	v_pk_mul_f32 v[116:117], v[166:167], v[58:59]
	v_pk_fma_f32 v[114:115], v[164:165], v[64:65], v[114:115]
	v_pk_fma_f32 v[116:117], v[164:165], v[60:61], v[116:117]
	v_add_f32_e32 v122, v114, v115
	v_pk_mul_f32 v[118:119], v[88:89], v[74:75] op_sel:[1,0]
	v_add_f32_e32 v222, v116, v117
	v_add_f32_dpp v122, v122, v122 quad_perm:[1,0,3,2] row_mask:0xf bank_mask:0xf bound_ctrl:1
	v_pk_mul_f32 v[120:121], v[88:89], v[76:77] op_sel:[1,0]
	ds_read_b128 v[54:57], v124 offset:18944
	v_add_f32_dpp v122, v122, v122 quad_perm:[2,3,0,1] row_mask:0xf bank_mask:0xf bound_ctrl:1
	v_pk_fma_f32 v[166:167], v[166:167], v[66:67], v[118:119]
	ds_read_b128 v[46:49], v124 offset:10752
	v_add_f32_dpp v122, v122, v122 row_half_mirror row_mask:0xf bank_mask:0xf bound_ctrl:1
	v_pk_fma_f32 v[164:165], v[164:165], v[68:69], v[120:121]
	ds_read_b128 v[50:53], v124 offset:35328
	v_add_f32_dpp v122, v122, v122 row_mirror row_mask:0xf bank_mask:0xf bound_ctrl:1
	v_add_f32_dpp v204, v208, v208 row_half_mirror row_mask:0xf bank_mask:0xa bound_ctrl:1
	v_add_f32_dpp v205, v209, v209 row_half_mirror row_mask:0xf bank_mask:0xa bound_ctrl:1
	v_pk_fma_f32 v[166:167], v[70:71], v[122:123], v[166:167] op_sel_hi:[1,0,1]
	v_pk_fma_f32 v[164:165], v[72:73], v[122:123], v[164:165] op_sel_hi:[1,0,1]
	ds_read_b128 v[58:61], v124 offset:2560
	ds_read_b128 v[42:45], v124 offset:27136
	s_waitcnt lgkmcnt(11)
	v_pk_mul_f32 v[114:115], v[166:167], v[2:3]
	v_pk_mul_f32 v[116:117], v[166:167], v[78:79]
	v_pk_fma_f32 v[114:115], v[164:165], v[4:5], v[114:115]
	v_pk_fma_f32 v[116:117], v[164:165], v[80:81], v[116:117]
	v_add_f32_e32 v122, v114, v115
	s_waitcnt lgkmcnt(10)
; #define LAS __attribute__((address_space(3)))
; template <int CTRL> __device__ __forceinline__ float dpp_f(float x) { return __int_as_float(__builtin_amdgcn_update_dpp(0, __float_as_int(x), CTRL, 0xf, 0xf, false)); }
; __device__ __forceinline__ void phase_scan(const Params& p, LAS unsigned char* lds) {
;     ...
;                     for (int hb = 0; hb < 2; ++hb) {
;                         f32x4 vn[4];
; #pragma unroll
;                         for (int u = 0; u < 4; ++u) vn[u] = *(const LAS f32x4*)(sV + srow * 32 + ((16 * (hb + 1)) & 31) + 4 * u);
; #pragma unroll
;                         for (int u16 = 0; u16 < 16; ++u16) {
;                             const int s = 16 * hb + u16;
;                             const int sn = (s + 1) & 31;
;                             const f32x4 a_n = *(const LAS f32x4*)(sA + sn * 64), w_n = *(const LAS f32x4*)(sW + sn * 64), b_n = *(const LAS f32x4*)(sB + sn * 64);
;                             const f32x4 k_n = *(const LAS f32x4*)(sK + sn * 64), r_n = *(const LAS f32x4*)(sR + sn * 64);
;                             const float v = vq[u16 >> 2][u16 & 3];
;                             const f32x2 vv = {v, v};
;                             f32x2 pp = S01 * (f32x2){a_[0], a_[1]}; pp = S23 * (f32x2){a_[2], a_[3]} + pp;
;                             f32x2 yy = S01 * (f32x2){rp[0], rp[1]}; yy = S23 * (f32x2){rp[2], rp[3]} + yy;
;                             float sa = pp[0] + pp[1], y = yy[0] + yy[1];
;                             sa += dpp_f<0xB1>(sa); y += dpp_f<0xB1>(y);
;                             sa += dpp_f<0x4E>(sa); y += dpp_f<0x4E>(y);
;                             sa += dpp_f<0x141>(sa); y += dpp_f<0x141>(y);
;                             sa += dpp_f<0x140>(sa); y += dpp_f<0x140>(y);
;                             sY[((s - 1) & 31) * 16 + srow] = y;
;                             const f32x2 sv = {sa, sa};
;                             S01 = S01 * (f32x2){w_[0], w_[1]} + vv * (f32x2){k_[0], k_[1]};
;                             S23 = S23 * (f32x2){w_[2], w_[3]} + vv * (f32x2){k_[2], k_[3]};
;                             S01 = sv * (f32x2){b_[0], b_[1]} + S01;
;                             S23 = sv * (f32x2){b_[2], b_[3]} + S23;
;                             rp = r_;
;                             a_ = a_n; w_ = w_n; b_ = b_n; k_ = k_n; r_ = r_n;
;                         }
	v_pk_mul_f32 v[118:119], v[90:91], v[14:15] op_sel_hi:[0,1]
	v_add_f32_e32 v223, v116, v117
	v_add_f32_dpp v122, v122, v122 quad_perm:[1,0,3,2] row_mask:0xf bank_mask:0xf bound_ctrl:1
	v_pk_mul_f32 v[120:121], v[90:91], v[16:17] op_sel_hi:[0,1]
	ds_read_b128 v[74:77], v124 offset:19200
	v_add_f32_dpp v122, v122, v122 quad_perm:[2,3,0,1] row_mask:0xf bank_mask:0xf bound_ctrl:1
	v_pk_fma_f32 v[166:167], v[166:167], v[6:7], v[118:119]
	ds_read_b128 v[66:69], v124 offset:11008
	v_add_f32_dpp v122, v122, v122 row_half_mirror row_mask:0xf bank_mask:0xf bound_ctrl:1
	v_pk_fma_f32 v[164:165], v[164:165], v[8:9], v[120:121]
	ds_read_b128 v[70:73], v124 offset:35584
	v_add_f32_dpp v122, v122, v122 row_mirror row_mask:0xf bank_mask:0xf bound_ctrl:1
	v_add_f32_dpp v206, v210, v210 row_half_mirror row_mask:0xf bank_mask:0xa bound_ctrl:1
	v_add_f32_dpp v207, v211, v211 row_half_mirror row_mask:0xf bank_mask:0xa bound_ctrl:1
	v_pk_fma_f32 v[166:167], v[10:11], v[122:123], v[166:167] op_sel_hi:[1,0,1]
	v_pk_fma_f32 v[164:165], v[12:13], v[122:123], v[164:165] op_sel_hi:[1,0,1]
	ds_read_b128 v[78:81], v124 offset:2816
	ds_read_b128 v[62:65], v124 offset:27392
	s_waitcnt lgkmcnt(10)
	v_pk_mul_f32 v[114:115], v[166:167], v[22:23]
	v_pk_mul_f32 v[116:117], v[166:167], v[18:19]
	v_pk_fma_f32 v[114:115], v[164:165], v[24:25], v[114:115]
	v_pk_fma_f32 v[116:117], v[164:165], v[20:21], v[116:117]
	v_add_f32_e32 v122, v114, v115
	v_pk_mul_f32 v[118:119], v[90:91], v[34:35] op_sel:[1,0]
	v_add_f32_e32 v224, v116, v117
	v_add_f32_dpp v122, v122, v122 quad_perm:[1,0,3,2] row_mask:0xf bank_mask:0xf bound_ctrl:1
	v_pk_mul_f32 v[120:121], v[90:91], v[36:37] op_sel:[1,0]
	ds_read_b128 v[14:17], v124 offset:19456
	v_add_f32_dpp v122, v122, v122 quad_perm:[2,3,0,1] row_mask:0xf bank_mask:0xf bound_ctrl:1
	v_pk_fma_f32 v[166:167], v[166:167], v[26:27], v[118:119]
	ds_read_b128 v[6:9], v124 offset:11264
	v_add_f32_dpp v122, v122, v122 row_half_mirror row_mask:0xf bank_mask:0xf bound_ctrl:1
	v_pk_fma_f32 v[164:165], v[164:165], v[28:29], v[120:121]
	ds_read_b128 v[10:13], v124 offset:35840
	v_add_f32_dpp v122, v122, v122 row_mirror row_mask:0xf bank_mask:0xf bound_ctrl:1
	v_add_f32_dpp v204, v204, v204 quad_perm:[1,0,3,2] row_mask:0xf bank_mask:0xf bound_ctrl:1
	v_add_f32_dpp v205, v205, v205 quad_perm:[1,0,3,2] row_mask:0xf bank_mask:0xf bound_ctrl:1
	v_pk_fma_f32 v[166:167], v[30:31], v[122:123], v[166:167] op_sel_hi:[1,0,1]
	v_pk_fma_f32 v[164:165], v[32:33], v[122:123], v[164:165] op_sel_hi:[1,0,1]
	ds_read_b128 v[18:21], v124 offset:3072
	ds_read_b128 v[2:5], v124 offset:27648
	ds_read_b128 v[94:97], v125 offset:41008
	s_waitcnt lgkmcnt(11)
	v_pk_mul_f32 v[114:115], v[166:167], v[42:43]
	v_pk_mul_f32 v[116:117], v[166:167], v[38:39]
	v_pk_fma_f32 v[114:115], v[164:165], v[44:45], v[114:115]
	v_pk_fma_f32 v[116:117], v[164:165], v[40:41], v[116:117]
	v_add_f32_e32 v122, v114, v115
	v_pk_mul_f32 v[118:119], v[92:93], v[54:55] op_sel_hi:[0,1]
	v_add_f32_e32 v225, v116, v117
	v_add_f32_dpp v122, v122, v122 quad_perm:[1,0,3,2] row_mask:0xf bank_mask:0xf bound_ctrl:1
	v_pk_mul_f32 v[120:121], v[92:93], v[56:57] op_sel_hi:[0,1]
	ds_read_b128 v[34:37], v124 offset:19712
	v_add_f32_dpp v122, v122, v122 quad_perm:[2,3,0,1] row_mask:0xf bank_mask:0xf bound_ctrl:1
	v_pk_fma_f32 v[166:167], v[166:167], v[46:47], v[118:119]
	ds_read_b128 v[26:29], v124 offset:11520
	v_add_f32_dpp v122, v122, v122 row_half_mirror row_mask:0xf bank_mask:0xf bound_ctrl:1
	v_pk_fma_f32 v[164:165], v[164:165], v[48:49], v[120:121]
	ds_read_b128 v[30:33], v124 offset:36096
	v_add_f32_dpp v122, v122, v122 row_mirror row_mask:0xf bank_mask:0xf bound_ctrl:1
	v_add_f32_dpp v206, v206, v206 quad_perm:[1,0,3,2] row_mask:0xf bank_mask:0xf bound_ctrl:1
	v_add_f32_dpp v207, v207, v207 quad_perm:[1,0,3,2] row_mask:0xf bank_mask:0xf bound_ctrl:1
	v_pk_fma_f32 v[166:167], v[50:51], v[122:123], v[166:167] op_sel_hi:[1,0,1]
	v_pk_fma_f32 v[164:165], v[52:53], v[122:123], v[164:165] op_sel_hi:[1,0,1]
	ds_read_b128 v[38:41], v124 offset:3328
	ds_read_b128 v[22:25], v124 offset:27904
	s_waitcnt lgkmcnt(11)
	v_pk_mul_f32 v[114:115], v[166:167], v[62:63]
	v_pk_mul_f32 v[116:117], v[166:167], v[58:59]
	v_pk_fma_f32 v[114:115], v[164:165], v[64:65], v[114:115]
	v_pk_fma_f32 v[116:117], v[164:165], v[60:61], v[116:117]
	v_add_f32_e32 v122, v114, v115
	v_pk_mul_f32 v[118:119], v[92:93], v[74:75] op_sel:[1,0]
	v_add_f32_e32 v226, v116, v117
	v_add_f32_dpp v122, v122, v122 quad_perm:[1,0,3,2] row_mask:0xf bank_mask:0xf bound_ctrl:1
	v_pk_mul_f32 v[120:121], v[92:93], v[76:77] op_sel:[1,0]
	ds_read_b128 v[54:57], v124 offset:19968
	v_add_f32_dpp v122, v122, v122 quad_perm:[2,3,0,1] row_mask:0xf bank_mask:0xf bound_ctrl:1
	v_pk_fma_f32 v[166:167], v[166:167], v[66:67], v[118:119]
	ds_read_b128 v[46:49], v124 offset:11776
	v_add_f32_dpp v122, v122, v122 row_half_mirror row_mask:0xf bank_mask:0xf bound_ctrl:1
	v_pk_fma_f32 v[164:165], v[164:165], v[68:69], v[120:121]
	ds_read_b128 v[50:53], v124 offset:36352
	v_add_f32_dpp v122, v122, v122 row_mirror row_mask:0xf bank_mask:0xf bound_ctrl:1
	v_add_f32_dpp v204, v204, v204 quad_perm:[2,3,0,1] row_mask:0xf bank_mask:0xf bound_ctrl:1
	v_add_f32_dpp v205, v205, v205 quad_perm:[2,3,0,1] row_mask:0xf bank_mask:0xf bound_ctrl:1
	v_pk_fma_f32 v[166:167], v[70:71], v[122:123], v[166:167] op_sel_hi:[1,0,1]
	v_pk_fma_f32 v[164:165], v[72:73], v[122:123], v[164:165] op_sel_hi:[1,0,1]
	ds_read_b128 v[58:61], v124 offset:3584
	ds_read_b128 v[42:45], v124 offset:28160
	s_waitcnt lgkmcnt(11)
; #define LAS __attribute__((address_space(3)))
; template <int CTRL> __device__ __forceinline__ float dpp_f(float x) { return __int_as_float(__builtin_amdgcn_update_dpp(0, __float_as_int(x), CTRL, 0xf, 0xf, false)); }
; __device__ __forceinline__ void phase_scan(const Params& p, LAS unsigned char* lds) {
;     ...
;                     for (int hb = 0; hb < 2; ++hb) {
;                         f32x4 vn[4];
; #pragma unroll
;                         for (int u = 0; u < 4; ++u) vn[u] = *(const LAS f32x4*)(sV + srow * 32 + ((16 * (hb + 1)) & 31) + 4 * u);
; #pragma unroll
;                         for (int u16 = 0; u16 < 16; ++u16) {
;                             const int s = 16 * hb + u16;
;                             const int sn = (s + 1) & 31;
;                             const f32x4 a_n = *(const LAS f32x4*)(sA + sn * 64), w_n = *(const LAS f32x4*)(sW + sn * 64), b_n = *(const LAS f32x4*)(sB + sn * 64);
;                             const f32x4 k_n = *(const LAS f32x4*)(sK + sn * 64), r_n = *(const LAS f32x4*)(sR + sn * 64);
;                             const float v = vq[u16 >> 2][u16 & 3];
;                             const f32x2 vv = {v, v};
;                             f32x2 pp = S01 * (f32x2){a_[0], a_[1]}; pp = S23 * (f32x2){a_[2], a_[3]} + pp;
;                             f32x2 yy = S01 * (f32x2){rp[0], rp[1]}; yy = S23 * (f32x2){rp[2], rp[3]} + yy;
;                             float sa = pp[0] + pp[1], y = yy[0] + yy[1];
;                             sa += dpp_f<0xB1>(sa); y += dpp_f<0xB1>(y);
;                             sa += dpp_f<0x4E>(sa); y += dpp_f<0x4E>(y);
;                             sa += dpp_f<0x141>(sa); y += dpp_f<0x141>(y);
;                             sa += dpp_f<0x140>(sa); y += dpp_f<0x140>(y);
;                             sY[((s - 1) & 31) * 16 + srow] = y;
;                             const f32x2 sv = {sa, sa};
;                             S01 = S01 * (f32x2){w_[0], w_[1]} + vv * (f32x2){k_[0], k_[1]};
;                             S23 = S23 * (f32x2){w_[2], w_[3]} + vv * (f32x2){k_[2], k_[3]};
;                             S01 = sv * (f32x2){b_[0], b_[1]} + S01;
;                             S23 = sv * (f32x2){b_[2], b_[3]} + S23;
;                             rp = r_;
;                             a_ = a_n; w_ = w_n; b_ = b_n; k_ = k_n; r_ = r_n;
;                         }
	v_pk_mul_f32 v[114:115], v[166:167], v[2:3]
	v_pk_mul_f32 v[116:117], v[166:167], v[78:79]
	v_pk_fma_f32 v[114:115], v[164:165], v[4:5], v[114:115]
	v_pk_fma_f32 v[116:117], v[164:165], v[80:81], v[116:117]
	v_add_f32_e32 v122, v114, v115
	s_waitcnt lgkmcnt(10)
	v_pk_mul_f32 v[118:119], v[94:95], v[14:15] op_sel_hi:[0,1]
	v_add_f32_e32 v227, v116, v117
	v_add_f32_dpp v122, v122, v122 quad_perm:[1,0,3,2] row_mask:0xf bank_mask:0xf bound_ctrl:1
	v_pk_mul_f32 v[120:121], v[94:95], v[16:17] op_sel_hi:[0,1]
	ds_read_b128 v[74:77], v124 offset:20224
	v_add_f32_dpp v122, v122, v122 quad_perm:[2,3,0,1] row_mask:0xf bank_mask:0xf bound_ctrl:1
	v_pk_fma_f32 v[166:167], v[166:167], v[6:7], v[118:119]
	ds_read_b128 v[66:69], v124 offset:12032
	v_add_f32_dpp v122, v122, v122 row_half_mirror row_mask:0xf bank_mask:0xf bound_ctrl:1
	v_pk_fma_f32 v[164:165], v[164:165], v[8:9], v[120:121]
	ds_read_b128 v[70:73], v124 offset:36608
	v_add_f32_dpp v122, v122, v122 row_mirror row_mask:0xf bank_mask:0xf bound_ctrl:1
	v_add_f32_dpp v206, v206, v206 quad_perm:[2,3,0,1] row_mask:0xf bank_mask:0xf bound_ctrl:1
	v_add_f32_dpp v207, v207, v207 quad_perm:[2,3,0,1] row_mask:0xf bank_mask:0xf bound_ctrl:1
	v_pk_fma_f32 v[166:167], v[10:11], v[122:123], v[166:167] op_sel_hi:[1,0,1]
	v_pk_fma_f32 v[164:165], v[12:13], v[122:123], v[164:165] op_sel_hi:[1,0,1]
	ds_read_b128 v[78:81], v124 offset:3840
	ds_read_b128 v[62:65], v124 offset:28416
	s_waitcnt lgkmcnt(10)
	v_pk_mul_f32 v[114:115], v[166:167], v[22:23]
	v_pk_mul_f32 v[116:117], v[166:167], v[18:19]
	v_pk_fma_f32 v[114:115], v[164:165], v[24:25], v[114:115]
	v_pk_fma_f32 v[116:117], v[164:165], v[20:21], v[116:117]
	v_add_f32_e32 v122, v114, v115
	v_pk_mul_f32 v[118:119], v[94:95], v[34:35] op_sel:[1,0]
	v_add_f32_e32 v228, v116, v117
	v_add_f32_dpp v122, v122, v122 quad_perm:[1,0,3,2] row_mask:0xf bank_mask:0xf bound_ctrl:1
	v_pk_mul_f32 v[120:121], v[94:95], v[36:37] op_sel:[1,0]
	ds_read_b128 v[14:17], v124 offset:20480
	v_add_f32_dpp v122, v122, v122 quad_perm:[2,3,0,1] row_mask:0xf bank_mask:0xf bound_ctrl:1
	v_pk_fma_f32 v[166:167], v[166:167], v[26:27], v[118:119]
	ds_read_b128 v[6:9], v124 offset:12288
	v_add_f32_dpp v122, v122, v122 row_half_mirror row_mask:0xf bank_mask:0xf bound_ctrl:1
	v_pk_fma_f32 v[164:165], v[164:165], v[28:29], v[120:121]
	ds_read_b128 v[10:13], v124 offset:36864
	v_add_f32_dpp v122, v122, v122 row_mirror row_mask:0xf bank_mask:0xf bound_ctrl:1
	v_cndmask_b32_e64 v202, v204, v205, s[34:35]
	v_cndmask_b32_e64 v202, v202, v206, s[56:57]
	v_pk_fma_f32 v[166:167], v[30:31], v[122:123], v[166:167] op_sel_hi:[1,0,1]
	v_pk_fma_f32 v[164:165], v[32:33], v[122:123], v[164:165] op_sel_hi:[1,0,1]
	ds_read_b128 v[18:21], v124 offset:4096
	ds_read_b128 v[2:5], v124 offset:28672
	ds_read_b128 v[98:101], v125 offset:41024
	s_waitcnt lgkmcnt(11)
	v_pk_mul_f32 v[114:115], v[166:167], v[42:43]
	v_pk_mul_f32 v[116:117], v[166:167], v[38:39]
	v_pk_fma_f32 v[114:115], v[164:165], v[44:45], v[114:115]
	v_pk_fma_f32 v[116:117], v[164:165], v[40:41], v[116:117]
	v_add_f32_e32 v122, v114, v115
	v_pk_mul_f32 v[118:119], v[96:97], v[54:55] op_sel_hi:[0,1]
	v_add_f32_e32 v229, v116, v117
	v_add_f32_dpp v122, v122, v122 quad_perm:[1,0,3,2] row_mask:0xf bank_mask:0xf bound_ctrl:1
	v_pk_mul_f32 v[120:121], v[96:97], v[56:57] op_sel_hi:[0,1]
	ds_read_b128 v[34:37], v124 offset:20736
	v_add_f32_dpp v122, v122, v122 quad_perm:[2,3,0,1] row_mask:0xf bank_mask:0xf bound_ctrl:1
	v_pk_fma_f32 v[166:167], v[166:167], v[46:47], v[118:119]
	ds_read_b128 v[26:29], v124 offset:12544
	v_add_f32_dpp v122, v122, v122 row_half_mirror row_mask:0xf bank_mask:0xf bound_ctrl:1
	v_pk_fma_f32 v[164:165], v[164:165], v[48:49], v[120:121]
	ds_read_b128 v[30:33], v124 offset:37120
	v_add_f32_dpp v122, v122, v122 row_mirror row_mask:0xf bank_mask:0xf bound_ctrl:1
	v_cndmask_b32_e64 v202, v202, v207, s[98:99]
	v_cvt_f16_f32_e32 v203, v202
	v_pk_fma_f32 v[166:167], v[50:51], v[122:123], v[166:167] op_sel_hi:[1,0,1]
	v_pk_fma_f32 v[164:165], v[52:53], v[122:123], v[164:165] op_sel_hi:[1,0,1]
	ds_read_b128 v[38:41], v124 offset:4352
	ds_read_b128 v[22:25], v124 offset:28928
	s_waitcnt lgkmcnt(11)
	v_pk_mul_f32 v[114:115], v[166:167], v[62:63]
	v_pk_mul_f32 v[116:117], v[166:167], v[58:59]
	v_pk_fma_f32 v[114:115], v[164:165], v[64:65], v[114:115]
	v_pk_fma_f32 v[116:117], v[164:165], v[60:61], v[116:117]
	v_add_f32_e32 v122, v114, v115
	v_pk_mul_f32 v[118:119], v[96:97], v[74:75] op_sel:[1,0]
	v_add_f32_e32 v230, v116, v117
	v_add_f32_dpp v122, v122, v122 quad_perm:[1,0,3,2] row_mask:0xf bank_mask:0xf bound_ctrl:1
	v_pk_mul_f32 v[120:121], v[96:97], v[76:77] op_sel:[1,0]
	ds_read_b128 v[54:57], v124 offset:20992
	v_add_f32_dpp v122, v122, v122 quad_perm:[2,3,0,1] row_mask:0xf bank_mask:0xf bound_ctrl:1
	v_pk_fma_f32 v[166:167], v[166:167], v[66:67], v[118:119]
	ds_read_b128 v[46:49], v124 offset:12800
	v_add_f32_dpp v122, v122, v122 row_half_mirror row_mask:0xf bank_mask:0xf bound_ctrl:1
	v_pk_fma_f32 v[164:165], v[164:165], v[68:69], v[120:121]
	ds_read_b128 v[50:53], v124 offset:37376
	v_add_f32_dpp v122, v122, v122 row_mirror row_mask:0xf bank_mask:0xf bound_ctrl:1
	s_mov_b64 exec, s[14:15]
	global_store_short v[128:129], v203, off
	s_mov_b64 exec, -1
	v_lshl_add_u64 v[128:129], v[128:129], 0, s[100:101]
	v_pk_fma_f32 v[166:167], v[70:71], v[122:123], v[166:167] op_sel_hi:[1,0,1]
	v_pk_fma_f32 v[164:165], v[72:73], v[122:123], v[164:165] op_sel_hi:[1,0,1]
	ds_read_b128 v[58:61], v124 offset:4608
	ds_read_b128 v[42:45], v124 offset:29184
	s_waitcnt lgkmcnt(11)
; #define LAS __attribute__((address_space(3)))
; template <int CTRL> __device__ __forceinline__ float dpp_f(float x) { return __int_as_float(__builtin_amdgcn_update_dpp(0, __float_as_int(x), CTRL, 0xf, 0xf, false)); }
; __device__ __forceinline__ void phase_scan(const Params& p, LAS unsigned char* lds) {
;     ...
;                     for (int hb = 0; hb < 2; ++hb) {
;                         f32x4 vn[4];
; #pragma unroll
;                         for (int u = 0; u < 4; ++u) vn[u] = *(const LAS f32x4*)(sV + srow * 32 + ((16 * (hb + 1)) & 31) + 4 * u);
; #pragma unroll
;                         for (int u16 = 0; u16 < 16; ++u16) {
;                             const int s = 16 * hb + u16;
;                             const int sn = (s + 1) & 31;
;                             const f32x4 a_n = *(const LAS f32x4*)(sA + sn * 64), w_n = *(const LAS f32x4*)(sW + sn * 64), b_n = *(const LAS f32x4*)(sB + sn * 64);
;                             const f32x4 k_n = *(const LAS f32x4*)(sK + sn * 64), r_n = *(const LAS f32x4*)(sR + sn * 64);
;                             const float v = vq[u16 >> 2][u16 & 3];
;                             const f32x2 vv = {v, v};
;                             f32x2 pp = S01 * (f32x2){a_[0], a_[1]}; pp = S23 * (f32x2){a_[2], a_[3]} + pp;
;                             f32x2 yy = S01 * (f32x2){rp[0], rp[1]}; yy = S23 * (f32x2){rp[2], rp[3]} + yy;
;                             float sa = pp[0] + pp[1], y = yy[0] + yy[1];
;                             sa += dpp_f<0xB1>(sa); y += dpp_f<0xB1>(y);
;                             sa += dpp_f<0x4E>(sa); y += dpp_f<0x4E>(y);
;                             sa += dpp_f<0x141>(sa); y += dpp_f<0x141>(y);
;                             sa += dpp_f<0x140>(sa); y += dpp_f<0x140>(y);
;                             sY[((s - 1) & 31) * 16 + srow] = y;
;                             const f32x2 sv = {sa, sa};
;                             S01 = S01 * (f32x2){w_[0], w_[1]} + vv * (f32x2){k_[0], k_[1]};
;                             S23 = S23 * (f32x2){w_[2], w_[3]} + vv * (f32x2){k_[2], k_[3]};
;                             S01 = sv * (f32x2){b_[0], b_[1]} + S01;
;                             S23 = sv * (f32x2){b_[2], b_[3]} + S23;
;                             rp = r_;
;                             a_ = a_n; w_ = w_n; b_ = b_n; k_ = k_n; r_ = r_n;
;                         }
	v_pk_mul_f32 v[114:115], v[166:167], v[2:3]
	v_pk_mul_f32 v[116:117], v[166:167], v[78:79]
	v_pk_fma_f32 v[114:115], v[164:165], v[4:5], v[114:115]
	v_pk_fma_f32 v[116:117], v[164:165], v[80:81], v[116:117]
	v_add_f32_e32 v122, v114, v115
	s_waitcnt lgkmcnt(10)
	v_pk_mul_f32 v[118:119], v[98:99], v[14:15] op_sel_hi:[0,1]
	v_add_f32_e32 v231, v116, v117
	v_add_f32_dpp v122, v122, v122 quad_perm:[1,0,3,2] row_mask:0xf bank_mask:0xf bound_ctrl:1
	v_pk_mul_f32 v[120:121], v[98:99], v[16:17] op_sel_hi:[0,1]
	ds_read_b128 v[74:77], v124 offset:21248
	v_add_f32_dpp v122, v122, v122 quad_perm:[2,3,0,1] row_mask:0xf bank_mask:0xf bound_ctrl:1
	v_pk_fma_f32 v[166:167], v[166:167], v[6:7], v[118:119]
	ds_read_b128 v[66:69], v124 offset:13056
	v_add_f32_dpp v122, v122, v122 row_half_mirror row_mask:0xf bank_mask:0xf bound_ctrl:1
	v_pk_fma_f32 v[164:165], v[164:165], v[8:9], v[120:121]
	ds_read_b128 v[70:73], v124 offset:37632
	v_add_f32_dpp v122, v122, v122 row_mirror row_mask:0xf bank_mask:0xf bound_ctrl:1
	v_add_f32_dpp v220, v220, v220 row_mirror row_mask:0xf bank_mask:0xf bound_ctrl:1
	v_add_f32_dpp v220, v228, v228 row_mirror row_mask:0xf bank_mask:0xc bound_ctrl:1
	v_pk_fma_f32 v[166:167], v[10:11], v[122:123], v[166:167] op_sel_hi:[1,0,1]
	v_pk_fma_f32 v[164:165], v[12:13], v[122:123], v[164:165] op_sel_hi:[1,0,1]
	ds_read_b128 v[78:81], v124 offset:4864
	ds_read_b128 v[62:65], v124 offset:29440
	s_waitcnt lgkmcnt(10)
	v_pk_mul_f32 v[114:115], v[166:167], v[22:23]
	v_pk_mul_f32 v[116:117], v[166:167], v[18:19]
	v_pk_fma_f32 v[114:115], v[164:165], v[24:25], v[114:115]
	v_pk_fma_f32 v[116:117], v[164:165], v[20:21], v[116:117]
	v_add_f32_e32 v122, v114, v115
	v_pk_mul_f32 v[118:119], v[98:99], v[34:35] op_sel:[1,0]
	v_add_f32_e32 v232, v116, v117
	v_add_f32_dpp v122, v122, v122 quad_perm:[1,0,3,2] row_mask:0xf bank_mask:0xf bound_ctrl:1
	v_pk_mul_f32 v[120:121], v[98:99], v[36:37] op_sel:[1,0]
	ds_read_b128 v[14:17], v124 offset:21504
	v_add_f32_dpp v122, v122, v122 quad_perm:[2,3,0,1] row_mask:0xf bank_mask:0xf bound_ctrl:1
	v_pk_fma_f32 v[166:167], v[166:167], v[26:27], v[118:119]
	ds_read_b128 v[6:9], v124 offset:13312
	v_add_f32_dpp v122, v122, v122 row_half_mirror row_mask:0xf bank_mask:0xf bound_ctrl:1
	v_pk_fma_f32 v[164:165], v[164:165], v[28:29], v[120:121]
	ds_read_b128 v[10:13], v124 offset:37888
	v_add_f32_dpp v122, v122, v122 row_mirror row_mask:0xf bank_mask:0xf bound_ctrl:1
	v_add_f32_dpp v221, v221, v221 row_mirror row_mask:0xf bank_mask:0xf bound_ctrl:1
	v_add_f32_dpp v221, v229, v229 row_mirror row_mask:0xf bank_mask:0xc bound_ctrl:1
	v_pk_fma_f32 v[166:167], v[30:31], v[122:123], v[166:167] op_sel_hi:[1,0,1]
	v_pk_fma_f32 v[164:165], v[32:33], v[122:123], v[164:165] op_sel_hi:[1,0,1]
	ds_read_b128 v[18:21], v124 offset:5120
	ds_read_b128 v[2:5], v124 offset:29696
	ds_read_b128 v[102:105], v125 offset:41040
	s_waitcnt lgkmcnt(11)
	v_pk_mul_f32 v[114:115], v[166:167], v[42:43]
	v_pk_mul_f32 v[116:117], v[166:167], v[38:39]
	v_pk_fma_f32 v[114:115], v[164:165], v[44:45], v[114:115]
	v_pk_fma_f32 v[116:117], v[164:165], v[40:41], v[116:117]
	v_add_f32_e32 v122, v114, v115
	v_pk_mul_f32 v[118:119], v[100:101], v[54:55] op_sel_hi:[0,1]
	v_add_f32_e32 v233, v116, v117
	v_add_f32_dpp v122, v122, v122 quad_perm:[1,0,3,2] row_mask:0xf bank_mask:0xf bound_ctrl:1
	v_pk_mul_f32 v[120:121], v[100:101], v[56:57] op_sel_hi:[0,1]
	ds_read_b128 v[34:37], v124 offset:21760
	v_add_f32_dpp v122, v122, v122 quad_perm:[2,3,0,1] row_mask:0xf bank_mask:0xf bound_ctrl:1
	v_pk_fma_f32 v[166:167], v[166:167], v[46:47], v[118:119]
	ds_read_b128 v[26:29], v124 offset:13568
	v_add_f32_dpp v122, v122, v122 row_half_mirror row_mask:0xf bank_mask:0xf bound_ctrl:1
	v_pk_fma_f32 v[164:165], v[164:165], v[48:49], v[120:121]
	ds_read_b128 v[30:33], v124 offset:38144
	v_add_f32_dpp v122, v122, v122 row_mirror row_mask:0xf bank_mask:0xf bound_ctrl:1
	v_add_f32_dpp v222, v222, v222 row_mirror row_mask:0xf bank_mask:0xf bound_ctrl:1
	v_add_f32_dpp v222, v230, v230 row_mirror row_mask:0xf bank_mask:0xc bound_ctrl:1
	v_pk_fma_f32 v[166:167], v[50:51], v[122:123], v[166:167] op_sel_hi:[1,0,1]
	v_pk_fma_f32 v[164:165], v[52:53], v[122:123], v[164:165] op_sel_hi:[1,0,1]
	ds_read_b128 v[38:41], v124 offset:5376
	ds_read_b128 v[22:25], v124 offset:29952
	s_waitcnt lgkmcnt(11)
	v_pk_mul_f32 v[114:115], v[166:167], v[62:63]
	v_pk_mul_f32 v[116:117], v[166:167], v[58:59]
	v_pk_fma_f32 v[114:115], v[164:165], v[64:65], v[114:115]
	v_pk_fma_f32 v[116:117], v[164:165], v[60:61], v[116:117]
	v_add_f32_e32 v122, v114, v115
	v_pk_mul_f32 v[118:119], v[100:101], v[74:75] op_sel:[1,0]
	v_add_f32_e32 v234, v116, v117
	v_add_f32_dpp v122, v122, v122 quad_perm:[1,0,3,2] row_mask:0xf bank_mask:0xf bound_ctrl:1
	v_pk_mul_f32 v[120:121], v[100:101], v[76:77] op_sel:[1,0]
	ds_read_b128 v[54:57], v124 offset:22016
	v_add_f32_dpp v122, v122, v122 quad_perm:[2,3,0,1] row_mask:0xf bank_mask:0xf bound_ctrl:1
	v_pk_fma_f32 v[166:167], v[166:167], v[66:67], v[118:119]
	ds_read_b128 v[46:49], v124 offset:13824
	v_add_f32_dpp v122, v122, v122 row_half_mirror row_mask:0xf bank_mask:0xf bound_ctrl:1
	v_pk_fma_f32 v[164:165], v[164:165], v[68:69], v[120:121]
	ds_read_b128 v[50:53], v124 offset:38400
	v_add_f32_dpp v122, v122, v122 row_mirror row_mask:0xf bank_mask:0xf bound_ctrl:1
	v_add_f32_dpp v223, v223, v223 row_mirror row_mask:0xf bank_mask:0xf bound_ctrl:1
	v_add_f32_dpp v223, v231, v231 row_mirror row_mask:0xf bank_mask:0xc bound_ctrl:1
	v_pk_fma_f32 v[166:167], v[70:71], v[122:123], v[166:167] op_sel_hi:[1,0,1]
	v_pk_fma_f32 v[164:165], v[72:73], v[122:123], v[164:165] op_sel_hi:[1,0,1]
	ds_read_b128 v[58:61], v124 offset:5632
	ds_read_b128 v[42:45], v124 offset:30208
	s_waitcnt lgkmcnt(11)
; #define LAS __attribute__((address_space(3)))
; template <int CTRL> __device__ __forceinline__ float dpp_f(float x) { return __int_as_float(__builtin_amdgcn_update_dpp(0, __float_as_int(x), CTRL, 0xf, 0xf, false)); }
; __device__ __forceinline__ void phase_scan(const Params& p, LAS unsigned char* lds) {
;     ...
;                     for (int hb = 0; hb < 2; ++hb) {
;                         f32x4 vn[4];
; #pragma unroll
;                         for (int u = 0; u < 4; ++u) vn[u] = *(const LAS f32x4*)(sV + srow * 32 + ((16 * (hb + 1)) & 31) + 4 * u);
; #pragma unroll
;                         for (int u16 = 0; u16 < 16; ++u16) {
;                             const int s = 16 * hb + u16;
;                             const int sn = (s + 1) & 31;
;                             const f32x4 a_n = *(const LAS f32x4*)(sA + sn * 64), w_n = *(const LAS f32x4*)(sW + sn * 64), b_n = *(const LAS f32x4*)(sB + sn * 64);
;                             const f32x4 k_n = *(const LAS f32x4*)(sK + sn * 64), r_n = *(const LAS f32x4*)(sR + sn * 64);
;                             const float v = vq[u16 >> 2][u16 & 3];
;                             const f32x2 vv = {v, v};
;                             f32x2 pp = S01 * (f32x2){a_[0], a_[1]}; pp = S23 * (f32x2){a_[2], a_[3]} + pp;
;                             f32x2 yy = S01 * (f32x2){rp[0], rp[1]}; yy = S23 * (f32x2){rp[2], rp[3]} + yy;
;                             float sa = pp[0] + pp[1], y = yy[0] + yy[1];
;                             sa += dpp_f<0xB1>(sa); y += dpp_f<0xB1>(y);
;                             sa += dpp_f<0x4E>(sa); y += dpp_f<0x4E>(y);
;                             sa += dpp_f<0x141>(sa); y += dpp_f<0x141>(y);
;                             sa += dpp_f<0x140>(sa); y += dpp_f<0x140>(y);
;                             sY[((s - 1) & 31) * 16 + srow] = y;
;                             const f32x2 sv = {sa, sa};
;                             S01 = S01 * (f32x2){w_[0], w_[1]} + vv * (f32x2){k_[0], k_[1]};
;                             S23 = S23 * (f32x2){w_[2], w_[3]} + vv * (f32x2){k_[2], k_[3]};
;                             S01 = sv * (f32x2){b_[0], b_[1]} + S01;
;                             S23 = sv * (f32x2){b_[2], b_[3]} + S23;
;                             rp = r_;
;                             a_ = a_n; w_ = w_n; b_ = b_n; k_ = k_n; r_ = r_n;
;                         }
	v_pk_mul_f32 v[114:115], v[166:167], v[2:3]
	v_pk_mul_f32 v[116:117], v[166:167], v[78:79]
	v_pk_fma_f32 v[114:115], v[164:165], v[4:5], v[114:115]
	v_pk_fma_f32 v[116:117], v[164:165], v[80:81], v[116:117]
	v_add_f32_e32 v122, v114, v115
	s_waitcnt lgkmcnt(10)
	v_pk_mul_f32 v[118:119], v[102:103], v[14:15] op_sel_hi:[0,1]
	v_add_f32_e32 v235, v116, v117
	v_add_f32_dpp v122, v122, v122 quad_perm:[1,0,3,2] row_mask:0xf bank_mask:0xf bound_ctrl:1
	v_pk_mul_f32 v[120:121], v[102:103], v[16:17] op_sel_hi:[0,1]
	ds_read_b128 v[74:77], v124 offset:22272
	v_add_f32_dpp v122, v122, v122 quad_perm:[2,3,0,1] row_mask:0xf bank_mask:0xf bound_ctrl:1
	v_pk_fma_f32 v[166:167], v[166:167], v[6:7], v[118:119]
	ds_read_b128 v[66:69], v124 offset:14080
	v_add_f32_dpp v122, v122, v122 row_half_mirror row_mask:0xf bank_mask:0xf bound_ctrl:1
	v_pk_fma_f32 v[164:165], v[164:165], v[8:9], v[120:121]
	ds_read_b128 v[70:73], v124 offset:38656
	v_add_f32_dpp v122, v122, v122 row_mirror row_mask:0xf bank_mask:0xf bound_ctrl:1
	v_add_f32_dpp v224, v224, v224 row_mirror row_mask:0xf bank_mask:0xf bound_ctrl:1
	v_add_f32_dpp v224, v232, v232 row_mirror row_mask:0xf bank_mask:0xc bound_ctrl:1
	v_pk_fma_f32 v[166:167], v[10:11], v[122:123], v[166:167] op_sel_hi:[1,0,1]
	v_pk_fma_f32 v[164:165], v[12:13], v[122:123], v[164:165] op_sel_hi:[1,0,1]
	ds_read_b128 v[78:81], v124 offset:5888
	ds_read_b128 v[62:65], v124 offset:30464
	s_waitcnt lgkmcnt(10)
	v_pk_mul_f32 v[114:115], v[166:167], v[22:23]
	v_pk_mul_f32 v[116:117], v[166:167], v[18:19]
	v_pk_fma_f32 v[114:115], v[164:165], v[24:25], v[114:115]
	v_pk_fma_f32 v[116:117], v[164:165], v[20:21], v[116:117]
	v_add_f32_e32 v122, v114, v115
	v_pk_mul_f32 v[118:119], v[102:103], v[34:35] op_sel:[1,0]
	v_add_f32_e32 v204, v116, v117
	v_add_f32_dpp v122, v122, v122 quad_perm:[1,0,3,2] row_mask:0xf bank_mask:0xf bound_ctrl:1
	v_pk_mul_f32 v[120:121], v[102:103], v[36:37] op_sel:[1,0]
	ds_read_b128 v[14:17], v124 offset:22528
	v_add_f32_dpp v122, v122, v122 quad_perm:[2,3,0,1] row_mask:0xf bank_mask:0xf bound_ctrl:1
	v_pk_fma_f32 v[166:167], v[166:167], v[26:27], v[118:119]
	ds_read_b128 v[6:9], v124 offset:14336
	v_add_f32_dpp v122, v122, v122 row_half_mirror row_mask:0xf bank_mask:0xf bound_ctrl:1
	v_pk_fma_f32 v[164:165], v[164:165], v[28:29], v[120:121]
	ds_read_b128 v[10:13], v124 offset:38912
	v_add_f32_dpp v122, v122, v122 row_mirror row_mask:0xf bank_mask:0xf bound_ctrl:1
	v_add_f32_dpp v225, v225, v225 row_mirror row_mask:0xf bank_mask:0xf bound_ctrl:1
	v_add_f32_dpp v225, v233, v233 row_mirror row_mask:0xf bank_mask:0xc bound_ctrl:1
	v_pk_fma_f32 v[166:167], v[30:31], v[122:123], v[166:167] op_sel_hi:[1,0,1]
	v_pk_fma_f32 v[164:165], v[32:33], v[122:123], v[164:165] op_sel_hi:[1,0,1]
	ds_read_b128 v[18:21], v124 offset:6144
	ds_read_b128 v[2:5], v124 offset:30720
	ds_read_b128 v[106:109], v125 offset:41056
	s_waitcnt lgkmcnt(11)
	v_pk_mul_f32 v[114:115], v[166:167], v[42:43]
	v_pk_mul_f32 v[116:117], v[166:167], v[38:39]
	v_pk_fma_f32 v[114:115], v[164:165], v[44:45], v[114:115]
	v_pk_fma_f32 v[116:117], v[164:165], v[40:41], v[116:117]
	v_add_f32_e32 v122, v114, v115
	v_pk_mul_f32 v[118:119], v[104:105], v[54:55] op_sel_hi:[0,1]
	v_add_f32_e32 v205, v116, v117
	v_add_f32_dpp v122, v122, v122 quad_perm:[1,0,3,2] row_mask:0xf bank_mask:0xf bound_ctrl:1
	v_pk_mul_f32 v[120:121], v[104:105], v[56:57] op_sel_hi:[0,1]
	ds_read_b128 v[34:37], v124 offset:22784
	v_add_f32_dpp v122, v122, v122 quad_perm:[2,3,0,1] row_mask:0xf bank_mask:0xf bound_ctrl:1
	v_pk_fma_f32 v[166:167], v[166:167], v[46:47], v[118:119]
	ds_read_b128 v[26:29], v124 offset:14592
	v_add_f32_dpp v122, v122, v122 row_half_mirror row_mask:0xf bank_mask:0xf bound_ctrl:1
	v_pk_fma_f32 v[164:165], v[164:165], v[48:49], v[120:121]
	ds_read_b128 v[30:33], v124 offset:39168
	v_add_f32_dpp v122, v122, v122 row_mirror row_mask:0xf bank_mask:0xf bound_ctrl:1
	v_add_f32_dpp v226, v226, v226 row_mirror row_mask:0xf bank_mask:0xf bound_ctrl:1
	v_add_f32_dpp v226, v234, v234 row_mirror row_mask:0xf bank_mask:0xc bound_ctrl:1
	v_pk_fma_f32 v[166:167], v[50:51], v[122:123], v[166:167] op_sel_hi:[1,0,1]
	v_pk_fma_f32 v[164:165], v[52:53], v[122:123], v[164:165] op_sel_hi:[1,0,1]
	ds_read_b128 v[38:41], v124 offset:6400
	ds_read_b128 v[22:25], v124 offset:30976
	s_waitcnt lgkmcnt(11)
	v_pk_mul_f32 v[114:115], v[166:167], v[62:63]
	v_pk_mul_f32 v[116:117], v[166:167], v[58:59]
	v_pk_fma_f32 v[114:115], v[164:165], v[64:65], v[114:115]
	v_pk_fma_f32 v[116:117], v[164:165], v[60:61], v[116:117]
	v_add_f32_e32 v122, v114, v115
	v_pk_mul_f32 v[118:119], v[104:105], v[74:75] op_sel:[1,0]
	v_add_f32_e32 v206, v116, v117
	v_add_f32_dpp v122, v122, v122 quad_perm:[1,0,3,2] row_mask:0xf bank_mask:0xf bound_ctrl:1
	v_pk_mul_f32 v[120:121], v[104:105], v[76:77] op_sel:[1,0]
	ds_read_b128 v[54:57], v124 offset:23040
	v_add_f32_dpp v122, v122, v122 quad_perm:[2,3,0,1] row_mask:0xf bank_mask:0xf bound_ctrl:1
	v_pk_fma_f32 v[166:167], v[166:167], v[66:67], v[118:119]
	ds_read_b128 v[46:49], v124 offset:14848
	v_add_f32_dpp v122, v122, v122 row_half_mirror row_mask:0xf bank_mask:0xf bound_ctrl:1
	v_pk_fma_f32 v[164:165], v[164:165], v[68:69], v[120:121]
	ds_read_b128 v[50:53], v124 offset:39424
	v_add_f32_dpp v122, v122, v122 row_mirror row_mask:0xf bank_mask:0xf bound_ctrl:1
	v_add_f32_dpp v227, v227, v227 row_mirror row_mask:0xf bank_mask:0xf bound_ctrl:1
	v_add_f32_dpp v227, v235, v235 row_mirror row_mask:0xf bank_mask:0xc bound_ctrl:1
	v_pk_fma_f32 v[166:167], v[70:71], v[122:123], v[166:167] op_sel_hi:[1,0,1]
	v_pk_fma_f32 v[164:165], v[72:73], v[122:123], v[164:165] op_sel_hi:[1,0,1]
	ds_read_b128 v[58:61], v124 offset:6656
	ds_read_b128 v[42:45], v124 offset:31232
	s_waitcnt lgkmcnt(11)
; #define LAS __attribute__((address_space(3)))
; template <int CTRL> __device__ __forceinline__ float dpp_f(float x) { return __int_as_float(__builtin_amdgcn_update_dpp(0, __float_as_int(x), CTRL, 0xf, 0xf, false)); }
; __device__ __forceinline__ void phase_scan(const Params& p, LAS unsigned char* lds) {
;     ...
;                     for (int hb = 0; hb < 2; ++hb) {
;                         f32x4 vn[4];
; #pragma unroll
;                         for (int u = 0; u < 4; ++u) vn[u] = *(const LAS f32x4*)(sV + srow * 32 + ((16 * (hb + 1)) & 31) + 4 * u);
; #pragma unroll
;                         for (int u16 = 0; u16 < 16; ++u16) {
;                             const int s = 16 * hb + u16;
;                             const int sn = (s + 1) & 31;
;                             const f32x4 a_n = *(const LAS f32x4*)(sA + sn * 64), w_n = *(const LAS f32x4*)(sW + sn * 64), b_n = *(const LAS f32x4*)(sB + sn * 64);
;                             const f32x4 k_n = *(const LAS f32x4*)(sK + sn * 64), r_n = *(const LAS f32x4*)(sR + sn * 64);
;                             const float v = vq[u16 >> 2][u16 & 3];
;                             const f32x2 vv = {v, v};
;                             f32x2 pp = S01 * (f32x2){a_[0], a_[1]}; pp = S23 * (f32x2){a_[2], a_[3]} + pp;
;                             f32x2 yy = S01 * (f32x2){rp[0], rp[1]}; yy = S23 * (f32x2){rp[2], rp[3]} + yy;
;                             float sa = pp[0] + pp[1], y = yy[0] + yy[1];
;                             sa += dpp_f<0xB1>(sa); y += dpp_f<0xB1>(y);
;                             sa += dpp_f<0x4E>(sa); y += dpp_f<0x4E>(y);
;                             sa += dpp_f<0x141>(sa); y += dpp_f<0x141>(y);
;                             sa += dpp_f<0x140>(sa); y += dpp_f<0x140>(y);
;                             sY[((s - 1) & 31) * 16 + srow] = y;
;                             const f32x2 sv = {sa, sa};
;                             S01 = S01 * (f32x2){w_[0], w_[1]} + vv * (f32x2){k_[0], k_[1]};
;                             S23 = S23 * (f32x2){w_[2], w_[3]} + vv * (f32x2){k_[2], k_[3]};
;                             S01 = sv * (f32x2){b_[0], b_[1]} + S01;
;                             S23 = sv * (f32x2){b_[2], b_[3]} + S23;
;                             rp = r_;
;                             a_ = a_n; w_ = w_n; b_ = b_n; k_ = k_n; r_ = r_n;
;                         }
	v_pk_mul_f32 v[114:115], v[166:167], v[2:3]
	v_pk_mul_f32 v[116:117], v[166:167], v[78:79]
	v_pk_fma_f32 v[114:115], v[164:165], v[4:5], v[114:115]
	v_pk_fma_f32 v[116:117], v[164:165], v[80:81], v[116:117]
	v_add_f32_e32 v122, v114, v115
	s_waitcnt lgkmcnt(10)
	v_pk_mul_f32 v[118:119], v[106:107], v[14:15] op_sel_hi:[0,1]
	v_add_f32_e32 v207, v116, v117
	v_add_f32_dpp v122, v122, v122 quad_perm:[1,0,3,2] row_mask:0xf bank_mask:0xf bound_ctrl:1
	v_pk_mul_f32 v[120:121], v[106:107], v[16:17] op_sel_hi:[0,1]
	ds_read_b128 v[74:77], v124 offset:23296
	v_add_f32_dpp v122, v122, v122 quad_perm:[2,3,0,1] row_mask:0xf bank_mask:0xf bound_ctrl:1
	v_pk_fma_f32 v[166:167], v[166:167], v[6:7], v[118:119]
	ds_read_b128 v[66:69], v124 offset:15104
	v_add_f32_dpp v122, v122, v122 row_half_mirror row_mask:0xf bank_mask:0xf bound_ctrl:1
	v_pk_fma_f32 v[164:165], v[164:165], v[8:9], v[120:121]
	ds_read_b128 v[70:73], v124 offset:39680
	v_add_f32_dpp v122, v122, v122 row_mirror row_mask:0xf bank_mask:0xf bound_ctrl:1
	v_add_f32_dpp v220, v220, v220 row_half_mirror row_mask:0xf bank_mask:0xf bound_ctrl:1
	v_add_f32_dpp v221, v221, v221 row_half_mirror row_mask:0xf bank_mask:0xf bound_ctrl:1
	v_pk_fma_f32 v[166:167], v[10:11], v[122:123], v[166:167] op_sel_hi:[1,0,1]
	v_pk_fma_f32 v[164:165], v[12:13], v[122:123], v[164:165] op_sel_hi:[1,0,1]
	ds_read_b128 v[78:81], v124 offset:6912
	ds_read_b128 v[62:65], v124 offset:31488
	s_waitcnt lgkmcnt(10)
	v_pk_mul_f32 v[114:115], v[166:167], v[22:23]
	v_pk_mul_f32 v[116:117], v[166:167], v[18:19]
	v_pk_fma_f32 v[114:115], v[164:165], v[24:25], v[114:115]
	v_pk_fma_f32 v[116:117], v[164:165], v[20:21], v[116:117]
	v_add_f32_e32 v122, v114, v115
	v_pk_mul_f32 v[118:119], v[106:107], v[34:35] op_sel:[1,0]
	v_add_f32_e32 v208, v116, v117
	v_add_f32_dpp v122, v122, v122 quad_perm:[1,0,3,2] row_mask:0xf bank_mask:0xf bound_ctrl:1
	v_pk_mul_f32 v[120:121], v[106:107], v[36:37] op_sel:[1,0]
	ds_read_b128 v[14:17], v124 offset:23552
	v_add_f32_dpp v122, v122, v122 quad_perm:[2,3,0,1] row_mask:0xf bank_mask:0xf bound_ctrl:1
	v_pk_fma_f32 v[166:167], v[166:167], v[26:27], v[118:119]
	ds_read_b128 v[6:9], v124 offset:15360
	v_add_f32_dpp v122, v122, v122 row_half_mirror row_mask:0xf bank_mask:0xf bound_ctrl:1
	v_pk_fma_f32 v[164:165], v[164:165], v[28:29], v[120:121]
	ds_read_b128 v[10:13], v124 offset:39936
	v_add_f32_dpp v122, v122, v122 row_mirror row_mask:0xf bank_mask:0xf bound_ctrl:1
	v_add_f32_dpp v222, v222, v222 row_half_mirror row_mask:0xf bank_mask:0xf bound_ctrl:1
	v_add_f32_dpp v223, v223, v223 row_half_mirror row_mask:0xf bank_mask:0xf bound_ctrl:1
	v_pk_fma_f32 v[166:167], v[30:31], v[122:123], v[166:167] op_sel_hi:[1,0,1]
	v_pk_fma_f32 v[164:165], v[32:33], v[122:123], v[164:165] op_sel_hi:[1,0,1]
	ds_read_b128 v[18:21], v124 offset:7168
	ds_read_b128 v[2:5], v124 offset:31744
	ds_read_b128 v[110:113], v125 offset:41072
	s_waitcnt lgkmcnt(11)
	v_pk_mul_f32 v[114:115], v[166:167], v[42:43]
	v_pk_mul_f32 v[116:117], v[166:167], v[38:39]
	v_pk_fma_f32 v[114:115], v[164:165], v[44:45], v[114:115]
	v_pk_fma_f32 v[116:117], v[164:165], v[40:41], v[116:117]
	v_add_f32_e32 v122, v114, v115
	v_pk_mul_f32 v[118:119], v[108:109], v[54:55] op_sel_hi:[0,1]
	v_add_f32_e32 v209, v116, v117
	v_add_f32_dpp v122, v122, v122 quad_perm:[1,0,3,2] row_mask:0xf bank_mask:0xf bound_ctrl:1
	v_pk_mul_f32 v[120:121], v[108:109], v[56:57] op_sel_hi:[0,1]
	ds_read_b128 v[34:37], v124 offset:23808
	v_add_f32_dpp v122, v122, v122 quad_perm:[2,3,0,1] row_mask:0xf bank_mask:0xf bound_ctrl:1
	v_pk_fma_f32 v[166:167], v[166:167], v[46:47], v[118:119]
	ds_read_b128 v[26:29], v124 offset:15616
	v_add_f32_dpp v122, v122, v122 row_half_mirror row_mask:0xf bank_mask:0xf bound_ctrl:1
	v_pk_fma_f32 v[164:165], v[164:165], v[48:49], v[120:121]
	ds_read_b128 v[30:33], v124 offset:40192
	v_add_f32_dpp v122, v122, v122 row_mirror row_mask:0xf bank_mask:0xf bound_ctrl:1
	v_add_f32_dpp v220, v224, v224 row_half_mirror row_mask:0xf bank_mask:0xa bound_ctrl:1
	v_add_f32_dpp v221, v225, v225 row_half_mirror row_mask:0xf bank_mask:0xa bound_ctrl:1
	v_pk_fma_f32 v[166:167], v[50:51], v[122:123], v[166:167] op_sel_hi:[1,0,1]
	v_pk_fma_f32 v[164:165], v[52:53], v[122:123], v[164:165] op_sel_hi:[1,0,1]
	ds_read_b128 v[38:41], v124 offset:7424
	ds_read_b128 v[22:25], v124 offset:32000
	s_waitcnt lgkmcnt(11)
	v_pk_mul_f32 v[114:115], v[166:167], v[62:63]
	v_pk_mul_f32 v[116:117], v[166:167], v[58:59]
	v_pk_fma_f32 v[114:115], v[164:165], v[64:65], v[114:115]
	v_pk_fma_f32 v[116:117], v[164:165], v[60:61], v[116:117]
	v_add_f32_e32 v122, v114, v115
	v_pk_mul_f32 v[118:119], v[108:109], v[74:75] op_sel:[1,0]
	v_add_f32_e32 v210, v116, v117
	v_add_f32_dpp v122, v122, v122 quad_perm:[1,0,3,2] row_mask:0xf bank_mask:0xf bound_ctrl:1
	v_pk_mul_f32 v[120:121], v[108:109], v[76:77] op_sel:[1,0]
	ds_read_b128 v[54:57], v124 offset:24064
	v_add_f32_dpp v122, v122, v122 quad_perm:[2,3,0,1] row_mask:0xf bank_mask:0xf bound_ctrl:1
	v_pk_fma_f32 v[166:167], v[166:167], v[66:67], v[118:119]
	ds_read_b128 v[46:49], v124 offset:15872
	v_add_f32_dpp v122, v122, v122 row_half_mirror row_mask:0xf bank_mask:0xf bound_ctrl:1
	v_pk_fma_f32 v[164:165], v[164:165], v[68:69], v[120:121]
	ds_read_b128 v[50:53], v124 offset:40448
	v_add_f32_dpp v122, v122, v122 row_mirror row_mask:0xf bank_mask:0xf bound_ctrl:1
	v_add_f32_dpp v222, v226, v226 row_half_mirror row_mask:0xf bank_mask:0xa bound_ctrl:1
	v_add_f32_dpp v223, v227, v227 row_half_mirror row_mask:0xf bank_mask:0xa bound_ctrl:1
	v_pk_fma_f32 v[166:167], v[70:71], v[122:123], v[166:167] op_sel_hi:[1,0,1]
	v_pk_fma_f32 v[164:165], v[72:73], v[122:123], v[164:165] op_sel_hi:[1,0,1]
	ds_read_b128 v[58:61], v124 offset:7680
	ds_read_b128 v[42:45], v124 offset:32256
	s_waitcnt lgkmcnt(11)
; #define LAS __attribute__((address_space(3)))
; template <int CTRL> __device__ __forceinline__ float dpp_f(float x) { return __int_as_float(__builtin_amdgcn_update_dpp(0, __float_as_int(x), CTRL, 0xf, 0xf, false)); }
; __device__ __forceinline__ void phase_scan(const Params& p, LAS unsigned char* lds) {
;     ...
;                         for (int u16 = 0; u16 < 16; ++u16) {
;                             const int s = 16 * hb + u16;
;                             const int sn = (s + 1) & 31;
;                             const f32x4 a_n = *(const LAS f32x4*)(sA + sn * 64), w_n = *(const LAS f32x4*)(sW + sn * 64), b_n = *(const LAS f32x4*)(sB + sn * 64);
;                             const f32x4 k_n = *(const LAS f32x4*)(sK + sn * 64), r_n = *(const LAS f32x4*)(sR + sn * 64);
;                             const float v = vq[u16 >> 2][u16 & 3];
;                             const f32x2 vv = {v, v};
;                             f32x2 pp = S01 * (f32x2){a_[0], a_[1]}; pp = S23 * (f32x2){a_[2], a_[3]} + pp;
;                             f32x2 yy = S01 * (f32x2){rp[0], rp[1]}; yy = S23 * (f32x2){rp[2], rp[3]} + yy;
;                             float sa = pp[0] + pp[1], y = yy[0] + yy[1];
;                             sa += dpp_f<0xB1>(sa); y += dpp_f<0xB1>(y);
;                             sa += dpp_f<0x4E>(sa); y += dpp_f<0x4E>(y);
;                             sa += dpp_f<0x141>(sa); y += dpp_f<0x141>(y);
;                             sa += dpp_f<0x140>(sa); y += dpp_f<0x140>(y);
;                             sY[((s - 1) & 31) * 16 + srow] = y;
;                             const f32x2 sv = {sa, sa};
;                             S01 = S01 * (f32x2){w_[0], w_[1]} + vv * (f32x2){k_[0], k_[1]};
;                             S23 = S23 * (f32x2){w_[2], w_[3]} + vv * (f32x2){k_[2], k_[3]};
;                             S01 = sv * (f32x2){b_[0], b_[1]} + S01;
;                             S23 = sv * (f32x2){b_[2], b_[3]} + S23;
;                             rp = r_;
;                             a_ = a_n; w_ = w_n; b_ = b_n; k_ = k_n; r_ = r_n;
;                         }
	v_pk_mul_f32 v[114:115], v[166:167], v[2:3]
	v_pk_mul_f32 v[116:117], v[166:167], v[78:79]
	v_pk_fma_f32 v[114:115], v[164:165], v[4:5], v[114:115]
	v_pk_fma_f32 v[116:117], v[164:165], v[80:81], v[116:117]
	v_add_f32_e32 v122, v114, v115
	s_waitcnt lgkmcnt(10)
	v_pk_mul_f32 v[118:119], v[110:111], v[14:15] op_sel_hi:[0,1]
	v_add_f32_e32 v211, v116, v117
	v_add_f32_dpp v122, v122, v122 quad_perm:[1,0,3,2] row_mask:0xf bank_mask:0xf bound_ctrl:1
	v_pk_mul_f32 v[120:121], v[110:111], v[16:17] op_sel_hi:[0,1]
	ds_read_b128 v[74:77], v124 offset:24320
	v_add_f32_dpp v122, v122, v122 quad_perm:[2,3,0,1] row_mask:0xf bank_mask:0xf bound_ctrl:1
	v_pk_fma_f32 v[166:167], v[166:167], v[6:7], v[118:119]
	ds_read_b128 v[66:69], v124 offset:16128
	v_add_f32_dpp v122, v122, v122 row_half_mirror row_mask:0xf bank_mask:0xf bound_ctrl:1
	v_pk_fma_f32 v[164:165], v[164:165], v[8:9], v[120:121]
	ds_read_b128 v[70:73], v124 offset:40704
	v_add_f32_dpp v122, v122, v122 row_mirror row_mask:0xf bank_mask:0xf bound_ctrl:1
	v_add_f32_dpp v220, v220, v220 quad_perm:[1,0,3,2] row_mask:0xf bank_mask:0xf bound_ctrl:1
	v_add_f32_dpp v221, v221, v221 quad_perm:[1,0,3,2] row_mask:0xf bank_mask:0xf bound_ctrl:1
	v_pk_fma_f32 v[166:167], v[10:11], v[122:123], v[166:167] op_sel_hi:[1,0,1]
	v_pk_fma_f32 v[164:165], v[12:13], v[122:123], v[164:165] op_sel_hi:[1,0,1]
	ds_read_b128 v[78:81], v124 offset:7936
	ds_read_b128 v[62:65], v124 offset:32512
	v_add_f32_dpp v222, v222, v222 quad_perm:[1,0,3,2] row_mask:0xf bank_mask:0xf bound_ctrl:1
	v_add_f32_dpp v223, v223, v223 quad_perm:[1,0,3,2] row_mask:0xf bank_mask:0xf bound_ctrl:1
	v_add_f32_dpp v220, v220, v220 quad_perm:[2,3,0,1] row_mask:0xf bank_mask:0xf bound_ctrl:1
	v_add_f32_dpp v221, v221, v221 quad_perm:[2,3,0,1] row_mask:0xf bank_mask:0xf bound_ctrl:1
	v_add_f32_dpp v222, v222, v222 quad_perm:[2,3,0,1] row_mask:0xf bank_mask:0xf bound_ctrl:1
	v_add_f32_dpp v223, v223, v223 quad_perm:[2,3,0,1] row_mask:0xf bank_mask:0xf bound_ctrl:1
	v_cndmask_b32_e64 v202, v220, v221, s[34:35]
	v_cndmask_b32_e64 v202, v202, v222, s[56:57]
	v_cndmask_b32_e64 v202, v202, v223, s[98:99]
	v_cvt_f16_f32_e32 v203, v202
	global_store_short v[126:127], v203, off
	v_lshl_add_u64 v[126:127], v[126:127], 0, s[100:101]
	s_setprio 0
	s_branch .LBB0_603
; template <int CTRL> __device__ __forceinline__ float dpp_f(float x) { return __int_as_float(__builtin_amdgcn_update_dpp(0, __float_as_int(x), CTRL, 0xf, 0xf, false)); }
; __device__ __forceinline__ void phase_scan(const Params& p, LAS unsigned char* lds) {
;     ...
;                             const float v = vq[u16 >> 2][u16 & 3];
;                             const f32x2 vv = {v, v};
;                             f32x2 pp = S01 * (f32x2){a_[0], a_[1]}; pp = S23 * (f32x2){a_[2], a_[3]} + pp;
;                             f32x2 yy = S01 * (f32x2){rp[0], rp[1]}; yy = S23 * (f32x2){rp[2], rp[3]} + yy;
;                             float sa = pp[0] + pp[1], y = yy[0] + yy[1];
;                             sa += dpp_f<0xB1>(sa); y += dpp_f<0xB1>(y);
;                             sa += dpp_f<0x4E>(sa); y += dpp_f<0x4E>(y);
;                             sa += dpp_f<0x141>(sa); y += dpp_f<0x141>(y);
;                             sa += dpp_f<0x140>(sa); y += dpp_f<0x140>(y);
;                             sY[((s - 1) & 31) * 16 + srow] = y;
;                             const f32x2 sv = {sa, sa};
;                             S01 = S01 * (f32x2){w_[0], w_[1]} + vv * (f32x2){k_[0], k_[1]};
;                             S23 = S23 * (f32x2){w_[2], w_[3]} + vv * (f32x2){k_[2], k_[3]};
;                             S01 = sv * (f32x2){b_[0], b_[1]} + S01;
;                             S23 = sv * (f32x2){b_[2], b_[3]} + S23;
;                             rp = r_;
;                             a_ = a_n; w_ = w_n; b_ = b_n; k_ = k_n; r_ = r_n;
;                         }
; #pragma unroll
;                         for (int u = 0; u < 4; ++u) vq[u] = vn[u];
;                     }
;                     { f32x2 yy = S01 * (f32x2){rp[0], rp[1]}; yy = S23 * (f32x2){rp[2], rp[3]} + yy; sY[31 * 16 + srow] = red16(yy[0] + yy[1]); }
;     ...
;         if (wave >= 4) SCAN_YSTORE(SEQ / 32 - 1);
.LBB0_620:
	s_mov_b64 s[10:11], 0
	s_cmp_eq_u64 s[0:1], 0
	s_cbranch_scc0 .LBB0_594
	s_setprio 3
	s_mov_b32 s14, 0x0fff0fff
	s_mov_b32 s15, s14
	v_pk_mul_f32 v[114:115], v[166:167], v[22:23]
	v_pk_mul_f32 v[116:117], v[166:167], v[18:19]
	v_pk_fma_f32 v[114:115], v[164:165], v[24:25], v[114:115]
	v_pk_fma_f32 v[116:117], v[164:165], v[20:21], v[116:117]
	v_add_f32_e32 v122, v114, v115
	v_pk_mul_f32 v[118:119], v[110:111], v[34:35] op_sel:[1,0]
	v_add_f32_e32 v212, v116, v117
	v_add_f32_dpp v122, v122, v122 quad_perm:[1,0,3,2] row_mask:0xf bank_mask:0xf bound_ctrl:1
	v_pk_mul_f32 v[120:121], v[110:111], v[36:37] op_sel:[1,0]
	v_add_f32_dpp v204, v204, v204 row_mirror row_mask:0xf bank_mask:0xf bound_ctrl:1
	v_add_f32_dpp v122, v122, v122 quad_perm:[2,3,0,1] row_mask:0xf bank_mask:0xf bound_ctrl:1
	v_pk_fma_f32 v[166:167], v[166:167], v[26:27], v[118:119]
	v_add_f32_dpp v204, v212, v212 row_mirror row_mask:0xf bank_mask:0xc bound_ctrl:1
	v_add_f32_dpp v122, v122, v122 row_half_mirror row_mask:0xf bank_mask:0xf bound_ctrl:1
	v_pk_fma_f32 v[164:165], v[164:165], v[28:29], v[120:121]
	s_nop 0
	v_add_f32_dpp v122, v122, v122 row_mirror row_mask:0xf bank_mask:0xf bound_ctrl:1
	s_nop 0
	v_pk_fma_f32 v[166:167], v[30:31], v[122:123], v[166:167] op_sel_hi:[1,0,1]
	v_pk_fma_f32 v[164:165], v[32:33], v[122:123], v[164:165] op_sel_hi:[1,0,1]
	v_pk_mul_f32 v[114:115], v[166:167], v[42:43]
	v_pk_mul_f32 v[116:117], v[166:167], v[38:39]
	v_pk_fma_f32 v[114:115], v[164:165], v[44:45], v[114:115]
	v_pk_fma_f32 v[116:117], v[164:165], v[40:41], v[116:117]
	v_add_f32_e32 v122, v114, v115
	v_pk_mul_f32 v[118:119], v[112:113], v[54:55] op_sel_hi:[0,1]
	v_add_f32_e32 v213, v116, v117
	v_add_f32_dpp v122, v122, v122 quad_perm:[1,0,3,2] row_mask:0xf bank_mask:0xf bound_ctrl:1
	v_pk_mul_f32 v[120:121], v[112:113], v[56:57] op_sel_hi:[0,1]
	v_add_f32_dpp v205, v205, v205 row_mirror row_mask:0xf bank_mask:0xf bound_ctrl:1
	v_add_f32_dpp v122, v122, v122 quad_perm:[2,3,0,1] row_mask:0xf bank_mask:0xf bound_ctrl:1
	v_pk_fma_f32 v[166:167], v[166:167], v[46:47], v[118:119]
	v_add_f32_dpp v205, v213, v213 row_mirror row_mask:0xf bank_mask:0xc bound_ctrl:1
	v_add_f32_dpp v122, v122, v122 row_half_mirror row_mask:0xf bank_mask:0xf bound_ctrl:1
	v_pk_fma_f32 v[164:165], v[164:165], v[48:49], v[120:121]
	s_nop 0
	v_add_f32_dpp v122, v122, v122 row_mirror row_mask:0xf bank_mask:0xf bound_ctrl:1
	s_nop 0
	v_pk_fma_f32 v[166:167], v[50:51], v[122:123], v[166:167] op_sel_hi:[1,0,1]
	v_pk_fma_f32 v[164:165], v[52:53], v[122:123], v[164:165] op_sel_hi:[1,0,1]
	v_pk_mul_f32 v[114:115], v[166:167], v[62:63]
	v_pk_mul_f32 v[116:117], v[166:167], v[58:59]
	v_pk_fma_f32 v[114:115], v[164:165], v[64:65], v[114:115]
	v_pk_fma_f32 v[116:117], v[164:165], v[60:61], v[116:117]
	v_add_f32_e32 v122, v114, v115
	v_pk_mul_f32 v[118:119], v[112:113], v[74:75] op_sel:[1,0]
	v_add_f32_e32 v214, v116, v117
	v_add_f32_dpp v122, v122, v122 quad_perm:[1,0,3,2] row_mask:0xf bank_mask:0xf bound_ctrl:1
	v_pk_mul_f32 v[120:121], v[112:113], v[76:77] op_sel:[1,0]
	v_add_f32_dpp v206, v206, v206 row_mirror row_mask:0xf bank_mask:0xf bound_ctrl:1
	v_add_f32_dpp v122, v122, v122 quad_perm:[2,3,0,1] row_mask:0xf bank_mask:0xf bound_ctrl:1
	v_pk_fma_f32 v[166:167], v[166:167], v[66:67], v[118:119]
	v_add_f32_dpp v206, v214, v214 row_mirror row_mask:0xf bank_mask:0xc bound_ctrl:1
	v_add_f32_dpp v122, v122, v122 row_half_mirror row_mask:0xf bank_mask:0xf bound_ctrl:1
	v_pk_fma_f32 v[164:165], v[164:165], v[68:69], v[120:121]
	s_nop 0
	v_add_f32_dpp v122, v122, v122 row_mirror row_mask:0xf bank_mask:0xf bound_ctrl:1
	s_nop 0
	v_pk_fma_f32 v[166:167], v[70:71], v[122:123], v[166:167] op_sel_hi:[1,0,1]
	v_pk_fma_f32 v[164:165], v[72:73], v[122:123], v[164:165] op_sel_hi:[1,0,1]
	v_pk_mul_f32 v[116:117], v[166:167], v[78:79]
	s_nop 0
	v_pk_fma_f32 v[116:117], v[164:165], v[80:81], v[116:117]
	s_nop 0
	v_add_f32_e32 v215, v116, v117
	v_mov_b32_e32 v216, 0
	v_mov_b32_e32 v217, 0
	v_mov_b32_e32 v218, 0
	v_mov_b32_e32 v219, 0
	s_nop 1
	v_add_f32_dpp v207, v207, v207 row_mirror row_mask:0xf bank_mask:0xf bound_ctrl:1
	v_add_f32_dpp v207, v215, v215 row_mirror row_mask:0xf bank_mask:0xc bound_ctrl:1
	v_add_f32_dpp v208, v208, v208 row_mirror row_mask:0xf bank_mask:0xf bound_ctrl:1
	v_add_f32_dpp v208, v216, v216 row_mirror row_mask:0xf bank_mask:0xc bound_ctrl:1
	v_add_f32_dpp v209, v209, v209 row_mirror row_mask:0xf bank_mask:0xf bound_ctrl:1
	v_add_f32_dpp v209, v217, v217 row_mirror row_mask:0xf bank_mask:0xc bound_ctrl:1
	v_add_f32_dpp v210, v210, v210 row_mirror row_mask:0xf bank_mask:0xf bound_ctrl:1
	v_add_f32_dpp v210, v218, v218 row_mirror row_mask:0xf bank_mask:0xc bound_ctrl:1
	v_add_f32_dpp v211, v211, v211 row_mirror row_mask:0xf bank_mask:0xf bound_ctrl:1
	v_add_f32_dpp v211, v219, v219 row_mirror row_mask:0xf bank_mask:0xc bound_ctrl:1
	s_nop 1
	v_add_f32_dpp v204, v204, v204 row_half_mirror row_mask:0xf bank_mask:0xf bound_ctrl:1
	v_add_f32_dpp v205, v205, v205 row_half_mirror row_mask:0xf bank_mask:0xf bound_ctrl:1
	v_add_f32_dpp v206, v206, v206 row_half_mirror row_mask:0xf bank_mask:0xf bound_ctrl:1
	v_add_f32_dpp v207, v207, v207 row_half_mirror row_mask:0xf bank_mask:0xf bound_ctrl:1
	v_add_f32_dpp v204, v208, v208 row_half_mirror row_mask:0xf bank_mask:0xa bound_ctrl:1
	v_add_f32_dpp v205, v209, v209 row_half_mirror row_mask:0xf bank_mask:0xa bound_ctrl:1
	v_add_f32_dpp v206, v210, v210 row_half_mirror row_mask:0xf bank_mask:0xa bound_ctrl:1
	v_add_f32_dpp v207, v211, v211 row_half_mirror row_mask:0xf bank_mask:0xa bound_ctrl:1
	v_add_f32_dpp v204, v204, v204 quad_perm:[1,0,3,2] row_mask:0xf bank_mask:0xf bound_ctrl:1
	v_add_f32_dpp v205, v205, v205 quad_perm:[1,0,3,2] row_mask:0xf bank_mask:0xf bound_ctrl:1
	v_add_f32_dpp v206, v206, v206 quad_perm:[1,0,3,2] row_mask:0xf bank_mask:0xf bound_ctrl:1
	v_add_f32_dpp v207, v207, v207 quad_perm:[1,0,3,2] row_mask:0xf bank_mask:0xf bound_ctrl:1
	v_add_f32_dpp v204, v204, v204 quad_perm:[2,3,0,1] row_mask:0xf bank_mask:0xf bound_ctrl:1
	v_add_f32_dpp v205, v205, v205 quad_perm:[2,3,0,1] row_mask:0xf bank_mask:0xf bound_ctrl:1
	v_add_f32_dpp v206, v206, v206 quad_perm:[2,3,0,1] row_mask:0xf bank_mask:0xf bound_ctrl:1
	v_add_f32_dpp v207, v207, v207 quad_perm:[2,3,0,1] row_mask:0xf bank_mask:0xf bound_ctrl:1
	v_cndmask_b32_e64 v202, v204, v205, s[34:35]
	v_cndmask_b32_e64 v202, v202, v206, s[56:57]
	v_cndmask_b32_e64 v202, v202, v207, s[98:99]
	v_cvt_f16_f32_e32 v203, v202
	s_mov_b64 exec, s[14:15]
	global_store_short v[128:129], v203, off
	s_mov_b64 exec, -1
	v_lshl_add_u64 v[128:129], v[128:129], 0, s[100:101]
	s_setprio 0
	s_branch .LBB0_594

; __global__ void __launch_bounds__(512, 2) mega(Params p) {
;     extern __shared__ __attribute__((aligned(16))) unsigned char smem[];
;     LAS unsigned char* lds = (LAS unsigned char*)smem;
;     cg::grid_group grid = cg::this_grid();
;     unsigned char* ws = p.ws;
;     const int lo = p.ph_lo, hi = p.ph_hi;
;     ...
;     volatile LAS unsigned* bst = (volatile LAS unsigned*)(lds + LDS_MAIN);
;     if (threadIdx.x < 4) bst[threadIdx.x] = 0u;
;     __syncthreads();
;     const XcdBarrier bar = xcd_barrier_post((unsigned*)(ws + WS_BAR), bst);
;     if (hi > 1000) grid.sync();
;     ...
;     if (IN(0)) for (int rep_ = 0; rep_ <= ((REPMASK >> 0) & 1); ++rep_) { phase0(p, lds); } SEAM(0);
;     if (IN(1)) for (int rep_ = 0; rep_ <= ((REPMASK >> 1) & 1); ++rep_) { pg8::Gemm g{(const h16*)p.out, (const h16*)(ws + WS_W1T), NTOK, 7168, 1024}; pg8::StaticOrder S; S.init(NTOK, 7168, gridDim.x, blockIdx.x);
;                  Epi1 E{(h16*)(ws + WS_XC), (h16*)(ws + WS_G), (h16*)(ws + WS_U), (h16*)(ws + WS_V), (float*)(ws + WS_STATS)}; pg8::gemm_phase<Epi1>(lds, g, S, E); } SEAM(1);
;     if (IN(3)) for (int rep_ = 0; rep_ <= ((REPMASK >> 3) & 1); ++rep_) { phase_mix0(p, lds); } SEAM(3);
;     if (IN(4)) for (int rep_ = 0; rep_ <= ((REPMASK >> 4) & 1); ++rep_) { pg8::Gemm g{(const h16*)(ws + WS_YCAT), (const h16*)(ws + WS_W2T), NTOK, 1024, 2048}; pg8::StaticOrder S; S.init(NTOK, 1024, gridDim.x, blockIdx.x);
;                  Epi2 E{(h16*)(ws + WS_O1)}; pg8::gemm_phase<Epi2>(lds, g, S, E); } SEAM(4);
;     if (IN(5)) for (int rep_ = 0; rep_ <= ((REPMASK >> 5) & 1); ++rep_) { phase_norm1(p); } SEAM(5);
;     if (IN(6)) for (int rep_ = 0; rep_ <= ((REPMASK >> 6) & 1); ++rep_) { pg8::Gemm g{(const h16*)p.out, (const h16*)(ws + WS_W3T), NTOK, 5376, 1024}; pg8::StaticOrder S; S.init(NTOK, 5376, gridDim.x, blockIdx.x);
;                  Epi3 E{(h16*)(ws + WS_PC), (h16*)(ws + WS_ZCD), (h16*)(ws + WS_FD)}; pg8::gemm_phase<Epi3>(lds, g, S, E); } SEAM(6);
;     if (IN(7)) for (int rep_ = 0; rep_ <= ((REPMASK >> 7) & 1); ++rep_) { phase_fft(p, lds); }
;     if (IN(8)) for (int rep_ = 0; rep_ <= ((REPMASK >> 8) & 1); ++rep_) { phase_scan(p, lds); } SEAM(8);
;     if (IN(9)) for (int rep_ = 0; rep_ <= ((REPMASK >> 9) & 1); ++rep_) { phase_fnet_out(p, lds); }
;     if (IN(10)) for (int rep_ = 0; rep_ <= ((REPMASK >> 10) & 1); ++rep_) { phase_post(p); } SEAM(10);
	.amdhsa_kernel _Z4mega6Params
		.amdhsa_group_segment_fixed_size 0
		.amdhsa_private_segment_fixed_size 0
		.amdhsa_kernarg_size 472
		.amdhsa_user_sgpr_count 2
		.amdhsa_user_sgpr_dispatch_ptr 0
		.amdhsa_user_sgpr_queue_ptr 0
		.amdhsa_user_sgpr_kernarg_segment_ptr 1
		.amdhsa_user_sgpr_dispatch_id 0
		.amdhsa_user_sgpr_kernarg_preload_length 0
		.amdhsa_user_sgpr_kernarg_preload_offset 0
		.amdhsa_user_sgpr_private_segment_size 0
		.amdhsa_uses_dynamic_stack 0
		.amdhsa_enable_private_segment 0
		.amdhsa_system_sgpr_workgroup_id_x 1
		.amdhsa_system_sgpr_workgroup_id_y 0
		.amdhsa_system_sgpr_workgroup_id_z 0
		.amdhsa_system_sgpr_workgroup_info 0
		.amdhsa_system_vgpr_workitem_id 2
		.amdhsa_next_free_vgpr 256
		.amdhsa_next_free_sgpr 102
		.amdhsa_accum_offset 256
		.amdhsa_reserve_vcc 1
		.amdhsa_float_round_mode_32 0
		.amdhsa_float_round_mode_16_64 0
		.amdhsa_float_denorm_mode_32 3
		.amdhsa_float_denorm_mode_16_64 3
		.amdhsa_dx10_clamp 1
		.amdhsa_ieee_mode 1
		.amdhsa_fp16_overflow 0
		.amdhsa_tg_split 0
		.amdhsa_exception_fp_ieee_invalid_op 0
		.amdhsa_exception_fp_denorm_src 0
		.amdhsa_exception_fp_ieee_div_zero 0
		.amdhsa_exception_fp_ieee_overflow 0
		.amdhsa_exception_fp_ieee_underflow 0
		.amdhsa_exception_fp_ieee_inexact 0
		.amdhsa_exception_int_div_zero 0
	.end_amdhsa_kernel

; __global__ void __launch_bounds__(512, 2) mega(Params p) {
;     extern __shared__ __attribute__((aligned(16))) unsigned char smem[];
;     LAS unsigned char* lds = (LAS unsigned char*)smem;
;     cg::grid_group grid = cg::this_grid();
;     unsigned char* ws = p.ws;
;     const int lo = p.ph_lo, hi = p.ph_hi;
;     ...
;     volatile LAS unsigned* bst = (volatile LAS unsigned*)(lds + LDS_MAIN);
;     if (threadIdx.x < 4) bst[threadIdx.x] = 0u;
;     __syncthreads();
;     const XcdBarrier bar = xcd_barrier_post((unsigned*)(ws + WS_BAR), bst);
;     if (hi > 1000) grid.sync();
;     ...
;     if (IN(0)) for (int rep_ = 0; rep_ <= ((REPMASK >> 0) & 1); ++rep_) { phase0(p, lds); } SEAM(0);
;     if (IN(1)) for (int rep_ = 0; rep_ <= ((REPMASK >> 1) & 1); ++rep_) { pg8::Gemm g{(const h16*)p.out, (const h16*)(ws + WS_W1T), NTOK, 7168, 1024}; pg8::StaticOrder S; S.init(NTOK, 7168, gridDim.x, blockIdx.x);
;                  Epi1 E{(h16*)(ws + WS_XC), (h16*)(ws + WS_G), (h16*)(ws + WS_U), (h16*)(ws + WS_V), (float*)(ws + WS_STATS)}; pg8::gemm_phase<Epi1>(lds, g, S, E); } SEAM(1);
;     if (IN(3)) for (int rep_ = 0; rep_ <= ((REPMASK >> 3) & 1); ++rep_) { phase_mix0(p, lds); } SEAM(3);
;     if (IN(4)) for (int rep_ = 0; rep_ <= ((REPMASK >> 4) & 1); ++rep_) { pg8::Gemm g{(const h16*)(ws + WS_YCAT), (const h16*)(ws + WS_W2T), NTOK, 1024, 2048}; pg8::StaticOrder S; S.init(NTOK, 1024, gridDim.x, blockIdx.x);
;                  Epi2 E{(h16*)(ws + WS_O1)}; pg8::gemm_phase<Epi2>(lds, g, S, E); } SEAM(4);
;     if (IN(5)) for (int rep_ = 0; rep_ <= ((REPMASK >> 5) & 1); ++rep_) { phase_norm1(p); } SEAM(5);
;     if (IN(6)) for (int rep_ = 0; rep_ <= ((REPMASK >> 6) & 1); ++rep_) { pg8::Gemm g{(const h16*)p.out, (const h16*)(ws + WS_W3T), NTOK, 5376, 1024}; pg8::StaticOrder S; S.init(NTOK, 5376, gridDim.x, blockIdx.x);
;                  Epi3 E{(h16*)(ws + WS_PC), (h16*)(ws + WS_ZCD), (h16*)(ws + WS_FD)}; pg8::gemm_phase<Epi3>(lds, g, S, E); } SEAM(6);
;     if (IN(7)) for (int rep_ = 0; rep_ <= ((REPMASK >> 7) & 1); ++rep_) { phase_fft(p, lds); }
;     if (IN(8)) for (int rep_ = 0; rep_ <= ((REPMASK >> 8) & 1); ++rep_) { phase_scan(p, lds); } SEAM(8);
;     if (IN(9)) for (int rep_ = 0; rep_ <= ((REPMASK >> 9) & 1); ++rep_) { phase_fnet_out(p, lds); }
;     if (IN(10)) for (int rep_ = 0; rep_ <= ((REPMASK >> 10) & 1); ++rep_) { phase_post(p); } SEAM(10);
amdhsa.kernels:
  - .agpr_count:     0
    .args:
      - .offset:         0
        .size:           216
        .value_kind:     by_value
      - .offset:         216
        .size:           4
        .value_kind:     hidden_block_count_x
      - .offset:         220
        .size:           4
        .value_kind:     hidden_block_count_y
      - .offset:         224
        .size:           4
        .value_kind:     hidden_block_count_z
      - .offset:         228
        .size:           2
        .value_kind:     hidden_group_size_x
      - .offset:         230
        .size:           2
        .value_kind:     hidden_group_size_y
      - .offset:         232
        .size:           2
        .value_kind:     hidden_group_size_z
      - .offset:         234
        .size:           2
        .value_kind:     hidden_remainder_x
      - .offset:         236
        .size:           2
        .value_kind:     hidden_remainder_y
      - .offset:         238
        .size:           2
        .value_kind:     hidden_remainder_z
      - .offset:         256
        .size:           8
        .value_kind:     hidden_global_offset_x
      - .offset:         264
        .size:           8
        .value_kind:     hidden_global_offset_y
      - .offset:         272
        .size:           8
        .value_kind:     hidden_global_offset_z
      - .offset:         280
        .size:           2
        .value_kind:     hidden_grid_dims
      - .offset:         304
        .size:           8
        .value_kind:     hidden_multigrid_sync_arg
      - .offset:         336
        .size:           4
        .value_kind:     hidden_dynamic_lds_size
    .group_segment_fixed_size: 0
    .kernarg_segment_align: 8
    .kernarg_segment_size: 472
    .language:       OpenCL C
    .language_version:
      - 2
      - 0
    .max_flat_workgroup_size: 512
    .name:           _Z4mega6Params
    .private_segment_fixed_size: 0
    .sgpr_count:     108
    .sgpr_spill_count: 6
    .symbol:         _Z4mega6Params.kd
    .uniform_work_group_size: 1
    .uses_dynamic_stack: false
    .vgpr_count:     256
    .vgpr_spill_count: 0
    .wavefront_size: 64
